# GEMM MFMA clusters: momentary priority drops every 4 MFMAs
# baseline (speedup 1.0000x reference)
.Lh9_17:
	global_load_lds_dwordx4 v[176:177], off
	v_lshl_add_u64 v[176:177], v[136:137], 0, s[8:9]
	s_add_i32 m0, s17, 0xe000
	s_nop 0
	global_load_lds_dwordx4 v[176:177], off
	s_waitcnt vmcnt(8)
	s_waitcnt lgkmcnt(0)
	s_barrier
	s_cmp_eq_u32 s32, 2
	s_cbranch_scc1 .Lh9_18
	s_setprio 1
	s_waitcnt lgkmcnt(0)
	v_mfma_f32_16x16x32_bf16 v[126:129], v[144:147], v[208:211], v[126:129]
	v_mfma_f32_16x16x32_bf16 v[122:125], v[152:155], v[208:211], v[122:125]
	v_mfma_f32_16x16x32_bf16 v[118:121], v[144:147], v[216:219], v[118:121]
	v_mfma_f32_16x16x32_bf16 v[114:117], v[152:155], v[216:219], v[114:117]
	s_setprio 0
	s_setprio 1
	v_mfma_f32_16x16x32_bf16 v[102:105], v[144:147], v[224:227], v[102:105]
	v_mfma_f32_16x16x32_bf16 v[98:101], v[152:155], v[224:227], v[98:101]
	v_mfma_f32_16x16x32_bf16 v[86:89], v[144:147], v[232:235], v[86:89]
	v_mfma_f32_16x16x32_bf16 v[82:85], v[152:155], v[232:235], v[82:85]
	s_setprio 0
	s_setprio 1
	v_mfma_f32_16x16x32_bf16 v[126:129], v[148:151], v[212:215], v[126:129]
	v_mfma_f32_16x16x32_bf16 v[122:125], v[158:161], v[212:215], v[122:125]
	v_mfma_f32_16x16x32_bf16 v[118:121], v[148:151], v[220:223], v[118:121]
	v_mfma_f32_16x16x32_bf16 v[114:117], v[158:161], v[220:223], v[114:117]
	s_setprio 0
	s_setprio 1
	v_mfma_f32_16x16x32_bf16 v[102:105], v[148:151], v[228:231], v[102:105]
	v_mfma_f32_16x16x32_bf16 v[98:101], v[158:161], v[228:231], v[98:101]
	v_mfma_f32_16x16x32_bf16 v[86:89], v[148:151], v[236:239], v[86:89]
	v_mfma_f32_16x16x32_bf16 v[82:85], v[158:161], v[236:239], v[82:85]
	s_setprio 0
	s_setprio 1
	v_mfma_f32_16x16x32_bf16 v[110:113], v[162:165], v[208:211], v[110:113]
	v_mfma_f32_16x16x32_bf16 v[106:109], v[200:203], v[208:211], v[106:109]
	v_mfma_f32_16x16x32_bf16 v[94:97], v[162:165], v[216:219], v[94:97]
	v_mfma_f32_16x16x32_bf16 v[90:93], v[200:203], v[216:219], v[90:93]
	s_setprio 0
	s_setprio 1
	v_mfma_f32_16x16x32_bf16 v[78:81], v[162:165], v[224:227], v[78:81]
	v_mfma_f32_16x16x32_bf16 v[74:77], v[200:203], v[224:227], v[74:77]
	v_mfma_f32_16x16x32_bf16 v[70:73], v[162:165], v[232:235], v[70:73]
	v_mfma_f32_16x16x32_bf16 v[66:69], v[200:203], v[232:235], v[66:69]
	s_setprio 0
	s_setprio 1
	v_mfma_f32_16x16x32_bf16 v[110:113], v[196:199], v[212:215], v[110:113]
	v_mfma_f32_16x16x32_bf16 v[106:109], v[204:207], v[212:215], v[106:109]
	v_mfma_f32_16x16x32_bf16 v[94:97], v[196:199], v[220:223], v[94:97]
	v_mfma_f32_16x16x32_bf16 v[90:93], v[204:207], v[220:223], v[90:93]
	s_setprio 0
	s_setprio 1
	v_mfma_f32_16x16x32_bf16 v[78:81], v[196:199], v[228:231], v[78:81]
	v_mfma_f32_16x16x32_bf16 v[74:77], v[204:207], v[228:231], v[74:77]
	v_mfma_f32_16x16x32_bf16 v[70:73], v[196:199], v[236:239], v[70:73]
	v_mfma_f32_16x16x32_bf16 v[66:69], v[204:207], v[236:239], v[66:69]
	s_setprio 0

.Lh9_19:
	global_load_lds_dwordx4 v[176:177], off
	s_add_i32 m0, s20, 0x2000
	s_add_u32 s62, s18, 0xb0000
	v_lshl_add_u64 v[178:179], s[18:19], 0, v[134:135]
	s_addc_u32 s63, s19, 0
	s_add_i32 s20, s59, s16
	global_load_lds_dwordx4 v[178:179], off
	v_lshl_add_u64 v[194:195], s[62:63], 0, v[0:1]
	s_mov_b32 m0, s20
	v_lshl_add_u64 v[240:241], s[40:41], 0, v[132:133]
	global_load_lds_dwordx4 v[194:195], off
	v_lshl_add_u64 v[194:195], s[62:63], 0, v[134:135]
	s_add_i32 m0, s20, 0x2000
	s_nop 0
	global_load_lds_dwordx4 v[194:195], off
	v_lshl_add_u64 v[194:195], s[40:41], 0, v[130:131]
	s_mov_b32 m0, s17
	s_nop 0
	global_load_lds_dwordx4 v[194:195], off
	s_mov_b32 m0, s28
	s_nop 0
	global_load_lds_dwordx4 v[240:241], off
	s_waitcnt vmcnt(8)
	s_waitcnt lgkmcnt(0)
	s_barrier
	s_cmp_eq_u32 s32, 1
	s_cbranch_scc1 .Lh9_20
	s_setprio 1
	s_waitcnt lgkmcnt(0)
	v_mfma_f32_16x16x32_bf16 v[62:65], v[144:147], v[208:211], v[62:65]
	v_mfma_f32_16x16x32_bf16 v[58:61], v[152:155], v[208:211], v[58:61]
	v_mfma_f32_16x16x32_bf16 v[54:57], v[144:147], v[216:219], v[54:57]
	v_mfma_f32_16x16x32_bf16 v[50:53], v[152:155], v[216:219], v[50:53]
	s_setprio 0
	s_setprio 1
	v_mfma_f32_16x16x32_bf16 v[38:41], v[144:147], v[224:227], v[38:41]
	v_mfma_f32_16x16x32_bf16 v[34:37], v[152:155], v[224:227], v[34:37]
	v_mfma_f32_16x16x32_bf16 v[22:25], v[144:147], v[232:235], v[22:25]
	v_mfma_f32_16x16x32_bf16 v[18:21], v[152:155], v[232:235], v[18:21]
	s_setprio 0
	s_setprio 1
	v_mfma_f32_16x16x32_bf16 v[62:65], v[148:151], v[212:215], v[62:65]
	v_mfma_f32_16x16x32_bf16 v[58:61], v[158:161], v[212:215], v[58:61]
	v_mfma_f32_16x16x32_bf16 v[54:57], v[148:151], v[220:223], v[54:57]
	v_mfma_f32_16x16x32_bf16 v[50:53], v[158:161], v[220:223], v[50:53]
	s_setprio 0
	s_setprio 1
	v_mfma_f32_16x16x32_bf16 v[38:41], v[148:151], v[228:231], v[38:41]
	v_mfma_f32_16x16x32_bf16 v[34:37], v[158:161], v[228:231], v[34:37]
	v_mfma_f32_16x16x32_bf16 v[22:25], v[148:151], v[236:239], v[22:25]
	v_mfma_f32_16x16x32_bf16 v[18:21], v[158:161], v[236:239], v[18:21]
	s_setprio 0
	s_setprio 1
	v_mfma_f32_16x16x32_bf16 v[46:49], v[162:165], v[208:211], v[46:49]
	v_mfma_f32_16x16x32_bf16 v[42:45], v[200:203], v[208:211], v[42:45]
	v_mfma_f32_16x16x32_bf16 v[30:33], v[162:165], v[216:219], v[30:33]
	v_mfma_f32_16x16x32_bf16 v[26:29], v[200:203], v[216:219], v[26:29]
	s_setprio 0
	s_setprio 1
	v_mfma_f32_16x16x32_bf16 v[14:17], v[162:165], v[224:227], v[14:17]
	v_mfma_f32_16x16x32_bf16 v[10:13], v[200:203], v[224:227], v[10:13]
	v_mfma_f32_16x16x32_bf16 v[6:9], v[162:165], v[232:235], v[6:9]
	v_mfma_f32_16x16x32_bf16 v[2:5], v[200:203], v[232:235], v[2:5]
	s_setprio 0
	s_setprio 1
	v_mfma_f32_16x16x32_bf16 v[46:49], v[196:199], v[212:215], v[46:49]
	v_mfma_f32_16x16x32_bf16 v[42:45], v[204:207], v[212:215], v[42:45]
	v_mfma_f32_16x16x32_bf16 v[30:33], v[196:199], v[220:223], v[30:33]
	v_mfma_f32_16x16x32_bf16 v[26:29], v[204:207], v[220:223], v[26:29]
	s_setprio 0
	s_setprio 1
	v_mfma_f32_16x16x32_bf16 v[14:17], v[196:199], v[228:231], v[14:17]
	v_mfma_f32_16x16x32_bf16 v[10:13], v[204:207], v[228:231], v[10:13]
	v_mfma_f32_16x16x32_bf16 v[6:9], v[196:199], v[236:239], v[6:9]
	v_mfma_f32_16x16x32_bf16 v[2:5], v[204:207], v[236:239], v[2:5]
	s_setprio 0

.Lh9_21:
	global_load_lds_dwordx4 v[242:243], off
	v_lshl_add_u64 v[242:243], s[40:41], 0, v[132:133]
	s_mov_b32 m0, s43
	s_nop 0
	global_load_lds_dwordx4 v[242:243], off
	s_waitcnt vmcnt(8)
	s_waitcnt lgkmcnt(0)
	s_barrier
	s_cmp_eq_u32 s32, 2
	s_cbranch_scc1 .Lh9_22
	s_setprio 1
	s_waitcnt lgkmcnt(0)
	v_mfma_f32_16x16x32_bf16 v[126:129], v[144:147], v[208:211], v[126:129]
	v_mfma_f32_16x16x32_bf16 v[122:125], v[152:155], v[208:211], v[122:125]
	v_mfma_f32_16x16x32_bf16 v[118:121], v[144:147], v[216:219], v[118:121]
	v_mfma_f32_16x16x32_bf16 v[114:117], v[152:155], v[216:219], v[114:117]
	s_setprio 0
	s_setprio 1
	v_mfma_f32_16x16x32_bf16 v[102:105], v[144:147], v[224:227], v[102:105]
	v_mfma_f32_16x16x32_bf16 v[98:101], v[152:155], v[224:227], v[98:101]
	v_mfma_f32_16x16x32_bf16 v[86:89], v[144:147], v[232:235], v[86:89]
	v_mfma_f32_16x16x32_bf16 v[82:85], v[152:155], v[232:235], v[82:85]
	s_setprio 0
	s_setprio 1
	v_mfma_f32_16x16x32_bf16 v[126:129], v[148:151], v[212:215], v[126:129]
	v_mfma_f32_16x16x32_bf16 v[122:125], v[158:161], v[212:215], v[122:125]
	v_mfma_f32_16x16x32_bf16 v[118:121], v[148:151], v[220:223], v[118:121]
	v_mfma_f32_16x16x32_bf16 v[114:117], v[158:161], v[220:223], v[114:117]
	s_setprio 0
	s_setprio 1
	v_mfma_f32_16x16x32_bf16 v[102:105], v[148:151], v[228:231], v[102:105]
	v_mfma_f32_16x16x32_bf16 v[98:101], v[158:161], v[228:231], v[98:101]
	v_mfma_f32_16x16x32_bf16 v[86:89], v[148:151], v[236:239], v[86:89]
	v_mfma_f32_16x16x32_bf16 v[82:85], v[158:161], v[236:239], v[82:85]
	s_setprio 0
	s_setprio 1
	v_mfma_f32_16x16x32_bf16 v[110:113], v[162:165], v[208:211], v[110:113]
	v_mfma_f32_16x16x32_bf16 v[106:109], v[200:203], v[208:211], v[106:109]
	v_mfma_f32_16x16x32_bf16 v[94:97], v[162:165], v[216:219], v[94:97]
	v_mfma_f32_16x16x32_bf16 v[90:93], v[200:203], v[216:219], v[90:93]
	s_setprio 0
	s_setprio 1
	v_mfma_f32_16x16x32_bf16 v[78:81], v[162:165], v[224:227], v[78:81]
	v_mfma_f32_16x16x32_bf16 v[74:77], v[200:203], v[224:227], v[74:77]
	v_mfma_f32_16x16x32_bf16 v[70:73], v[162:165], v[232:235], v[70:73]
	v_mfma_f32_16x16x32_bf16 v[66:69], v[200:203], v[232:235], v[66:69]
	s_setprio 0
	s_setprio 1
	v_mfma_f32_16x16x32_bf16 v[110:113], v[196:199], v[212:215], v[110:113]
	v_mfma_f32_16x16x32_bf16 v[106:109], v[204:207], v[212:215], v[106:109]
	v_mfma_f32_16x16x32_bf16 v[94:97], v[196:199], v[220:223], v[94:97]
	v_mfma_f32_16x16x32_bf16 v[90:93], v[204:207], v[220:223], v[90:93]
	s_setprio 0
	s_setprio 1
	v_mfma_f32_16x16x32_bf16 v[78:81], v[196:199], v[228:231], v[78:81]
	v_mfma_f32_16x16x32_bf16 v[74:77], v[204:207], v[228:231], v[74:77]
	v_mfma_f32_16x16x32_bf16 v[70:73], v[196:199], v[236:239], v[70:73]
	v_mfma_f32_16x16x32_bf16 v[66:69], v[204:207], v[236:239], v[66:69]
	s_setprio 0

.Lh9_23:
	global_load_lds_dwordx4 v[176:177], off
	s_add_i32 m0, s20, 0x2000
	s_add_u32 s18, s18, 0xb0080
	v_lshl_add_u64 v[176:177], v[178:179], 0, s[24:25]
	s_addc_u32 s19, s19, 0
	s_add_i32 s20, s59, s16
	global_load_lds_dwordx4 v[176:177], off
	v_lshl_add_u64 v[176:177], s[18:19], 0, v[0:1]
	s_mov_b32 m0, s20
	s_nop 0
	global_load_lds_dwordx4 v[176:177], off
	v_lshl_add_u64 v[176:177], s[18:19], 0, v[134:135]
	s_add_i32 m0, s20, 0x2000
	s_nop 0
	global_load_lds_dwordx4 v[176:177], off
	v_lshl_add_u64 v[176:177], v[194:195], 0, s[24:25]
	s_mov_b32 m0, s46
	s_nop 0
	global_load_lds_dwordx4 v[176:177], off
	v_lshl_add_u64 v[176:177], v[240:241], 0, s[24:25]
	s_mov_b32 m0, s47
	s_nop 0
	global_load_lds_dwordx4 v[176:177], off
	s_waitcnt vmcnt(8)
	s_waitcnt lgkmcnt(0)
	s_barrier
	s_cmp_eq_u32 s32, 1
	s_cbranch_scc1 .Lh9_24
	s_setprio 1
	s_waitcnt lgkmcnt(0)
	v_mfma_f32_16x16x32_bf16 v[62:65], v[144:147], v[208:211], v[62:65]
	v_mfma_f32_16x16x32_bf16 v[58:61], v[152:155], v[208:211], v[58:61]
	v_mfma_f32_16x16x32_bf16 v[54:57], v[144:147], v[216:219], v[54:57]
	v_mfma_f32_16x16x32_bf16 v[50:53], v[152:155], v[216:219], v[50:53]
	s_setprio 0
	s_setprio 1
	v_mfma_f32_16x16x32_bf16 v[38:41], v[144:147], v[224:227], v[38:41]
	v_mfma_f32_16x16x32_bf16 v[34:37], v[152:155], v[224:227], v[34:37]
	v_mfma_f32_16x16x32_bf16 v[22:25], v[144:147], v[232:235], v[22:25]
	v_mfma_f32_16x16x32_bf16 v[18:21], v[152:155], v[232:235], v[18:21]
	s_setprio 0
	s_setprio 1
	v_mfma_f32_16x16x32_bf16 v[62:65], v[148:151], v[212:215], v[62:65]
	v_mfma_f32_16x16x32_bf16 v[58:61], v[158:161], v[212:215], v[58:61]
	v_mfma_f32_16x16x32_bf16 v[54:57], v[148:151], v[220:223], v[54:57]
	v_mfma_f32_16x16x32_bf16 v[50:53], v[158:161], v[220:223], v[50:53]
	s_setprio 0
	s_setprio 1
	v_mfma_f32_16x16x32_bf16 v[38:41], v[148:151], v[228:231], v[38:41]
	v_mfma_f32_16x16x32_bf16 v[34:37], v[158:161], v[228:231], v[34:37]
	v_mfma_f32_16x16x32_bf16 v[22:25], v[148:151], v[236:239], v[22:25]
	v_mfma_f32_16x16x32_bf16 v[18:21], v[158:161], v[236:239], v[18:21]
	s_setprio 0
	s_setprio 1
	v_mfma_f32_16x16x32_bf16 v[46:49], v[162:165], v[208:211], v[46:49]
	v_mfma_f32_16x16x32_bf16 v[42:45], v[200:203], v[208:211], v[42:45]
	v_mfma_f32_16x16x32_bf16 v[30:33], v[162:165], v[216:219], v[30:33]
	v_mfma_f32_16x16x32_bf16 v[26:29], v[200:203], v[216:219], v[26:29]
	s_setprio 0
	s_setprio 1
	v_mfma_f32_16x16x32_bf16 v[14:17], v[162:165], v[224:227], v[14:17]
	v_mfma_f32_16x16x32_bf16 v[10:13], v[200:203], v[224:227], v[10:13]
	v_mfma_f32_16x16x32_bf16 v[6:9], v[162:165], v[232:235], v[6:9]
	v_mfma_f32_16x16x32_bf16 v[2:5], v[200:203], v[232:235], v[2:5]
	s_setprio 0
	s_setprio 1
	v_mfma_f32_16x16x32_bf16 v[46:49], v[196:199], v[212:215], v[46:49]
	v_mfma_f32_16x16x32_bf16 v[42:45], v[204:207], v[212:215], v[42:45]
	v_mfma_f32_16x16x32_bf16 v[30:33], v[196:199], v[220:223], v[30:33]
	v_mfma_f32_16x16x32_bf16 v[26:29], v[204:207], v[220:223], v[26:29]
	s_setprio 0
	s_setprio 1
	v_mfma_f32_16x16x32_bf16 v[14:17], v[196:199], v[228:231], v[14:17]
	v_mfma_f32_16x16x32_bf16 v[10:13], v[204:207], v[228:231], v[10:13]
	v_mfma_f32_16x16x32_bf16 v[6:9], v[196:199], v[236:239], v[6:9]
	v_mfma_f32_16x16x32_bf16 v[2:5], v[204:207], v[236:239], v[2:5]
	s_setprio 0

.LBB0_81:
	s_add_u32 s20, s94, 0xfce78080
	s_addc_u32 s59, s95, -1
	s_cmp_lg_u32 s58, 12
	s_cselect_b32 s20, s20, 0
	s_cselect_b32 s59, s59, 0
	s_add_u32 vcc_lo, s40, s20
	s_addc_u32 vcc_hi, s41, s59
	s_add_i32 s82, 0, 0x10000
	s_add_u32 s96, s42, s20
	v_add_u32_e32 v143, s82, v141
	s_addc_u32 s97, s43, s59
	s_add_i32 s20, 0, 0x14000
	ds_read_b128 v[144:147], v143
	ds_read_b128 v[148:151], v143 offset:1024
	ds_read_b128 v[152:155], v143 offset:2048
	ds_read_b128 v[158:161], v143 offset:3072
	v_add_u32_e32 v143, s20, v141
	ds_read_b128 v[162:165], v143
	ds_read_b128 v[196:199], v143 offset:1024
	ds_read_b128 v[200:203], v143 offset:2048
	ds_read_b128 v[204:207], v143 offset:3072
	v_lshl_add_u64 v[176:177], v[138:139], 0, s[94:95]
	s_add_i32 m0, s16, 0xc000
	ds_read_b128 v[208:211], v142
	ds_read_b128 v[212:215], v142 offset:1024
	ds_read_b128 v[216:219], v142 offset:2048
	ds_read_b128 v[220:223], v142 offset:3072
	ds_read_b128 v[224:227], v142 offset:4096
	ds_read_b128 v[228:231], v142 offset:5120
	ds_read_b128 v[232:235], v142 offset:6144
	ds_read_b128 v[236:239], v142 offset:7168
	global_load_lds_dwordx4 v[176:177], off
	v_lshl_add_u64 v[176:177], v[136:137], 0, s[94:95]
	s_add_i32 m0, s16, 0xe000
	s_nop 0
	global_load_lds_dwordx4 v[176:177], off
	s_waitcnt vmcnt(8)
	s_waitcnt lgkmcnt(0)
	s_barrier
	s_setprio 1
	s_waitcnt lgkmcnt(0)
	v_mfma_f32_16x16x32_bf16 v[126:129], v[144:147], v[208:211], v[126:129]
	v_mfma_f32_16x16x32_bf16 v[122:125], v[152:155], v[208:211], v[122:125]
	v_mfma_f32_16x16x32_bf16 v[118:121], v[144:147], v[216:219], v[118:121]
	v_mfma_f32_16x16x32_bf16 v[114:117], v[152:155], v[216:219], v[114:117]
	s_setprio 0
	s_setprio 1
	v_mfma_f32_16x16x32_bf16 v[102:105], v[144:147], v[224:227], v[102:105]
	v_mfma_f32_16x16x32_bf16 v[98:101], v[152:155], v[224:227], v[98:101]
	v_mfma_f32_16x16x32_bf16 v[86:89], v[144:147], v[232:235], v[86:89]
	v_mfma_f32_16x16x32_bf16 v[82:85], v[152:155], v[232:235], v[82:85]
	s_setprio 0
	s_setprio 1
	v_mfma_f32_16x16x32_bf16 v[126:129], v[148:151], v[212:215], v[126:129]
	v_mfma_f32_16x16x32_bf16 v[122:125], v[158:161], v[212:215], v[122:125]
	v_mfma_f32_16x16x32_bf16 v[118:121], v[148:151], v[220:223], v[118:121]
	v_mfma_f32_16x16x32_bf16 v[114:117], v[158:161], v[220:223], v[114:117]
	s_setprio 0
	s_setprio 1
	v_mfma_f32_16x16x32_bf16 v[102:105], v[148:151], v[228:231], v[102:105]
	v_mfma_f32_16x16x32_bf16 v[98:101], v[158:161], v[228:231], v[98:101]
	v_mfma_f32_16x16x32_bf16 v[86:89], v[148:151], v[236:239], v[86:89]
	v_mfma_f32_16x16x32_bf16 v[82:85], v[158:161], v[236:239], v[82:85]
	s_setprio 0
	s_setprio 1
	v_mfma_f32_16x16x32_bf16 v[110:113], v[162:165], v[208:211], v[110:113]
	v_mfma_f32_16x16x32_bf16 v[106:109], v[200:203], v[208:211], v[106:109]
	v_mfma_f32_16x16x32_bf16 v[94:97], v[162:165], v[216:219], v[94:97]
	v_mfma_f32_16x16x32_bf16 v[90:93], v[200:203], v[216:219], v[90:93]
	s_setprio 0
	s_setprio 1
	v_mfma_f32_16x16x32_bf16 v[78:81], v[162:165], v[224:227], v[78:81]
	v_mfma_f32_16x16x32_bf16 v[74:77], v[200:203], v[224:227], v[74:77]
	v_mfma_f32_16x16x32_bf16 v[70:73], v[162:165], v[232:235], v[70:73]
	v_mfma_f32_16x16x32_bf16 v[66:69], v[200:203], v[232:235], v[66:69]
	s_setprio 0
	s_setprio 1
	v_mfma_f32_16x16x32_bf16 v[110:113], v[196:199], v[212:215], v[110:113]
	v_mfma_f32_16x16x32_bf16 v[106:109], v[204:207], v[212:215], v[106:109]
	v_mfma_f32_16x16x32_bf16 v[94:97], v[196:199], v[220:223], v[94:97]
	v_mfma_f32_16x16x32_bf16 v[90:93], v[204:207], v[220:223], v[90:93]
	s_setprio 0
	s_setprio 1
	v_mfma_f32_16x16x32_bf16 v[78:81], v[196:199], v[228:231], v[78:81]
	v_mfma_f32_16x16x32_bf16 v[74:77], v[204:207], v[228:231], v[74:77]
	v_mfma_f32_16x16x32_bf16 v[70:73], v[196:199], v[236:239], v[70:73]
	v_mfma_f32_16x16x32_bf16 v[66:69], v[204:207], v[236:239], v[66:69]
	s_setprio 0
	s_barrier
	s_add_i32 s59, s82, s3
	v_lshl_add_u64 v[176:177], s[96:97], 0, v[0:1]
	s_mov_b32 m0, s59
	ds_read_b128 v[208:211], v142 offset:16384
	ds_read_b128 v[212:215], v142 offset:17408
	ds_read_b128 v[216:219], v142 offset:18432
	ds_read_b128 v[220:223], v142 offset:19456
	ds_read_b128 v[224:227], v142 offset:20480
	ds_read_b128 v[228:231], v142 offset:21504
	ds_read_b128 v[232:235], v142 offset:22528
	ds_read_b128 v[236:239], v142 offset:23552
	global_load_lds_dwordx4 v[176:177], off
	s_add_i32 m0, s59, 0x2000
	s_add_u32 s82, s96, 0x580000
	v_lshl_add_u64 v[178:179], s[96:97], 0, v[134:135]
	s_addc_u32 s83, s97, 0
	s_add_i32 s20, s20, s3
	global_load_lds_dwordx4 v[178:179], off
	v_lshl_add_u64 v[194:195], s[82:83], 0, v[0:1]
	s_mov_b32 m0, s20
	v_lshl_add_u64 v[240:241], vcc, 0, v[132:133]
	global_load_lds_dwordx4 v[194:195], off
	v_lshl_add_u64 v[194:195], s[82:83], 0, v[134:135]
	s_add_i32 m0, s20, 0x2000
	s_nop 0
	global_load_lds_dwordx4 v[194:195], off
	v_lshl_add_u64 v[194:195], vcc, 0, v[130:131]
	s_mov_b32 m0, s16
	s_nop 0
	global_load_lds_dwordx4 v[194:195], off
	s_mov_b32 m0, s17
	s_nop 0
	global_load_lds_dwordx4 v[240:241], off
	s_waitcnt vmcnt(8)
	s_waitcnt lgkmcnt(0)
	s_barrier
	s_setprio 1
	s_waitcnt lgkmcnt(0)
	v_mfma_f32_16x16x32_bf16 v[62:65], v[144:147], v[208:211], v[62:65]
	v_mfma_f32_16x16x32_bf16 v[58:61], v[152:155], v[208:211], v[58:61]
	v_mfma_f32_16x16x32_bf16 v[54:57], v[144:147], v[216:219], v[54:57]
	v_mfma_f32_16x16x32_bf16 v[50:53], v[152:155], v[216:219], v[50:53]
	s_setprio 0
	s_setprio 1
	v_mfma_f32_16x16x32_bf16 v[38:41], v[144:147], v[224:227], v[38:41]
	v_mfma_f32_16x16x32_bf16 v[34:37], v[152:155], v[224:227], v[34:37]
	v_mfma_f32_16x16x32_bf16 v[22:25], v[144:147], v[232:235], v[22:25]
	v_mfma_f32_16x16x32_bf16 v[18:21], v[152:155], v[232:235], v[18:21]
	s_setprio 0
	s_setprio 1
	v_mfma_f32_16x16x32_bf16 v[62:65], v[148:151], v[212:215], v[62:65]
	v_mfma_f32_16x16x32_bf16 v[58:61], v[158:161], v[212:215], v[58:61]
	v_mfma_f32_16x16x32_bf16 v[54:57], v[148:151], v[220:223], v[54:57]
	v_mfma_f32_16x16x32_bf16 v[50:53], v[158:161], v[220:223], v[50:53]
	s_setprio 0
	s_setprio 1
	v_mfma_f32_16x16x32_bf16 v[38:41], v[148:151], v[228:231], v[38:41]
	v_mfma_f32_16x16x32_bf16 v[34:37], v[158:161], v[228:231], v[34:37]
	v_mfma_f32_16x16x32_bf16 v[22:25], v[148:151], v[236:239], v[22:25]
	v_mfma_f32_16x16x32_bf16 v[18:21], v[158:161], v[236:239], v[18:21]
	s_setprio 0
	s_setprio 1
	v_mfma_f32_16x16x32_bf16 v[46:49], v[162:165], v[208:211], v[46:49]
	v_mfma_f32_16x16x32_bf16 v[42:45], v[200:203], v[208:211], v[42:45]
	v_mfma_f32_16x16x32_bf16 v[30:33], v[162:165], v[216:219], v[30:33]
	v_mfma_f32_16x16x32_bf16 v[26:29], v[200:203], v[216:219], v[26:29]
	s_setprio 0
	s_setprio 1
	v_mfma_f32_16x16x32_bf16 v[14:17], v[162:165], v[224:227], v[14:17]
	v_mfma_f32_16x16x32_bf16 v[10:13], v[200:203], v[224:227], v[10:13]
	v_mfma_f32_16x16x32_bf16 v[6:9], v[162:165], v[232:235], v[6:9]
	v_mfma_f32_16x16x32_bf16 v[2:5], v[200:203], v[232:235], v[2:5]
	s_setprio 0
	s_setprio 1
	v_mfma_f32_16x16x32_bf16 v[46:49], v[196:199], v[212:215], v[46:49]
	v_mfma_f32_16x16x32_bf16 v[42:45], v[204:207], v[212:215], v[42:45]
	v_mfma_f32_16x16x32_bf16 v[30:33], v[196:199], v[220:223], v[30:33]
	v_mfma_f32_16x16x32_bf16 v[26:29], v[204:207], v[220:223], v[26:29]
	s_setprio 0
	s_setprio 1
	v_mfma_f32_16x16x32_bf16 v[14:17], v[196:199], v[228:231], v[14:17]
	v_mfma_f32_16x16x32_bf16 v[10:13], v[204:207], v[228:231], v[10:13]
	v_mfma_f32_16x16x32_bf16 v[6:9], v[196:199], v[236:239], v[6:9]
	v_mfma_f32_16x16x32_bf16 v[2:5], v[204:207], v[236:239], v[2:5]
	s_setprio 0
	s_barrier
	s_add_i32 s20, 0, 0x18000
	v_add_u32_e32 v143, s20, v141
	s_add_i32 s59, 0, 0x1c000
	ds_read_b128 v[144:147], v143
	ds_read_b128 v[148:151], v143 offset:1024
	ds_read_b128 v[152:155], v143 offset:2048
	ds_read_b128 v[158:161], v143 offset:3072
	v_add_u32_e32 v143, s59, v141
	ds_read_b128 v[162:165], v143
	ds_read_b128 v[196:199], v143 offset:1024
	ds_read_b128 v[200:203], v143 offset:2048
	ds_read_b128 v[204:207], v143 offset:3072
	s_add_u32 s82, vcc_lo, 0x40000
	s_addc_u32 s83, vcc_hi, 0
	s_mov_b32 m0, s28
	v_lshl_add_u64 v[242:243], s[82:83], 0, v[130:131]
	ds_read_b128 v[208:211], v142 offset:32768
	ds_read_b128 v[212:215], v142 offset:33792
	ds_read_b128 v[216:219], v142 offset:34816
	ds_read_b128 v[220:223], v142 offset:35840
	ds_read_b128 v[224:227], v142 offset:36864
	ds_read_b128 v[228:231], v142 offset:37888
	ds_read_b128 v[232:235], v142 offset:38912
	ds_read_b128 v[236:239], v142 offset:39936
	global_load_lds_dwordx4 v[242:243], off
	v_lshl_add_u64 v[242:243], s[82:83], 0, v[132:133]
	s_mov_b32 m0, s70
	s_nop 0
	global_load_lds_dwordx4 v[242:243], off
	s_waitcnt vmcnt(8)
	s_waitcnt lgkmcnt(0)
	s_barrier
	s_setprio 1
	s_waitcnt lgkmcnt(0)
	v_mfma_f32_16x16x32_bf16 v[126:129], v[144:147], v[208:211], v[126:129]
	v_mfma_f32_16x16x32_bf16 v[122:125], v[152:155], v[208:211], v[122:125]
	v_mfma_f32_16x16x32_bf16 v[118:121], v[144:147], v[216:219], v[118:121]
	v_mfma_f32_16x16x32_bf16 v[114:117], v[152:155], v[216:219], v[114:117]
	s_setprio 0
	s_setprio 1
	v_mfma_f32_16x16x32_bf16 v[102:105], v[144:147], v[224:227], v[102:105]
	v_mfma_f32_16x16x32_bf16 v[98:101], v[152:155], v[224:227], v[98:101]
	v_mfma_f32_16x16x32_bf16 v[86:89], v[144:147], v[232:235], v[86:89]
	v_mfma_f32_16x16x32_bf16 v[82:85], v[152:155], v[232:235], v[82:85]
	s_setprio 0
	s_setprio 1
	v_mfma_f32_16x16x32_bf16 v[126:129], v[148:151], v[212:215], v[126:129]
	v_mfma_f32_16x16x32_bf16 v[122:125], v[158:161], v[212:215], v[122:125]
	v_mfma_f32_16x16x32_bf16 v[118:121], v[148:151], v[220:223], v[118:121]
	v_mfma_f32_16x16x32_bf16 v[114:117], v[158:161], v[220:223], v[114:117]
	s_setprio 0
	s_setprio 1
	v_mfma_f32_16x16x32_bf16 v[102:105], v[148:151], v[228:231], v[102:105]
	v_mfma_f32_16x16x32_bf16 v[98:101], v[158:161], v[228:231], v[98:101]
	v_mfma_f32_16x16x32_bf16 v[86:89], v[148:151], v[236:239], v[86:89]
	v_mfma_f32_16x16x32_bf16 v[82:85], v[158:161], v[236:239], v[82:85]
	s_setprio 0
	s_setprio 1
	v_mfma_f32_16x16x32_bf16 v[110:113], v[162:165], v[208:211], v[110:113]
	v_mfma_f32_16x16x32_bf16 v[106:109], v[200:203], v[208:211], v[106:109]
	v_mfma_f32_16x16x32_bf16 v[94:97], v[162:165], v[216:219], v[94:97]
	v_mfma_f32_16x16x32_bf16 v[90:93], v[200:203], v[216:219], v[90:93]
	s_setprio 0
	s_setprio 1
	v_mfma_f32_16x16x32_bf16 v[78:81], v[162:165], v[224:227], v[78:81]
	v_mfma_f32_16x16x32_bf16 v[74:77], v[200:203], v[224:227], v[74:77]
	v_mfma_f32_16x16x32_bf16 v[70:73], v[162:165], v[232:235], v[70:73]
	v_mfma_f32_16x16x32_bf16 v[66:69], v[200:203], v[232:235], v[66:69]
	s_setprio 0
	s_setprio 1
	v_mfma_f32_16x16x32_bf16 v[110:113], v[196:199], v[212:215], v[110:113]
	v_mfma_f32_16x16x32_bf16 v[106:109], v[204:207], v[212:215], v[106:109]
	v_mfma_f32_16x16x32_bf16 v[94:97], v[196:199], v[220:223], v[94:97]
	v_mfma_f32_16x16x32_bf16 v[90:93], v[204:207], v[220:223], v[90:93]
	s_setprio 0
	s_setprio 1
	v_mfma_f32_16x16x32_bf16 v[78:81], v[196:199], v[228:231], v[78:81]
	v_mfma_f32_16x16x32_bf16 v[74:77], v[204:207], v[228:231], v[74:77]
	v_mfma_f32_16x16x32_bf16 v[70:73], v[196:199], v[236:239], v[70:73]
	v_mfma_f32_16x16x32_bf16 v[66:69], v[204:207], v[236:239], v[66:69]
	s_setprio 0
	s_barrier
	s_add_i32 s20, s20, s3
	v_lshl_add_u64 v[176:177], v[176:177], 0, s[24:25]
	s_mov_b32 m0, s20
	ds_read_b128 v[208:211], v142 offset:49152
	ds_read_b128 v[212:215], v142 offset:50176
	ds_read_b128 v[216:219], v142 offset:51200
	ds_read_b128 v[220:223], v142 offset:52224
	ds_read_b128 v[224:227], v142 offset:53248
	ds_read_b128 v[228:231], v142 offset:54272
	ds_read_b128 v[232:235], v142 offset:55296
	ds_read_b128 v[236:239], v142 offset:56320
	global_load_lds_dwordx4 v[176:177], off
	s_add_i32 m0, s20, 0x2000
	s_add_u32 s82, s96, 0x580080
	v_lshl_add_u64 v[176:177], v[178:179], 0, s[24:25]
	s_addc_u32 s83, s97, 0
	s_add_i32 s20, s59, s3
	global_load_lds_dwordx4 v[176:177], off
	v_lshl_add_u64 v[176:177], s[82:83], 0, v[0:1]
	s_mov_b32 m0, s20
	s_nop 0
	global_load_lds_dwordx4 v[176:177], off
	v_lshl_add_u64 v[176:177], s[82:83], 0, v[134:135]
	s_add_i32 m0, s20, 0x2000
	s_nop 0
	global_load_lds_dwordx4 v[176:177], off
	v_lshl_add_u64 v[176:177], v[194:195], 0, s[24:25]
	s_mov_b32 m0, s86
	s_nop 0
	global_load_lds_dwordx4 v[176:177], off
	v_lshl_add_u64 v[176:177], v[240:241], 0, s[24:25]
	s_mov_b32 m0, s87
	s_nop 0
	global_load_lds_dwordx4 v[176:177], off
	s_waitcnt vmcnt(8)
	s_waitcnt lgkmcnt(0)
	s_barrier
	s_setprio 1
	s_waitcnt lgkmcnt(0)
	v_mfma_f32_16x16x32_bf16 v[62:65], v[144:147], v[208:211], v[62:65]
	v_mfma_f32_16x16x32_bf16 v[58:61], v[152:155], v[208:211], v[58:61]
	v_mfma_f32_16x16x32_bf16 v[54:57], v[144:147], v[216:219], v[54:57]
	v_mfma_f32_16x16x32_bf16 v[50:53], v[152:155], v[216:219], v[50:53]
	s_setprio 0
	s_setprio 1
	v_mfma_f32_16x16x32_bf16 v[38:41], v[144:147], v[224:227], v[38:41]
	v_mfma_f32_16x16x32_bf16 v[34:37], v[152:155], v[224:227], v[34:37]
	v_mfma_f32_16x16x32_bf16 v[22:25], v[144:147], v[232:235], v[22:25]
	v_mfma_f32_16x16x32_bf16 v[18:21], v[152:155], v[232:235], v[18:21]
	s_setprio 0
	s_setprio 1
	v_mfma_f32_16x16x32_bf16 v[62:65], v[148:151], v[212:215], v[62:65]
	v_mfma_f32_16x16x32_bf16 v[58:61], v[158:161], v[212:215], v[58:61]
	v_mfma_f32_16x16x32_bf16 v[54:57], v[148:151], v[220:223], v[54:57]
	v_mfma_f32_16x16x32_bf16 v[50:53], v[158:161], v[220:223], v[50:53]
	s_setprio 0
	s_setprio 1
	v_mfma_f32_16x16x32_bf16 v[38:41], v[148:151], v[228:231], v[38:41]
	v_mfma_f32_16x16x32_bf16 v[34:37], v[158:161], v[228:231], v[34:37]
	v_mfma_f32_16x16x32_bf16 v[22:25], v[148:151], v[236:239], v[22:25]
	v_mfma_f32_16x16x32_bf16 v[18:21], v[158:161], v[236:239], v[18:21]
	s_setprio 0
	s_setprio 1
	v_mfma_f32_16x16x32_bf16 v[46:49], v[162:165], v[208:211], v[46:49]
	v_mfma_f32_16x16x32_bf16 v[42:45], v[200:203], v[208:211], v[42:45]
	v_mfma_f32_16x16x32_bf16 v[30:33], v[162:165], v[216:219], v[30:33]
	v_mfma_f32_16x16x32_bf16 v[26:29], v[200:203], v[216:219], v[26:29]
	s_setprio 0
	s_setprio 1
	v_mfma_f32_16x16x32_bf16 v[14:17], v[162:165], v[224:227], v[14:17]
	v_mfma_f32_16x16x32_bf16 v[10:13], v[200:203], v[224:227], v[10:13]
	v_mfma_f32_16x16x32_bf16 v[6:9], v[162:165], v[232:235], v[6:9]
	v_mfma_f32_16x16x32_bf16 v[2:5], v[200:203], v[232:235], v[2:5]
	s_setprio 0
	s_setprio 1
	v_mfma_f32_16x16x32_bf16 v[46:49], v[196:199], v[212:215], v[46:49]
	v_mfma_f32_16x16x32_bf16 v[42:45], v[204:207], v[212:215], v[42:45]
	v_mfma_f32_16x16x32_bf16 v[30:33], v[196:199], v[220:223], v[30:33]
	v_mfma_f32_16x16x32_bf16 v[26:29], v[204:207], v[220:223], v[26:29]
	s_setprio 0
	s_setprio 1
	v_mfma_f32_16x16x32_bf16 v[14:17], v[196:199], v[228:231], v[14:17]
	v_mfma_f32_16x16x32_bf16 v[10:13], v[204:207], v[228:231], v[10:13]
	v_mfma_f32_16x16x32_bf16 v[6:9], v[196:199], v[236:239], v[6:9]
	v_mfma_f32_16x16x32_bf16 v[2:5], v[204:207], v[236:239], v[2:5]
	s_setprio 0
	s_barrier
	s_add_i32 s58, s58, 2
	s_add_u32 s94, s94, 0x100
	s_addc_u32 s95, s95, 0
	s_cmp_gt_u32 s58, 13
	s_cbranch_scc0 .LBB0_81
	s_waitcnt vmcnt(0)
	s_cmpk_lt_u32 s1, 0x100
	s_cbranch_scc0 .LBB0_84
	s_barrier

.LBB0_173:
	s_add_u32 s20, s18, 0xf5678080
	s_addc_u32 s40, s19, -1
	s_cmp_lg_u32 s47, 12
	s_cselect_b32 s20, s20, 0
	s_cselect_b32 s41, s40, 0
	s_add_u32 s42, s2, s20
	s_addc_u32 s43, s3, s41
	s_add_i32 s52, 0, 0x10000
	s_add_u32 s40, s8, s20
	v_add_u32_e32 v143, s52, v141
	s_addc_u32 s41, s9, s41
	s_add_i32 s20, 0, 0x14000
	ds_read_b128 v[144:147], v143
	ds_read_b128 v[148:151], v143 offset:1024
	ds_read_b128 v[152:155], v143 offset:2048
	ds_read_b128 v[158:161], v143 offset:3072
	v_add_u32_e32 v143, s20, v141
	ds_read_b128 v[162:165], v143
	ds_read_b128 v[196:199], v143 offset:1024
	ds_read_b128 v[200:203], v143 offset:2048
	ds_read_b128 v[204:207], v143 offset:3072
	v_lshl_add_u64 v[176:177], v[138:139], 0, s[18:19]
	s_add_i32 m0, s12, 0xc000
	ds_read_b128 v[208:211], v142
	ds_read_b128 v[212:215], v142 offset:1024
	ds_read_b128 v[216:219], v142 offset:2048
	ds_read_b128 v[220:223], v142 offset:3072
	ds_read_b128 v[224:227], v142 offset:4096
	ds_read_b128 v[228:231], v142 offset:5120
	ds_read_b128 v[232:235], v142 offset:6144
	ds_read_b128 v[236:239], v142 offset:7168
	global_load_lds_dwordx4 v[176:177], off
	v_lshl_add_u64 v[176:177], v[136:137], 0, s[18:19]
	s_add_i32 m0, s12, 0xe000
	s_nop 0
	global_load_lds_dwordx4 v[176:177], off
	s_waitcnt vmcnt(8)
	s_waitcnt lgkmcnt(0)
	s_barrier
	s_setprio 1
	s_waitcnt lgkmcnt(0)
	v_mfma_f32_16x16x32_bf16 v[126:129], v[144:147], v[208:211], v[126:129]
	v_mfma_f32_16x16x32_bf16 v[122:125], v[152:155], v[208:211], v[122:125]
	v_mfma_f32_16x16x32_bf16 v[118:121], v[144:147], v[216:219], v[118:121]
	v_mfma_f32_16x16x32_bf16 v[114:117], v[152:155], v[216:219], v[114:117]
	s_setprio 0
	s_setprio 1
	v_mfma_f32_16x16x32_bf16 v[102:105], v[144:147], v[224:227], v[102:105]
	v_mfma_f32_16x16x32_bf16 v[98:101], v[152:155], v[224:227], v[98:101]
	v_mfma_f32_16x16x32_bf16 v[86:89], v[144:147], v[232:235], v[86:89]
	v_mfma_f32_16x16x32_bf16 v[82:85], v[152:155], v[232:235], v[82:85]
	s_setprio 0
	s_setprio 1
	v_mfma_f32_16x16x32_bf16 v[126:129], v[148:151], v[212:215], v[126:129]
	v_mfma_f32_16x16x32_bf16 v[122:125], v[158:161], v[212:215], v[122:125]
	v_mfma_f32_16x16x32_bf16 v[118:121], v[148:151], v[220:223], v[118:121]
	v_mfma_f32_16x16x32_bf16 v[114:117], v[158:161], v[220:223], v[114:117]
	s_setprio 0
	s_setprio 1
	v_mfma_f32_16x16x32_bf16 v[102:105], v[148:151], v[228:231], v[102:105]
	v_mfma_f32_16x16x32_bf16 v[98:101], v[158:161], v[228:231], v[98:101]
	v_mfma_f32_16x16x32_bf16 v[86:89], v[148:151], v[236:239], v[86:89]
	v_mfma_f32_16x16x32_bf16 v[82:85], v[158:161], v[236:239], v[82:85]
	s_setprio 0
	s_setprio 1
	v_mfma_f32_16x16x32_bf16 v[110:113], v[162:165], v[208:211], v[110:113]
	v_mfma_f32_16x16x32_bf16 v[106:109], v[200:203], v[208:211], v[106:109]
	v_mfma_f32_16x16x32_bf16 v[94:97], v[162:165], v[216:219], v[94:97]
	v_mfma_f32_16x16x32_bf16 v[90:93], v[200:203], v[216:219], v[90:93]
	s_setprio 0
	s_setprio 1
	v_mfma_f32_16x16x32_bf16 v[78:81], v[162:165], v[224:227], v[78:81]
	v_mfma_f32_16x16x32_bf16 v[74:77], v[200:203], v[224:227], v[74:77]
	v_mfma_f32_16x16x32_bf16 v[70:73], v[162:165], v[232:235], v[70:73]
	v_mfma_f32_16x16x32_bf16 v[66:69], v[200:203], v[232:235], v[66:69]
	s_setprio 0
	s_setprio 1
	v_mfma_f32_16x16x32_bf16 v[110:113], v[196:199], v[212:215], v[110:113]
	v_mfma_f32_16x16x32_bf16 v[106:109], v[204:207], v[212:215], v[106:109]
	v_mfma_f32_16x16x32_bf16 v[94:97], v[196:199], v[220:223], v[94:97]
	v_mfma_f32_16x16x32_bf16 v[90:93], v[204:207], v[220:223], v[90:93]
	s_setprio 0
	s_setprio 1
	v_mfma_f32_16x16x32_bf16 v[78:81], v[196:199], v[228:231], v[78:81]
	v_mfma_f32_16x16x32_bf16 v[74:77], v[204:207], v[228:231], v[74:77]
	v_mfma_f32_16x16x32_bf16 v[70:73], v[196:199], v[236:239], v[70:73]
	v_mfma_f32_16x16x32_bf16 v[66:69], v[204:207], v[236:239], v[66:69]
	s_setprio 0
	s_barrier
	s_add_i32 s52, s52, s11
	v_lshl_add_u64 v[176:177], s[40:41], 0, v[0:1]
	s_mov_b32 m0, s52
	ds_read_b128 v[208:211], v142 offset:16384
	ds_read_b128 v[212:215], v142 offset:17408
	ds_read_b128 v[216:219], v142 offset:18432
	ds_read_b128 v[220:223], v142 offset:19456
	ds_read_b128 v[224:227], v142 offset:20480
	ds_read_b128 v[228:231], v142 offset:21504
	ds_read_b128 v[232:235], v142 offset:22528
	ds_read_b128 v[236:239], v142 offset:23552
	global_load_lds_dwordx4 v[176:177], off
	s_add_i32 m0, s52, 0x2000
	s_add_u32 s52, s40, 0x40000
	v_lshl_add_u64 v[178:179], s[40:41], 0, v[134:135]
	s_addc_u32 s53, s41, 0
	s_add_i32 s20, s20, s11
	global_load_lds_dwordx4 v[178:179], off
	v_lshl_add_u64 v[194:195], s[52:53], 0, v[0:1]
	s_mov_b32 m0, s20
	v_lshl_add_u64 v[240:241], s[42:43], 0, v[132:133]
	global_load_lds_dwordx4 v[194:195], off
	v_lshl_add_u64 v[194:195], s[52:53], 0, v[134:135]
	s_add_i32 m0, s20, 0x2000
	s_nop 0
	global_load_lds_dwordx4 v[194:195], off
	v_lshl_add_u64 v[194:195], s[42:43], 0, v[130:131]
	s_mov_b32 m0, s12
	s_nop 0
	global_load_lds_dwordx4 v[194:195], off
	s_mov_b32 m0, s13
	s_nop 0
	global_load_lds_dwordx4 v[240:241], off
	s_waitcnt vmcnt(8)
	s_waitcnt lgkmcnt(0)
	s_barrier
	s_setprio 1
	s_waitcnt lgkmcnt(0)
	v_mfma_f32_16x16x32_bf16 v[62:65], v[144:147], v[208:211], v[62:65]
	v_mfma_f32_16x16x32_bf16 v[58:61], v[152:155], v[208:211], v[58:61]
	v_mfma_f32_16x16x32_bf16 v[54:57], v[144:147], v[216:219], v[54:57]
	v_mfma_f32_16x16x32_bf16 v[50:53], v[152:155], v[216:219], v[50:53]
	s_setprio 0
	s_setprio 1
	v_mfma_f32_16x16x32_bf16 v[38:41], v[144:147], v[224:227], v[38:41]
	v_mfma_f32_16x16x32_bf16 v[34:37], v[152:155], v[224:227], v[34:37]
	v_mfma_f32_16x16x32_bf16 v[22:25], v[144:147], v[232:235], v[22:25]
	v_mfma_f32_16x16x32_bf16 v[18:21], v[152:155], v[232:235], v[18:21]
	s_setprio 0
	s_setprio 1
	v_mfma_f32_16x16x32_bf16 v[62:65], v[148:151], v[212:215], v[62:65]
	v_mfma_f32_16x16x32_bf16 v[58:61], v[158:161], v[212:215], v[58:61]
	v_mfma_f32_16x16x32_bf16 v[54:57], v[148:151], v[220:223], v[54:57]
	v_mfma_f32_16x16x32_bf16 v[50:53], v[158:161], v[220:223], v[50:53]
	s_setprio 0
	s_setprio 1
	v_mfma_f32_16x16x32_bf16 v[38:41], v[148:151], v[228:231], v[38:41]
	v_mfma_f32_16x16x32_bf16 v[34:37], v[158:161], v[228:231], v[34:37]
	v_mfma_f32_16x16x32_bf16 v[22:25], v[148:151], v[236:239], v[22:25]
	v_mfma_f32_16x16x32_bf16 v[18:21], v[158:161], v[236:239], v[18:21]
	s_setprio 0
	s_setprio 1
	v_mfma_f32_16x16x32_bf16 v[46:49], v[162:165], v[208:211], v[46:49]
	v_mfma_f32_16x16x32_bf16 v[42:45], v[200:203], v[208:211], v[42:45]
	v_mfma_f32_16x16x32_bf16 v[30:33], v[162:165], v[216:219], v[30:33]
	v_mfma_f32_16x16x32_bf16 v[26:29], v[200:203], v[216:219], v[26:29]
	s_setprio 0
	s_setprio 1
	v_mfma_f32_16x16x32_bf16 v[14:17], v[162:165], v[224:227], v[14:17]
	v_mfma_f32_16x16x32_bf16 v[10:13], v[200:203], v[224:227], v[10:13]
	v_mfma_f32_16x16x32_bf16 v[6:9], v[162:165], v[232:235], v[6:9]
	v_mfma_f32_16x16x32_bf16 v[2:5], v[200:203], v[232:235], v[2:5]
	s_setprio 0
	s_setprio 1
	v_mfma_f32_16x16x32_bf16 v[46:49], v[196:199], v[212:215], v[46:49]
	v_mfma_f32_16x16x32_bf16 v[42:45], v[204:207], v[212:215], v[42:45]
	v_mfma_f32_16x16x32_bf16 v[30:33], v[196:199], v[220:223], v[30:33]
	v_mfma_f32_16x16x32_bf16 v[26:29], v[204:207], v[220:223], v[26:29]
	s_setprio 0
	s_setprio 1
	v_mfma_f32_16x16x32_bf16 v[14:17], v[196:199], v[228:231], v[14:17]
	v_mfma_f32_16x16x32_bf16 v[10:13], v[204:207], v[228:231], v[10:13]
	v_mfma_f32_16x16x32_bf16 v[6:9], v[196:199], v[236:239], v[6:9]
	v_mfma_f32_16x16x32_bf16 v[2:5], v[204:207], v[236:239], v[2:5]
	s_setprio 0
	s_barrier
	s_add_i32 s20, 0, 0x18000
	v_add_u32_e32 v143, s20, v141
	s_add_i32 s52, 0, 0x1c000
	ds_read_b128 v[144:147], v143
	ds_read_b128 v[148:151], v143 offset:1024
	ds_read_b128 v[152:155], v143 offset:2048
	ds_read_b128 v[158:161], v143 offset:3072
	v_add_u32_e32 v143, s52, v141
	ds_read_b128 v[162:165], v143
	ds_read_b128 v[196:199], v143 offset:1024
	ds_read_b128 v[200:203], v143 offset:2048
	ds_read_b128 v[204:207], v143 offset:3072
	s_add_u32 s42, s42, 0x40000
	s_addc_u32 s43, s43, 0
	s_mov_b32 m0, s16
	v_lshl_add_u64 v[242:243], s[42:43], 0, v[130:131]
	ds_read_b128 v[208:211], v142 offset:32768
	ds_read_b128 v[212:215], v142 offset:33792
	ds_read_b128 v[216:219], v142 offset:34816
	ds_read_b128 v[220:223], v142 offset:35840
	ds_read_b128 v[224:227], v142 offset:36864
	ds_read_b128 v[228:231], v142 offset:37888
	ds_read_b128 v[232:235], v142 offset:38912
	ds_read_b128 v[236:239], v142 offset:39936
	global_load_lds_dwordx4 v[242:243], off
	v_lshl_add_u64 v[242:243], s[42:43], 0, v[132:133]
	s_mov_b32 m0, s17
	s_nop 0
	global_load_lds_dwordx4 v[242:243], off
	s_waitcnt vmcnt(8)
	s_waitcnt lgkmcnt(0)
	s_barrier
	s_setprio 1
	s_waitcnt lgkmcnt(0)
	v_mfma_f32_16x16x32_bf16 v[126:129], v[144:147], v[208:211], v[126:129]
	v_mfma_f32_16x16x32_bf16 v[122:125], v[152:155], v[208:211], v[122:125]
	v_mfma_f32_16x16x32_bf16 v[118:121], v[144:147], v[216:219], v[118:121]
	v_mfma_f32_16x16x32_bf16 v[114:117], v[152:155], v[216:219], v[114:117]
	s_setprio 0
	s_setprio 1
	v_mfma_f32_16x16x32_bf16 v[102:105], v[144:147], v[224:227], v[102:105]
	v_mfma_f32_16x16x32_bf16 v[98:101], v[152:155], v[224:227], v[98:101]
	v_mfma_f32_16x16x32_bf16 v[86:89], v[144:147], v[232:235], v[86:89]
	v_mfma_f32_16x16x32_bf16 v[82:85], v[152:155], v[232:235], v[82:85]
	s_setprio 0
	s_setprio 1
	v_mfma_f32_16x16x32_bf16 v[126:129], v[148:151], v[212:215], v[126:129]
	v_mfma_f32_16x16x32_bf16 v[122:125], v[158:161], v[212:215], v[122:125]
	v_mfma_f32_16x16x32_bf16 v[118:121], v[148:151], v[220:223], v[118:121]
	v_mfma_f32_16x16x32_bf16 v[114:117], v[158:161], v[220:223], v[114:117]
	s_setprio 0
	s_setprio 1
	v_mfma_f32_16x16x32_bf16 v[102:105], v[148:151], v[228:231], v[102:105]
	v_mfma_f32_16x16x32_bf16 v[98:101], v[158:161], v[228:231], v[98:101]
	v_mfma_f32_16x16x32_bf16 v[86:89], v[148:151], v[236:239], v[86:89]
	v_mfma_f32_16x16x32_bf16 v[82:85], v[158:161], v[236:239], v[82:85]
	s_setprio 0
	s_setprio 1
	v_mfma_f32_16x16x32_bf16 v[110:113], v[162:165], v[208:211], v[110:113]
	v_mfma_f32_16x16x32_bf16 v[106:109], v[200:203], v[208:211], v[106:109]
	v_mfma_f32_16x16x32_bf16 v[94:97], v[162:165], v[216:219], v[94:97]
	v_mfma_f32_16x16x32_bf16 v[90:93], v[200:203], v[216:219], v[90:93]
	s_setprio 0
	s_setprio 1
	v_mfma_f32_16x16x32_bf16 v[78:81], v[162:165], v[224:227], v[78:81]
	v_mfma_f32_16x16x32_bf16 v[74:77], v[200:203], v[224:227], v[74:77]
	v_mfma_f32_16x16x32_bf16 v[70:73], v[162:165], v[232:235], v[70:73]
	v_mfma_f32_16x16x32_bf16 v[66:69], v[200:203], v[232:235], v[66:69]
	s_setprio 0
	s_setprio 1
	v_mfma_f32_16x16x32_bf16 v[110:113], v[196:199], v[212:215], v[110:113]
	v_mfma_f32_16x16x32_bf16 v[106:109], v[204:207], v[212:215], v[106:109]
	v_mfma_f32_16x16x32_bf16 v[94:97], v[196:199], v[220:223], v[94:97]
	v_mfma_f32_16x16x32_bf16 v[90:93], v[204:207], v[220:223], v[90:93]
	s_setprio 0
	s_setprio 1
	v_mfma_f32_16x16x32_bf16 v[78:81], v[196:199], v[228:231], v[78:81]
	v_mfma_f32_16x16x32_bf16 v[74:77], v[204:207], v[228:231], v[74:77]
	v_mfma_f32_16x16x32_bf16 v[70:73], v[196:199], v[236:239], v[70:73]
	v_mfma_f32_16x16x32_bf16 v[66:69], v[204:207], v[236:239], v[66:69]
	s_setprio 0
	s_barrier
	s_add_i32 s20, s20, s11
	v_lshl_add_u64 v[176:177], v[176:177], 0, s[24:25]
	s_mov_b32 m0, s20
	ds_read_b128 v[208:211], v142 offset:49152
	ds_read_b128 v[212:215], v142 offset:50176
	ds_read_b128 v[216:219], v142 offset:51200
	ds_read_b128 v[220:223], v142 offset:52224
	ds_read_b128 v[224:227], v142 offset:53248
	ds_read_b128 v[228:231], v142 offset:54272
	ds_read_b128 v[232:235], v142 offset:55296
	ds_read_b128 v[236:239], v142 offset:56320
	global_load_lds_dwordx4 v[176:177], off
	s_add_i32 m0, s20, 0x2000
	s_add_u32 s40, s40, 0x40080
	v_lshl_add_u64 v[176:177], v[178:179], 0, s[24:25]
	s_addc_u32 s41, s41, 0
	s_add_i32 s20, s52, s11
	global_load_lds_dwordx4 v[176:177], off
	v_lshl_add_u64 v[176:177], s[40:41], 0, v[0:1]
	s_mov_b32 m0, s20
	s_nop 0
	global_load_lds_dwordx4 v[176:177], off
	v_lshl_add_u64 v[176:177], s[40:41], 0, v[134:135]
	s_add_i32 m0, s20, 0x2000
	s_nop 0
	global_load_lds_dwordx4 v[176:177], off
	v_lshl_add_u64 v[176:177], v[194:195], 0, s[24:25]
	s_mov_b32 m0, s28
	s_nop 0
	global_load_lds_dwordx4 v[176:177], off
	v_lshl_add_u64 v[176:177], v[240:241], 0, s[24:25]
	s_mov_b32 m0, s46
	s_nop 0
	global_load_lds_dwordx4 v[176:177], off
	s_waitcnt vmcnt(8)
	s_waitcnt lgkmcnt(0)
	s_barrier
	s_setprio 1
	s_waitcnt lgkmcnt(0)
	v_mfma_f32_16x16x32_bf16 v[62:65], v[144:147], v[208:211], v[62:65]
	v_mfma_f32_16x16x32_bf16 v[58:61], v[152:155], v[208:211], v[58:61]
	v_mfma_f32_16x16x32_bf16 v[54:57], v[144:147], v[216:219], v[54:57]
	v_mfma_f32_16x16x32_bf16 v[50:53], v[152:155], v[216:219], v[50:53]
	s_setprio 0
	s_setprio 1
	v_mfma_f32_16x16x32_bf16 v[38:41], v[144:147], v[224:227], v[38:41]
	v_mfma_f32_16x16x32_bf16 v[34:37], v[152:155], v[224:227], v[34:37]
	v_mfma_f32_16x16x32_bf16 v[22:25], v[144:147], v[232:235], v[22:25]
	v_mfma_f32_16x16x32_bf16 v[18:21], v[152:155], v[232:235], v[18:21]
	s_setprio 0
	s_setprio 1
	v_mfma_f32_16x16x32_bf16 v[62:65], v[148:151], v[212:215], v[62:65]
	v_mfma_f32_16x16x32_bf16 v[58:61], v[158:161], v[212:215], v[58:61]
	v_mfma_f32_16x16x32_bf16 v[54:57], v[148:151], v[220:223], v[54:57]
	v_mfma_f32_16x16x32_bf16 v[50:53], v[158:161], v[220:223], v[50:53]
	s_setprio 0
	s_setprio 1
	v_mfma_f32_16x16x32_bf16 v[38:41], v[148:151], v[228:231], v[38:41]
	v_mfma_f32_16x16x32_bf16 v[34:37], v[158:161], v[228:231], v[34:37]
	v_mfma_f32_16x16x32_bf16 v[22:25], v[148:151], v[236:239], v[22:25]
	v_mfma_f32_16x16x32_bf16 v[18:21], v[158:161], v[236:239], v[18:21]
	s_setprio 0
	s_setprio 1
	v_mfma_f32_16x16x32_bf16 v[46:49], v[162:165], v[208:211], v[46:49]
	v_mfma_f32_16x16x32_bf16 v[42:45], v[200:203], v[208:211], v[42:45]
	v_mfma_f32_16x16x32_bf16 v[30:33], v[162:165], v[216:219], v[30:33]
	v_mfma_f32_16x16x32_bf16 v[26:29], v[200:203], v[216:219], v[26:29]
	s_setprio 0
	s_setprio 1
	v_mfma_f32_16x16x32_bf16 v[14:17], v[162:165], v[224:227], v[14:17]
	v_mfma_f32_16x16x32_bf16 v[10:13], v[200:203], v[224:227], v[10:13]
	v_mfma_f32_16x16x32_bf16 v[6:9], v[162:165], v[232:235], v[6:9]
	v_mfma_f32_16x16x32_bf16 v[2:5], v[200:203], v[232:235], v[2:5]
	s_setprio 0
	s_setprio 1
	v_mfma_f32_16x16x32_bf16 v[46:49], v[196:199], v[212:215], v[46:49]
	v_mfma_f32_16x16x32_bf16 v[42:45], v[204:207], v[212:215], v[42:45]
	v_mfma_f32_16x16x32_bf16 v[30:33], v[196:199], v[220:223], v[30:33]
	v_mfma_f32_16x16x32_bf16 v[26:29], v[204:207], v[220:223], v[26:29]
	s_setprio 0
	s_setprio 1
	v_mfma_f32_16x16x32_bf16 v[14:17], v[196:199], v[228:231], v[14:17]
	v_mfma_f32_16x16x32_bf16 v[10:13], v[204:207], v[228:231], v[10:13]
	v_mfma_f32_16x16x32_bf16 v[6:9], v[196:199], v[236:239], v[6:9]
	v_mfma_f32_16x16x32_bf16 v[2:5], v[204:207], v[236:239], v[2:5]
	s_setprio 0
	s_barrier
	s_add_i32 s47, s47, 2
	s_add_u32 s18, s18, 0x100
	s_addc_u32 s19, s19, 0
	s_cmp_gt_u32 s47, 13
	s_cbranch_scc0 .LBB0_173
	s_waitcnt vmcnt(0)
	s_cmpk_lt_u32 s1, 0x100
	s_cbranch_scc0 .LBB0_169
	s_barrier
	s_branch .LBB0_169

.LBB0_336:
	s_add_u32 s20, s12, s56
	s_addc_u32 s58, s13, s57
	s_cmpk_eq_i32 s56, 0x700
	s_cselect_b64 s[6:7], -1, 0
	s_and_b64 s[10:11], s[6:7], exec
	s_cselect_b32 s62, vcc_lo, s20
	s_cselect_b32 s63, s97, s58
	s_and_b64 s[66:67], s[2:3], s[6:7]
	s_and_b64 s[6:7], s[66:67], exec
	s_cselect_b32 s10, s86, s40
	s_add_u32 s6, s16, s56
	s_addc_u32 s7, s17, s57
	s_add_u32 s11, s6, 0x3148100
	s_addc_u32 s20, s7, 0
	s_cmpk_eq_i32 s56, 0x700
	s_cselect_b64 s[6:7], -1, 0
	s_and_b64 s[6:7], s[6:7], exec
	s_cselect_b32 s58, s10, s11
	s_and_b64 s[6:7], s[66:67], exec
	s_cselect_b32 s10, s93, s41
	s_cmpk_eq_i32 s56, 0x700
	s_cselect_b64 s[84:85], -1, 0
	s_and_b64 s[6:7], s[84:85], exec
	s_cselect_b32 s59, s10, s20
	s_and_b64 s[6:7], s[66:67], exec
	s_mov_b32 s6, 0x20000
	s_cselect_b32 s66, s6, 0x40000
	s_cselect_b32 s10, 9, 10
	s_add_i32 s6, 0, 0x10000
	v_add_u32_e32 v154, s6, v143
	s_add_i32 s7, 0, 0x14000
	ds_read_b128 v[146:149], v154
	ds_read_b128 v[150:153], v154 offset:1024
	ds_read_b128 v[158:161], v154 offset:2048
	ds_read_b128 v[162:165], v154 offset:3072
	v_add_u32_e32 v154, s7, v143
	ds_read_b128 v[196:199], v154
	ds_read_b128 v[200:203], v154 offset:1024
	ds_read_b128 v[204:207], v154 offset:2048
	ds_read_b128 v[208:211], v154 offset:3072
	v_lshlrev_b32_e32 v0, s10, v134
	v_lshlrev_b32_e32 v145, s10, v136
	v_lshlrev_b32_e32 v155, s10, v138
	v_lshlrev_b32_e32 v157, s10, v139
	v_add_lshl_u32 v154, v0, v135, 1
	v_add_lshl_u32 v0, v155, v135, 1
	v_add_lshl_u32 v244, v145, v137, 1
	s_add_i32 s20, s87, 0
	v_lshl_add_u64 v[246:247], v[132:133], 0, s[56:57]
	s_add_i32 m0, s20, 0xc000
	ds_read_b128 v[212:215], v144
	ds_read_b128 v[216:219], v144 offset:1024
	ds_read_b128 v[220:223], v144 offset:2048
	ds_read_b128 v[224:227], v144 offset:3072
	ds_read_b128 v[228:231], v144 offset:4096
	ds_read_b128 v[232:235], v144 offset:5120
	ds_read_b128 v[236:239], v144 offset:6144
	ds_read_b128 v[240:243], v144 offset:7168
	global_load_lds_dwordx4 v[246:247], off
	v_lshl_add_u64 v[246:247], v[130:131], 0, s[56:57]
	s_add_i32 m0, s20, 0xe000
	s_nop 0
	global_load_lds_dwordx4 v[246:247], off
	s_waitcnt vmcnt(8)
	s_waitcnt lgkmcnt(0)
	s_barrier
	s_setprio 1
	s_waitcnt lgkmcnt(0)
	v_mfma_f32_16x16x32_bf16 v[126:129], v[146:149], v[212:215], v[126:129]
	v_mfma_f32_16x16x32_bf16 v[122:125], v[158:161], v[212:215], v[122:125]
	v_mfma_f32_16x16x32_bf16 v[110:113], v[146:149], v[220:223], v[110:113]
	v_mfma_f32_16x16x32_bf16 v[106:109], v[158:161], v[220:223], v[106:109]
	s_setprio 0
	s_setprio 1
	v_mfma_f32_16x16x32_bf16 v[94:97], v[146:149], v[228:231], v[94:97]
	v_mfma_f32_16x16x32_bf16 v[90:93], v[158:161], v[228:231], v[90:93]
	v_mfma_f32_16x16x32_bf16 v[78:81], v[146:149], v[236:239], v[78:81]
	v_mfma_f32_16x16x32_bf16 v[74:77], v[158:161], v[236:239], v[74:77]
	s_setprio 0
	s_setprio 1
	v_mfma_f32_16x16x32_bf16 v[126:129], v[150:153], v[216:219], v[126:129]
	v_mfma_f32_16x16x32_bf16 v[122:125], v[162:165], v[216:219], v[122:125]
	v_mfma_f32_16x16x32_bf16 v[110:113], v[150:153], v[224:227], v[110:113]
	v_mfma_f32_16x16x32_bf16 v[106:109], v[162:165], v[224:227], v[106:109]
	s_setprio 0
	s_setprio 1
	v_mfma_f32_16x16x32_bf16 v[94:97], v[150:153], v[232:235], v[94:97]
	v_mfma_f32_16x16x32_bf16 v[90:93], v[162:165], v[232:235], v[90:93]
	v_mfma_f32_16x16x32_bf16 v[78:81], v[150:153], v[240:243], v[78:81]
	v_mfma_f32_16x16x32_bf16 v[74:77], v[162:165], v[240:243], v[74:77]
	s_setprio 0
	s_setprio 1
	v_mfma_f32_16x16x32_bf16 v[118:121], v[196:199], v[212:215], v[118:121]
	v_mfma_f32_16x16x32_bf16 v[114:117], v[204:207], v[212:215], v[114:117]
	v_mfma_f32_16x16x32_bf16 v[102:105], v[196:199], v[220:223], v[102:105]
	v_mfma_f32_16x16x32_bf16 v[98:101], v[204:207], v[220:223], v[98:101]
	s_setprio 0
	s_setprio 1
	v_mfma_f32_16x16x32_bf16 v[86:89], v[196:199], v[228:231], v[86:89]
	v_mfma_f32_16x16x32_bf16 v[82:85], v[204:207], v[228:231], v[82:85]
	v_mfma_f32_16x16x32_bf16 v[70:73], v[196:199], v[236:239], v[70:73]
	v_mfma_f32_16x16x32_bf16 v[66:69], v[204:207], v[236:239], v[66:69]
	s_setprio 0
	s_setprio 1
	v_mfma_f32_16x16x32_bf16 v[118:121], v[200:203], v[216:219], v[118:121]
	v_mfma_f32_16x16x32_bf16 v[114:117], v[208:211], v[216:219], v[114:117]
	v_mfma_f32_16x16x32_bf16 v[102:105], v[200:203], v[224:227], v[102:105]
	v_mfma_f32_16x16x32_bf16 v[98:101], v[208:211], v[224:227], v[98:101]
	s_setprio 0
	s_setprio 1
	v_mfma_f32_16x16x32_bf16 v[86:89], v[200:203], v[232:235], v[86:89]
	v_mfma_f32_16x16x32_bf16 v[82:85], v[208:211], v[232:235], v[82:85]
	v_mfma_f32_16x16x32_bf16 v[70:73], v[200:203], v[240:243], v[70:73]
	v_mfma_f32_16x16x32_bf16 v[66:69], v[208:211], v[240:243], v[66:69]
	s_setprio 0
	s_barrier
	s_add_i32 s10, s6, s87
	s_mov_b32 m0, s10
	ds_read_b128 v[212:215], v144 offset:16384
	ds_read_b128 v[216:219], v144 offset:17408
	ds_read_b128 v[220:223], v144 offset:18432
	ds_read_b128 v[224:227], v144 offset:19456
	ds_read_b128 v[228:231], v144 offset:20480
	ds_read_b128 v[232:235], v144 offset:21504
	ds_read_b128 v[236:239], v144 offset:22528
	ds_read_b128 v[240:243], v144 offset:23552
	global_load_lds_dwordx4 v0, s[62:63]
	s_add_i32 m0, s10, 0x2000
	v_add_lshl_u32 v246, v157, v137, 1
	v_mov_b32_e32 v247, v1
	s_add_u32 s10, s62, s66
	v_lshl_add_u64 v[248:249], s[62:63], 0, v[0:1]
	v_lshl_add_u64 v[250:251], s[62:63], 0, v[246:247]
	global_load_lds_dwordx4 v246, s[62:63]
	s_addc_u32 s11, s63, 0
	s_add_i32 s62, s7, s87
	s_mov_b32 m0, s62
	v_mov_b32_e32 v155, v1
	global_load_lds_dwordx4 v0, s[10:11]
	s_add_i32 m0, s62, 0x2000
	v_mov_b32_e32 v245, v1
	global_load_lds_dwordx4 v246, s[10:11]
	s_mov_b32 m0, s20
	v_lshl_add_u64 v[194:195], s[10:11], 0, v[0:1]
	global_load_lds_dwordx4 v154, s[58:59]
	s_add_i32 m0, s20, 0x2000
	v_lshl_add_u64 v[176:177], s[10:11], 0, v[246:247]
	global_load_lds_dwordx4 v244, s[58:59]
	s_waitcnt vmcnt(8)
	s_waitcnt lgkmcnt(0)
	v_lshl_add_u64 v[246:247], s[58:59], 0, v[154:155]
	v_lshl_add_u64 v[178:179], s[58:59], 0, v[244:245]
	s_barrier
	s_setprio 1
	s_waitcnt lgkmcnt(0)
	v_mfma_f32_16x16x32_bf16 v[62:65], v[146:149], v[212:215], v[62:65]
	v_mfma_f32_16x16x32_bf16 v[58:61], v[158:161], v[212:215], v[58:61]
	v_mfma_f32_16x16x32_bf16 v[46:49], v[146:149], v[220:223], v[46:49]
	v_mfma_f32_16x16x32_bf16 v[42:45], v[158:161], v[220:223], v[42:45]
	s_setprio 0
	s_setprio 1
	v_mfma_f32_16x16x32_bf16 v[30:33], v[146:149], v[228:231], v[30:33]
	v_mfma_f32_16x16x32_bf16 v[26:29], v[158:161], v[228:231], v[26:29]
	v_mfma_f32_16x16x32_bf16 v[14:17], v[146:149], v[236:239], v[14:17]
	v_mfma_f32_16x16x32_bf16 v[10:13], v[158:161], v[236:239], v[10:13]
	s_setprio 0
	s_setprio 1
	v_mfma_f32_16x16x32_bf16 v[62:65], v[150:153], v[216:219], v[62:65]
	v_mfma_f32_16x16x32_bf16 v[58:61], v[162:165], v[216:219], v[58:61]
	v_mfma_f32_16x16x32_bf16 v[46:49], v[150:153], v[224:227], v[46:49]
	v_mfma_f32_16x16x32_bf16 v[42:45], v[162:165], v[224:227], v[42:45]
	s_setprio 0
	s_setprio 1
	v_mfma_f32_16x16x32_bf16 v[30:33], v[150:153], v[232:235], v[30:33]
	v_mfma_f32_16x16x32_bf16 v[26:29], v[162:165], v[232:235], v[26:29]
	v_mfma_f32_16x16x32_bf16 v[14:17], v[150:153], v[240:243], v[14:17]
	v_mfma_f32_16x16x32_bf16 v[10:13], v[162:165], v[240:243], v[10:13]
	s_setprio 0
	s_setprio 1
	v_mfma_f32_16x16x32_bf16 v[54:57], v[196:199], v[212:215], v[54:57]
	v_mfma_f32_16x16x32_bf16 v[50:53], v[204:207], v[212:215], v[50:53]
	v_mfma_f32_16x16x32_bf16 v[38:41], v[196:199], v[220:223], v[38:41]
	v_mfma_f32_16x16x32_bf16 v[34:37], v[204:207], v[220:223], v[34:37]
	s_setprio 0
	s_setprio 1
	v_mfma_f32_16x16x32_bf16 v[22:25], v[196:199], v[228:231], v[22:25]
	v_mfma_f32_16x16x32_bf16 v[18:21], v[204:207], v[228:231], v[18:21]
	v_mfma_f32_16x16x32_bf16 v[6:9], v[196:199], v[236:239], v[6:9]
	v_mfma_f32_16x16x32_bf16 v[2:5], v[204:207], v[236:239], v[2:5]
	s_setprio 0
	s_setprio 1
	v_mfma_f32_16x16x32_bf16 v[54:57], v[200:203], v[216:219], v[54:57]
	v_mfma_f32_16x16x32_bf16 v[50:53], v[208:211], v[216:219], v[50:53]
	v_mfma_f32_16x16x32_bf16 v[38:41], v[200:203], v[224:227], v[38:41]
	v_mfma_f32_16x16x32_bf16 v[34:37], v[208:211], v[224:227], v[34:37]
	s_setprio 0
	s_setprio 1
	v_mfma_f32_16x16x32_bf16 v[22:25], v[200:203], v[232:235], v[22:25]
	v_mfma_f32_16x16x32_bf16 v[18:21], v[208:211], v[232:235], v[18:21]
	v_mfma_f32_16x16x32_bf16 v[6:9], v[200:203], v[240:243], v[6:9]
	v_mfma_f32_16x16x32_bf16 v[2:5], v[208:211], v[240:243], v[2:5]
	s_setprio 0
	s_barrier
	s_add_i32 s10, 0, 0x18000
	v_add_u32_e32 v0, s10, v143
	s_add_i32 s11, 0, 0x1c000
	ds_read_b128 v[146:149], v0
	ds_read_b128 v[150:153], v0 offset:1024
	ds_read_b128 v[158:161], v0 offset:2048
	ds_read_b128 v[162:165], v0 offset:3072
	v_add_u32_e32 v0, s11, v143
	ds_read_b128 v[196:199], v0
	ds_read_b128 v[200:203], v0 offset:1024
	ds_read_b128 v[204:207], v0 offset:2048
	ds_read_b128 v[208:211], v0 offset:3072
	s_add_u32 s58, s58, s66
	s_addc_u32 s59, s59, 0
	s_add_i32 m0, s20, 0x4000
	ds_read_b128 v[212:215], v144 offset:32768
	ds_read_b128 v[216:219], v144 offset:33792
	ds_read_b128 v[220:223], v144 offset:34816
	ds_read_b128 v[224:227], v144 offset:35840
	ds_read_b128 v[228:231], v144 offset:36864
	ds_read_b128 v[232:235], v144 offset:37888
	ds_read_b128 v[236:239], v144 offset:38912
	ds_read_b128 v[240:243], v144 offset:39936
	global_load_lds_dwordx4 v154, s[58:59]
	s_add_i32 m0, s20, 0x6000
	s_nop 0
	global_load_lds_dwordx4 v244, s[58:59]
	s_waitcnt vmcnt(8)
	s_waitcnt lgkmcnt(0)
	s_barrier
	s_setprio 1
	s_waitcnt lgkmcnt(0)
	v_mfma_f32_16x16x32_bf16 v[126:129], v[146:149], v[212:215], v[126:129]
	v_mfma_f32_16x16x32_bf16 v[122:125], v[158:161], v[212:215], v[122:125]
	v_mfma_f32_16x16x32_bf16 v[110:113], v[146:149], v[220:223], v[110:113]
	v_mfma_f32_16x16x32_bf16 v[106:109], v[158:161], v[220:223], v[106:109]
	s_setprio 0
	s_setprio 1
	v_mfma_f32_16x16x32_bf16 v[94:97], v[146:149], v[228:231], v[94:97]
	v_mfma_f32_16x16x32_bf16 v[90:93], v[158:161], v[228:231], v[90:93]
	v_mfma_f32_16x16x32_bf16 v[78:81], v[146:149], v[236:239], v[78:81]
	v_mfma_f32_16x16x32_bf16 v[74:77], v[158:161], v[236:239], v[74:77]
	s_setprio 0
	s_setprio 1
	v_mfma_f32_16x16x32_bf16 v[126:129], v[150:153], v[216:219], v[126:129]
	v_mfma_f32_16x16x32_bf16 v[122:125], v[162:165], v[216:219], v[122:125]
	v_mfma_f32_16x16x32_bf16 v[110:113], v[150:153], v[224:227], v[110:113]
	v_mfma_f32_16x16x32_bf16 v[106:109], v[162:165], v[224:227], v[106:109]
	s_setprio 0
	s_setprio 1
	v_mfma_f32_16x16x32_bf16 v[94:97], v[150:153], v[232:235], v[94:97]
	v_mfma_f32_16x16x32_bf16 v[90:93], v[162:165], v[232:235], v[90:93]
	v_mfma_f32_16x16x32_bf16 v[78:81], v[150:153], v[240:243], v[78:81]
	v_mfma_f32_16x16x32_bf16 v[74:77], v[162:165], v[240:243], v[74:77]
	s_setprio 0
	s_setprio 1
	v_mfma_f32_16x16x32_bf16 v[118:121], v[196:199], v[212:215], v[118:121]
	v_mfma_f32_16x16x32_bf16 v[114:117], v[204:207], v[212:215], v[114:117]
	v_mfma_f32_16x16x32_bf16 v[102:105], v[196:199], v[220:223], v[102:105]
	v_mfma_f32_16x16x32_bf16 v[98:101], v[204:207], v[220:223], v[98:101]
	s_setprio 0
	s_setprio 1
	v_mfma_f32_16x16x32_bf16 v[86:89], v[196:199], v[228:231], v[86:89]
	v_mfma_f32_16x16x32_bf16 v[82:85], v[204:207], v[228:231], v[82:85]
	v_mfma_f32_16x16x32_bf16 v[70:73], v[196:199], v[236:239], v[70:73]
	v_mfma_f32_16x16x32_bf16 v[66:69], v[204:207], v[236:239], v[66:69]
	s_setprio 0
	s_setprio 1
	v_mfma_f32_16x16x32_bf16 v[118:121], v[200:203], v[216:219], v[118:121]
	v_mfma_f32_16x16x32_bf16 v[114:117], v[208:211], v[216:219], v[114:117]
	v_mfma_f32_16x16x32_bf16 v[102:105], v[200:203], v[224:227], v[102:105]
	v_mfma_f32_16x16x32_bf16 v[98:101], v[208:211], v[224:227], v[98:101]
	s_setprio 0
	s_setprio 1
	v_mfma_f32_16x16x32_bf16 v[86:89], v[200:203], v[232:235], v[86:89]
	v_mfma_f32_16x16x32_bf16 v[82:85], v[208:211], v[232:235], v[82:85]
	v_mfma_f32_16x16x32_bf16 v[70:73], v[200:203], v[240:243], v[70:73]
	v_mfma_f32_16x16x32_bf16 v[66:69], v[208:211], v[240:243], v[66:69]
	s_setprio 0
	s_barrier
	s_add_i32 s58, s10, s87
	v_lshl_add_u64 v[154:155], v[248:249], 0, s[24:25]
	s_mov_b32 m0, s58
	ds_read_b128 v[212:215], v144 offset:49152
	ds_read_b128 v[216:219], v144 offset:50176
	ds_read_b128 v[220:223], v144 offset:51200
	ds_read_b128 v[224:227], v144 offset:52224
	ds_read_b128 v[228:231], v144 offset:53248
	ds_read_b128 v[232:235], v144 offset:54272
	ds_read_b128 v[236:239], v144 offset:55296
	ds_read_b128 v[240:243], v144 offset:56320
	global_load_lds_dwordx4 v[154:155], off
	v_lshl_add_u64 v[154:155], v[250:251], 0, s[24:25]
	s_add_i32 m0, s58, 0x2000
	s_add_i32 s58, s11, s87
	global_load_lds_dwordx4 v[154:155], off
	v_lshl_add_u64 v[154:155], v[194:195], 0, s[24:25]
	s_mov_b32 m0, s58
	s_nop 0
	global_load_lds_dwordx4 v[154:155], off
	v_lshl_add_u64 v[154:155], v[176:177], 0, s[24:25]
	s_add_i32 m0, s58, 0x2000
	s_nop 0
	global_load_lds_dwordx4 v[154:155], off
	v_lshl_add_u64 v[154:155], v[246:247], 0, s[24:25]
	s_add_i32 m0, s20, 0x8000
	s_nop 0
	global_load_lds_dwordx4 v[154:155], off
	v_lshl_add_u64 v[154:155], v[178:179], 0, s[24:25]
	s_add_i32 m0, s20, 0xa000
	s_nop 0
	global_load_lds_dwordx4 v[154:155], off
	s_waitcnt vmcnt(8)
	s_waitcnt lgkmcnt(0)
	s_barrier
	s_setprio 1
	s_waitcnt lgkmcnt(0)
	v_mfma_f32_16x16x32_bf16 v[62:65], v[146:149], v[212:215], v[62:65]
	v_mfma_f32_16x16x32_bf16 v[58:61], v[158:161], v[212:215], v[58:61]
	v_mfma_f32_16x16x32_bf16 v[46:49], v[146:149], v[220:223], v[46:49]
	v_mfma_f32_16x16x32_bf16 v[42:45], v[158:161], v[220:223], v[42:45]
	s_setprio 0
	s_setprio 1
	v_mfma_f32_16x16x32_bf16 v[30:33], v[146:149], v[228:231], v[30:33]
	v_mfma_f32_16x16x32_bf16 v[26:29], v[158:161], v[228:231], v[26:29]
	v_mfma_f32_16x16x32_bf16 v[14:17], v[146:149], v[236:239], v[14:17]
	v_mfma_f32_16x16x32_bf16 v[10:13], v[158:161], v[236:239], v[10:13]
	s_setprio 0
	s_setprio 1
	v_mfma_f32_16x16x32_bf16 v[62:65], v[150:153], v[216:219], v[62:65]
	v_mfma_f32_16x16x32_bf16 v[58:61], v[162:165], v[216:219], v[58:61]
	v_mfma_f32_16x16x32_bf16 v[46:49], v[150:153], v[224:227], v[46:49]
	v_mfma_f32_16x16x32_bf16 v[42:45], v[162:165], v[224:227], v[42:45]
	s_setprio 0
	s_setprio 1
	v_mfma_f32_16x16x32_bf16 v[30:33], v[150:153], v[232:235], v[30:33]
	v_mfma_f32_16x16x32_bf16 v[26:29], v[162:165], v[232:235], v[26:29]
	v_mfma_f32_16x16x32_bf16 v[14:17], v[150:153], v[240:243], v[14:17]
	v_mfma_f32_16x16x32_bf16 v[10:13], v[162:165], v[240:243], v[10:13]
	s_setprio 0
	s_setprio 1
	v_mfma_f32_16x16x32_bf16 v[54:57], v[196:199], v[212:215], v[54:57]
	v_mfma_f32_16x16x32_bf16 v[50:53], v[204:207], v[212:215], v[50:53]
	v_mfma_f32_16x16x32_bf16 v[38:41], v[196:199], v[220:223], v[38:41]
	v_mfma_f32_16x16x32_bf16 v[34:37], v[204:207], v[220:223], v[34:37]
	s_setprio 0
	s_setprio 1
	v_mfma_f32_16x16x32_bf16 v[22:25], v[196:199], v[228:231], v[22:25]
	v_mfma_f32_16x16x32_bf16 v[18:21], v[204:207], v[228:231], v[18:21]
	v_mfma_f32_16x16x32_bf16 v[6:9], v[196:199], v[236:239], v[6:9]
	v_mfma_f32_16x16x32_bf16 v[2:5], v[204:207], v[236:239], v[2:5]
	s_setprio 0
	s_setprio 1
	v_mfma_f32_16x16x32_bf16 v[54:57], v[200:203], v[216:219], v[54:57]
	v_mfma_f32_16x16x32_bf16 v[50:53], v[208:211], v[216:219], v[50:53]
	v_mfma_f32_16x16x32_bf16 v[38:41], v[200:203], v[224:227], v[38:41]
	v_mfma_f32_16x16x32_bf16 v[34:37], v[208:211], v[224:227], v[34:37]
	s_setprio 0
	s_setprio 1
	v_mfma_f32_16x16x32_bf16 v[22:25], v[200:203], v[232:235], v[22:25]
	v_mfma_f32_16x16x32_bf16 v[18:21], v[208:211], v[232:235], v[18:21]
	v_mfma_f32_16x16x32_bf16 v[6:9], v[200:203], v[240:243], v[6:9]
	v_mfma_f32_16x16x32_bf16 v[2:5], v[208:211], v[240:243], v[2:5]
	s_setprio 0
	s_barrier
	s_add_i32 vcc_hi, vcc_hi, 2
	s_add_u32 s56, s56, 0x100
	s_addc_u32 s57, s57, 0
	s_cmp_lt_u32 vcc_hi, 14
	s_cbranch_scc1 .LBB0_336
	v_mul_f32_e32 v0, 0xbfb8aa3b, v126
	v_exp_f32_e32 v0, v0
	v_mul_f32_e32 v126, 0xbfb8aa3b, v127
	v_exp_f32_e32 v132, v126
	v_mul_f32_e32 v128, 0xbfb8aa3b, v128
	v_exp_f32_e32 v128, v128
	v_lshl_add_u32 v130, s96, 16, v142
	v_mul_f32_e32 v129, 0xbfb8aa3b, v129
	v_add_f32_e32 v0, 1.0, v0
	v_ashrrev_i32_e32 v131, 31, v130
	v_exp_f32_e32 v129, v129
	v_rcp_f32_e32 v0, v0
	v_lshl_add_u64 v[126:127], s[0:1], 0, v[130:131]
	v_add_f32_e32 v130, 1.0, v132
	v_rcp_f32_e32 v130, v130
	v_add_f32_e32 v128, 1.0, v128
	v_rcp_f32_e32 v128, v128
	v_add_f32_e32 v129, 1.0, v129
	v_fma_f32 v0, v0, s21, 0.5
	v_rcp_f32_e32 v129, v129
	v_max_f32_e32 v0, 1.0, v0
	v_fma_f32 v130, v130, s21, 0.5
	v_mul_f32_e32 v122, 0xbfb8aa3b, v122
	v_cvt_pk_u8_f32 v0, v0, 0, 0
	v_max_f32_e32 v130, 1.0, v130
	v_fma_f32 v128, v128, s21, 0.5
	v_exp_f32_e32 v122, v122
	v_mul_f32_e32 v123, 0xbfb8aa3b, v123
	v_cvt_pk_u8_f32 v0, v130, 1, v0
	v_max_f32_e32 v128, 1.0, v128
	v_exp_f32_e32 v123, v123
	v_cvt_pk_u8_f32 v0, v128, 2, v0
	v_fma_f32 v128, v129, s21, 0.5
	v_max_f32_e32 v128, 1.0, v128
	v_cvt_pk_u8_f32 v0, v128, 3, v0
	v_add_f32_e32 v122, 1.0, v122
	v_rcp_f32_e32 v122, v122
	global_store_dword v[126:127], v0, off
	v_add_f32_e32 v0, 1.0, v123
	v_rcp_f32_e32 v0, v0
	v_mul_f32_e32 v123, 0xbfb8aa3b, v124
	v_exp_f32_e32 v123, v123
	v_mul_f32_e32 v124, 0xbfb8aa3b, v125
	v_exp_f32_e32 v124, v124
	v_fma_f32 v122, v122, s21, 0.5
	v_max_f32_e32 v122, 1.0, v122
	v_fma_f32 v0, v0, s21, 0.5
	v_cvt_pk_u8_f32 v122, v122, 0, 0
	v_max_f32_e32 v0, 1.0, v0
	v_add_f32_e32 v123, 1.0, v123
	v_rcp_f32_e32 v123, v123
	v_cvt_pk_u8_f32 v0, v0, 1, v122
	v_add_f32_e32 v122, 1.0, v124
	v_rcp_f32_e32 v122, v122
	v_mul_f32_e32 v118, 0xbfb8aa3b, v118
	v_exp_f32_e32 v118, v118
	v_mul_f32_e32 v119, 0xbfb8aa3b, v119
	v_fma_f32 v123, v123, s21, 0.5
	v_exp_f32_e32 v119, v119
	v_max_f32_e32 v123, 1.0, v123
	v_fma_f32 v122, v122, s21, 0.5
	v_cvt_pk_u8_f32 v0, v123, 2, v0
	v_max_f32_e32 v122, 1.0, v122
	v_cvt_pk_u8_f32 v0, v122, 3, v0
	v_add_f32_e32 v118, 1.0, v118
	v_rcp_f32_e32 v118, v118
	global_store_dword v[126:127], v0, off offset:256
	v_add_f32_e32 v0, 1.0, v119
	v_rcp_f32_e32 v0, v0
	v_mul_f32_e32 v119, 0xbfb8aa3b, v120
	v_exp_f32_e32 v119, v119
	v_mul_f32_e32 v120, 0xbfb8aa3b, v121
	v_exp_f32_e32 v120, v120
	v_fma_f32 v118, v118, s21, 0.5
	v_max_f32_e32 v118, 1.0, v118
	v_fma_f32 v0, v0, s21, 0.5
	v_cvt_pk_u8_f32 v118, v118, 0, 0
	v_max_f32_e32 v0, 1.0, v0
	v_add_f32_e32 v119, 1.0, v119
	v_rcp_f32_e32 v119, v119
	v_cvt_pk_u8_f32 v0, v0, 1, v118
	v_add_f32_e32 v118, 1.0, v120
	v_rcp_f32_e32 v118, v118
	v_mul_f32_e32 v114, 0xbfb8aa3b, v114
	v_exp_f32_e32 v114, v114
	v_mul_f32_e32 v115, 0xbfb8aa3b, v115
	v_fma_f32 v119, v119, s21, 0.5
	v_exp_f32_e32 v115, v115
	v_max_f32_e32 v119, 1.0, v119
	v_fma_f32 v118, v118, s21, 0.5
	v_cvt_pk_u8_f32 v0, v119, 2, v0
	v_max_f32_e32 v118, 1.0, v118
	v_cvt_pk_u8_f32 v0, v118, 3, v0
	v_add_f32_e32 v114, 1.0, v114
	v_rcp_f32_e32 v114, v114
	global_store_dword v[126:127], v0, off offset:512
	v_add_f32_e32 v0, 1.0, v115
	v_rcp_f32_e32 v0, v0
	v_mul_f32_e32 v115, 0xbfb8aa3b, v116
	v_exp_f32_e32 v115, v115
	v_mul_f32_e32 v116, 0xbfb8aa3b, v117
	v_exp_f32_e32 v116, v116
	v_fma_f32 v114, v114, s21, 0.5
	v_max_f32_e32 v114, 1.0, v114
	v_fma_f32 v0, v0, s21, 0.5
	v_cvt_pk_u8_f32 v114, v114, 0, 0
	v_max_f32_e32 v0, 1.0, v0
	v_add_f32_e32 v115, 1.0, v115
	v_rcp_f32_e32 v115, v115
	v_cvt_pk_u8_f32 v0, v0, 1, v114
	v_add_f32_e32 v114, 1.0, v116
	v_rcp_f32_e32 v114, v114
	v_mul_f32_e32 v110, 0xbfb8aa3b, v110
	v_exp_f32_e32 v110, v110
	v_mul_f32_e32 v111, 0xbfb8aa3b, v111
	v_fma_f32 v115, v115, s21, 0.5
	v_exp_f32_e32 v111, v111
	v_max_f32_e32 v115, 1.0, v115
	v_fma_f32 v114, v114, s21, 0.5
	v_cvt_pk_u8_f32 v0, v115, 2, v0
	v_max_f32_e32 v114, 1.0, v114
	v_cvt_pk_u8_f32 v0, v114, 3, v0
	v_add_f32_e32 v110, 1.0, v110
	v_rcp_f32_e32 v110, v110
	global_store_dword v[126:127], v0, off offset:768
	v_add_f32_e32 v0, 1.0, v111
	v_rcp_f32_e32 v0, v0
	v_mul_f32_e32 v111, 0xbfb8aa3b, v112
	v_exp_f32_e32 v111, v111
	v_mul_f32_e32 v112, 0xbfb8aa3b, v113
	v_exp_f32_e32 v112, v112
	v_fma_f32 v110, v110, s21, 0.5
	v_max_f32_e32 v110, 1.0, v110
	v_fma_f32 v0, v0, s21, 0.5
	v_cvt_pk_u8_f32 v110, v110, 0, 0
	v_max_f32_e32 v0, 1.0, v0
	v_add_f32_e32 v111, 1.0, v111
	v_rcp_f32_e32 v111, v111
	v_cvt_pk_u8_f32 v0, v0, 1, v110
	v_add_f32_e32 v110, 1.0, v112
	v_rcp_f32_e32 v110, v110
	v_mul_f32_e32 v106, 0xbfb8aa3b, v106
	v_exp_f32_e32 v106, v106
	v_mul_f32_e32 v107, 0xbfb8aa3b, v107
	v_fma_f32 v111, v111, s21, 0.5
	v_exp_f32_e32 v107, v107
	v_max_f32_e32 v111, 1.0, v111
	v_fma_f32 v110, v110, s21, 0.5
	v_cvt_pk_u8_f32 v0, v111, 2, v0
	v_max_f32_e32 v110, 1.0, v110
	v_cvt_pk_u8_f32 v0, v110, 3, v0
	v_add_f32_e32 v106, 1.0, v106
	v_rcp_f32_e32 v106, v106
	global_store_dword v[126:127], v0, off offset:1024
	v_add_f32_e32 v0, 1.0, v107
	v_rcp_f32_e32 v0, v0
	v_mul_f32_e32 v107, 0xbfb8aa3b, v108
	v_exp_f32_e32 v107, v107
	v_mul_f32_e32 v108, 0xbfb8aa3b, v109
	v_exp_f32_e32 v108, v108
	v_fma_f32 v106, v106, s21, 0.5
	v_max_f32_e32 v106, 1.0, v106
	v_fma_f32 v0, v0, s21, 0.5
	v_cvt_pk_u8_f32 v106, v106, 0, 0
	v_max_f32_e32 v0, 1.0, v0
	v_add_f32_e32 v107, 1.0, v107
	v_rcp_f32_e32 v107, v107
	v_cvt_pk_u8_f32 v0, v0, 1, v106
	v_add_f32_e32 v106, 1.0, v108
	v_rcp_f32_e32 v106, v106
	v_mul_f32_e32 v102, 0xbfb8aa3b, v102
	v_exp_f32_e32 v102, v102
	v_mul_f32_e32 v103, 0xbfb8aa3b, v103
	v_fma_f32 v107, v107, s21, 0.5
	v_exp_f32_e32 v103, v103
	v_max_f32_e32 v107, 1.0, v107
	v_fma_f32 v106, v106, s21, 0.5
	v_cvt_pk_u8_f32 v0, v107, 2, v0
	v_max_f32_e32 v106, 1.0, v106
	v_cvt_pk_u8_f32 v0, v106, 3, v0
	v_add_f32_e32 v102, 1.0, v102
	v_rcp_f32_e32 v102, v102
	global_store_dword v[126:127], v0, off offset:1280
	v_add_f32_e32 v0, 1.0, v103
	v_rcp_f32_e32 v0, v0
	v_mul_f32_e32 v103, 0xbfb8aa3b, v104
	v_exp_f32_e32 v103, v103
	v_mul_f32_e32 v104, 0xbfb8aa3b, v105
	v_exp_f32_e32 v104, v104
	v_fma_f32 v102, v102, s21, 0.5
	v_max_f32_e32 v102, 1.0, v102
	v_fma_f32 v0, v0, s21, 0.5
	v_cvt_pk_u8_f32 v102, v102, 0, 0
	v_max_f32_e32 v0, 1.0, v0
	v_add_f32_e32 v103, 1.0, v103
	v_rcp_f32_e32 v103, v103
	v_cvt_pk_u8_f32 v0, v0, 1, v102
	v_add_f32_e32 v102, 1.0, v104
	v_rcp_f32_e32 v102, v102
	v_mul_f32_e32 v98, 0xbfb8aa3b, v98
	v_exp_f32_e32 v98, v98
	v_mul_f32_e32 v99, 0xbfb8aa3b, v99
	v_fma_f32 v103, v103, s21, 0.5
	v_exp_f32_e32 v99, v99
	v_max_f32_e32 v103, 1.0, v103
	v_fma_f32 v102, v102, s21, 0.5
	v_cvt_pk_u8_f32 v0, v103, 2, v0
	v_max_f32_e32 v102, 1.0, v102
	v_cvt_pk_u8_f32 v0, v102, 3, v0
	v_add_f32_e32 v98, 1.0, v98
	v_rcp_f32_e32 v98, v98
	global_store_dword v[126:127], v0, off offset:1536
	v_add_f32_e32 v0, 1.0, v99
	v_rcp_f32_e32 v0, v0
	v_mul_f32_e32 v99, 0xbfb8aa3b, v100
	v_exp_f32_e32 v99, v99
	v_mul_f32_e32 v100, 0xbfb8aa3b, v101
	v_exp_f32_e32 v100, v100
	v_fma_f32 v98, v98, s21, 0.5
	v_max_f32_e32 v98, 1.0, v98
	v_fma_f32 v0, v0, s21, 0.5
	v_cvt_pk_u8_f32 v98, v98, 0, 0
	v_max_f32_e32 v0, 1.0, v0
	v_add_f32_e32 v99, 1.0, v99
	v_rcp_f32_e32 v99, v99
	v_cvt_pk_u8_f32 v0, v0, 1, v98
	v_add_f32_e32 v98, 1.0, v100
	v_rcp_f32_e32 v98, v98
	v_mul_f32_e32 v94, 0xbfb8aa3b, v94
	v_exp_f32_e32 v94, v94
	v_mul_f32_e32 v95, 0xbfb8aa3b, v95
	v_fma_f32 v99, v99, s21, 0.5
	v_exp_f32_e32 v95, v95
	v_max_f32_e32 v99, 1.0, v99
	v_fma_f32 v98, v98, s21, 0.5
	v_cvt_pk_u8_f32 v0, v99, 2, v0
	v_max_f32_e32 v98, 1.0, v98
	v_cvt_pk_u8_f32 v0, v98, 3, v0
	v_add_f32_e32 v94, 1.0, v94
	v_rcp_f32_e32 v94, v94
	global_store_dword v[126:127], v0, off offset:1792
	v_add_f32_e32 v0, 1.0, v95
	v_rcp_f32_e32 v0, v0
	v_mul_f32_e32 v95, 0xbfb8aa3b, v96
	v_exp_f32_e32 v95, v95
	v_mul_f32_e32 v96, 0xbfb8aa3b, v97
	v_exp_f32_e32 v96, v96
	v_fma_f32 v94, v94, s21, 0.5
	v_max_f32_e32 v94, 1.0, v94
	v_fma_f32 v0, v0, s21, 0.5
	v_cvt_pk_u8_f32 v94, v94, 0, 0
	v_max_f32_e32 v0, 1.0, v0
	v_add_f32_e32 v95, 1.0, v95
	v_rcp_f32_e32 v95, v95
	v_cvt_pk_u8_f32 v0, v0, 1, v94
	v_add_f32_e32 v94, 1.0, v96
	v_rcp_f32_e32 v94, v94
	v_mul_f32_e32 v90, 0xbfb8aa3b, v90
	v_exp_f32_e32 v90, v90
	v_mul_f32_e32 v91, 0xbfb8aa3b, v91
	v_fma_f32 v95, v95, s21, 0.5
	v_exp_f32_e32 v91, v91
	v_max_f32_e32 v95, 1.0, v95
	v_fma_f32 v94, v94, s21, 0.5
	v_cvt_pk_u8_f32 v0, v95, 2, v0
	v_max_f32_e32 v94, 1.0, v94
	v_cvt_pk_u8_f32 v0, v94, 3, v0
	v_add_f32_e32 v90, 1.0, v90
	v_rcp_f32_e32 v90, v90
	global_store_dword v[126:127], v0, off offset:2048
	v_add_f32_e32 v0, 1.0, v91
	v_rcp_f32_e32 v0, v0
	v_mul_f32_e32 v91, 0xbfb8aa3b, v92
	v_exp_f32_e32 v91, v91
	v_mul_f32_e32 v92, 0xbfb8aa3b, v93
	v_exp_f32_e32 v92, v92
	v_fma_f32 v90, v90, s21, 0.5
	v_max_f32_e32 v90, 1.0, v90
	v_fma_f32 v0, v0, s21, 0.5
	v_cvt_pk_u8_f32 v90, v90, 0, 0
	v_max_f32_e32 v0, 1.0, v0
	v_add_f32_e32 v91, 1.0, v91
	v_rcp_f32_e32 v91, v91
	v_cvt_pk_u8_f32 v0, v0, 1, v90
	v_add_f32_e32 v90, 1.0, v92
	v_rcp_f32_e32 v90, v90
	v_mul_f32_e32 v86, 0xbfb8aa3b, v86
	v_exp_f32_e32 v86, v86
	v_mul_f32_e32 v87, 0xbfb8aa3b, v87
	v_fma_f32 v91, v91, s21, 0.5
	v_exp_f32_e32 v87, v87
	v_max_f32_e32 v91, 1.0, v91
	v_fma_f32 v90, v90, s21, 0.5
	v_cvt_pk_u8_f32 v0, v91, 2, v0
	v_max_f32_e32 v90, 1.0, v90
	v_cvt_pk_u8_f32 v0, v90, 3, v0
	v_add_f32_e32 v86, 1.0, v86
	v_rcp_f32_e32 v86, v86
	global_store_dword v[126:127], v0, off offset:2304
	v_add_f32_e32 v0, 1.0, v87
	v_rcp_f32_e32 v0, v0
	v_mul_f32_e32 v87, 0xbfb8aa3b, v88
	v_exp_f32_e32 v87, v87
	v_mul_f32_e32 v88, 0xbfb8aa3b, v89
	v_exp_f32_e32 v88, v88
	v_fma_f32 v86, v86, s21, 0.5
	v_max_f32_e32 v86, 1.0, v86
	v_fma_f32 v0, v0, s21, 0.5
	v_cvt_pk_u8_f32 v86, v86, 0, 0
	v_max_f32_e32 v0, 1.0, v0
	v_add_f32_e32 v87, 1.0, v87
	v_rcp_f32_e32 v87, v87
	v_cvt_pk_u8_f32 v0, v0, 1, v86
	v_add_f32_e32 v86, 1.0, v88
	v_rcp_f32_e32 v86, v86
	v_mul_f32_e32 v82, 0xbfb8aa3b, v82
	v_exp_f32_e32 v82, v82
	v_mul_f32_e32 v83, 0xbfb8aa3b, v83
	v_fma_f32 v87, v87, s21, 0.5
	v_exp_f32_e32 v83, v83
	v_max_f32_e32 v87, 1.0, v87
	v_fma_f32 v86, v86, s21, 0.5
	v_cvt_pk_u8_f32 v0, v87, 2, v0
	v_max_f32_e32 v86, 1.0, v86
	v_cvt_pk_u8_f32 v0, v86, 3, v0
	v_add_f32_e32 v82, 1.0, v82
	v_rcp_f32_e32 v82, v82
	global_store_dword v[126:127], v0, off offset:2560
	v_add_f32_e32 v0, 1.0, v83
	v_rcp_f32_e32 v0, v0
	v_mul_f32_e32 v83, 0xbfb8aa3b, v84
	v_exp_f32_e32 v83, v83
	v_mul_f32_e32 v84, 0xbfb8aa3b, v85
	v_exp_f32_e32 v84, v84
	v_fma_f32 v82, v82, s21, 0.5
	v_max_f32_e32 v82, 1.0, v82
	v_fma_f32 v0, v0, s21, 0.5
	v_cvt_pk_u8_f32 v82, v82, 0, 0
	v_max_f32_e32 v0, 1.0, v0
	v_add_f32_e32 v83, 1.0, v83
	v_rcp_f32_e32 v83, v83
	v_cvt_pk_u8_f32 v0, v0, 1, v82
	v_add_f32_e32 v82, 1.0, v84
	v_rcp_f32_e32 v82, v82
	v_mul_f32_e32 v78, 0xbfb8aa3b, v78
	v_exp_f32_e32 v78, v78
	v_mul_f32_e32 v79, 0xbfb8aa3b, v79
	v_fma_f32 v83, v83, s21, 0.5
	v_exp_f32_e32 v79, v79
	v_max_f32_e32 v83, 1.0, v83
	v_fma_f32 v82, v82, s21, 0.5
	v_cvt_pk_u8_f32 v0, v83, 2, v0
	v_max_f32_e32 v82, 1.0, v82
	v_cvt_pk_u8_f32 v0, v82, 3, v0
	v_add_f32_e32 v78, 1.0, v78
	v_rcp_f32_e32 v78, v78
	global_store_dword v[126:127], v0, off offset:2816
	v_add_f32_e32 v0, 1.0, v79
	v_rcp_f32_e32 v0, v0
	v_mul_f32_e32 v79, 0xbfb8aa3b, v80
	v_exp_f32_e32 v79, v79
	v_mul_f32_e32 v80, 0xbfb8aa3b, v81
	v_exp_f32_e32 v80, v80
	v_fma_f32 v78, v78, s21, 0.5
	v_max_f32_e32 v78, 1.0, v78
	v_fma_f32 v0, v0, s21, 0.5
	v_cvt_pk_u8_f32 v78, v78, 0, 0
	v_max_f32_e32 v0, 1.0, v0
	v_add_f32_e32 v79, 1.0, v79
	v_rcp_f32_e32 v79, v79
	v_cvt_pk_u8_f32 v0, v0, 1, v78
	v_add_f32_e32 v78, 1.0, v80
	v_rcp_f32_e32 v78, v78
	v_mul_f32_e32 v74, 0xbfb8aa3b, v74
	v_exp_f32_e32 v74, v74
	v_mul_f32_e32 v75, 0xbfb8aa3b, v75
	v_fma_f32 v79, v79, s21, 0.5
	v_exp_f32_e32 v75, v75
	v_max_f32_e32 v79, 1.0, v79
	v_fma_f32 v78, v78, s21, 0.5
	v_cvt_pk_u8_f32 v0, v79, 2, v0
	v_max_f32_e32 v78, 1.0, v78
	v_cvt_pk_u8_f32 v0, v78, 3, v0
	v_add_f32_e32 v74, 1.0, v74
	v_rcp_f32_e32 v74, v74
	global_store_dword v[126:127], v0, off offset:3072
	v_add_f32_e32 v0, 1.0, v75
	v_rcp_f32_e32 v0, v0
	v_mul_f32_e32 v75, 0xbfb8aa3b, v76
	v_exp_f32_e32 v75, v75
	v_mul_f32_e32 v76, 0xbfb8aa3b, v77
	v_exp_f32_e32 v76, v76
	v_fma_f32 v74, v74, s21, 0.5
	v_max_f32_e32 v74, 1.0, v74
	v_fma_f32 v0, v0, s21, 0.5
	v_cvt_pk_u8_f32 v74, v74, 0, 0
	v_max_f32_e32 v0, 1.0, v0
	v_add_f32_e32 v75, 1.0, v75
	v_rcp_f32_e32 v75, v75
	v_cvt_pk_u8_f32 v0, v0, 1, v74
	v_add_f32_e32 v74, 1.0, v76
	v_rcp_f32_e32 v74, v74
	v_mul_f32_e32 v70, 0xbfb8aa3b, v70
	v_exp_f32_e32 v70, v70
	v_mul_f32_e32 v71, 0xbfb8aa3b, v71
	v_fma_f32 v75, v75, s21, 0.5
	v_exp_f32_e32 v71, v71
	v_max_f32_e32 v75, 1.0, v75
	v_fma_f32 v74, v74, s21, 0.5
	v_cvt_pk_u8_f32 v0, v75, 2, v0
	v_max_f32_e32 v74, 1.0, v74
	v_cvt_pk_u8_f32 v0, v74, 3, v0
	v_add_f32_e32 v70, 1.0, v70
	v_rcp_f32_e32 v70, v70
	global_store_dword v[126:127], v0, off offset:3328
	v_add_f32_e32 v0, 1.0, v71
	v_rcp_f32_e32 v0, v0
	v_mul_f32_e32 v71, 0xbfb8aa3b, v72
	v_exp_f32_e32 v71, v71
	v_mul_f32_e32 v72, 0xbfb8aa3b, v73
	v_exp_f32_e32 v72, v72
	v_fma_f32 v70, v70, s21, 0.5
	v_max_f32_e32 v70, 1.0, v70
	v_fma_f32 v0, v0, s21, 0.5
	v_cvt_pk_u8_f32 v70, v70, 0, 0
	v_max_f32_e32 v0, 1.0, v0
	v_add_f32_e32 v71, 1.0, v71
	v_rcp_f32_e32 v71, v71
	v_cvt_pk_u8_f32 v0, v0, 1, v70
	v_add_f32_e32 v70, 1.0, v72
	v_rcp_f32_e32 v70, v70
	v_mul_f32_e32 v66, 0xbfb8aa3b, v66
	v_exp_f32_e32 v66, v66
	v_mul_f32_e32 v67, 0xbfb8aa3b, v67
	v_fma_f32 v71, v71, s21, 0.5
	v_exp_f32_e32 v67, v67
	v_max_f32_e32 v71, 1.0, v71
	v_fma_f32 v70, v70, s21, 0.5
	v_cvt_pk_u8_f32 v0, v71, 2, v0
	v_max_f32_e32 v70, 1.0, v70
	v_cvt_pk_u8_f32 v0, v70, 3, v0
	v_add_f32_e32 v66, 1.0, v66
	v_rcp_f32_e32 v66, v66
	global_store_dword v[126:127], v0, off offset:3584
	v_add_f32_e32 v0, 1.0, v67
	v_rcp_f32_e32 v0, v0
	v_mul_f32_e32 v67, 0xbfb8aa3b, v68
	v_exp_f32_e32 v67, v67
	v_mul_f32_e32 v68, 0xbfb8aa3b, v69
	v_exp_f32_e32 v68, v68
	v_fma_f32 v66, v66, s21, 0.5
	v_max_f32_e32 v66, 1.0, v66
	v_fma_f32 v0, v0, s21, 0.5
	v_cvt_pk_u8_f32 v66, v66, 0, 0
	v_max_f32_e32 v0, 1.0, v0
	v_add_f32_e32 v67, 1.0, v67
	v_rcp_f32_e32 v67, v67
	v_cvt_pk_u8_f32 v0, v0, 1, v66
	v_add_f32_e32 v66, 1.0, v68
	v_rcp_f32_e32 v66, v66
	v_mul_f32_e32 v62, 0xbfb8aa3b, v62
	v_exp_f32_e32 v62, v62
	v_mul_f32_e32 v63, 0xbfb8aa3b, v63
	v_fma_f32 v67, v67, s21, 0.5
	v_exp_f32_e32 v63, v63
	v_max_f32_e32 v67, 1.0, v67
	v_fma_f32 v66, v66, s21, 0.5
	v_cvt_pk_u8_f32 v0, v67, 2, v0
	v_max_f32_e32 v66, 1.0, v66
	v_cvt_pk_u8_f32 v0, v66, 3, v0
	v_add_f32_e32 v62, 1.0, v62
	v_rcp_f32_e32 v62, v62
	global_store_dword v[126:127], v0, off offset:3840
	v_add_f32_e32 v0, 1.0, v63
	v_rcp_f32_e32 v0, v0
	v_mul_f32_e32 v63, 0xbfb8aa3b, v64
	v_exp_f32_e32 v63, v63
	v_mul_f32_e32 v64, 0xbfb8aa3b, v65
	v_exp_f32_e32 v64, v64
	v_fma_f32 v62, v62, s21, 0.5
	v_max_f32_e32 v62, 1.0, v62
	v_fma_f32 v0, v0, s21, 0.5
	v_cvt_pk_u8_f32 v62, v62, 0, 0
	v_max_f32_e32 v0, 1.0, v0
	v_add_f32_e32 v63, 1.0, v63
	v_rcp_f32_e32 v63, v63
	v_cvt_pk_u8_f32 v0, v0, 1, v62
	v_add_f32_e32 v62, 1.0, v64
	v_rcp_f32_e32 v62, v62
	v_mul_f32_e32 v58, 0xbfb8aa3b, v58
	v_fma_f32 v63, v63, s21, 0.5
	v_exp_f32_e32 v58, v58
	v_mul_f32_e32 v59, 0xbfb8aa3b, v59
	v_max_f32_e32 v63, 1.0, v63
	v_fma_f32 v62, v62, s21, 0.5
	v_exp_f32_e32 v59, v59
	v_cvt_pk_u8_f32 v0, v63, 2, v0
	v_max_f32_e32 v62, 1.0, v62
	v_cvt_pk_u8_f32 v0, v62, 3, v0
	v_add_co_u32_e32 v62, vcc, s77, v126
	v_add_f32_e32 v58, 1.0, v58
	s_nop 0
	v_addc_co_u32_e32 v63, vcc, 0, v127, vcc
	v_rcp_f32_e32 v58, v58
	global_store_dword v[62:63], v0, off
	v_add_f32_e32 v0, 1.0, v59
	v_rcp_f32_e32 v0, v0
	v_mul_f32_e32 v59, 0xbfb8aa3b, v60
	v_exp_f32_e32 v59, v59
	v_mul_f32_e32 v60, 0xbfb8aa3b, v61
	v_exp_f32_e32 v60, v60
	v_fma_f32 v58, v58, s21, 0.5
	v_max_f32_e32 v58, 1.0, v58
	v_fma_f32 v0, v0, s21, 0.5
	v_cvt_pk_u8_f32 v58, v58, 0, 0
	v_max_f32_e32 v0, 1.0, v0
	v_add_f32_e32 v59, 1.0, v59
	v_rcp_f32_e32 v59, v59
	v_cvt_pk_u8_f32 v0, v0, 1, v58
	v_add_f32_e32 v58, 1.0, v60
	v_rcp_f32_e32 v58, v58
	v_mul_f32_e32 v54, 0xbfb8aa3b, v54
	v_exp_f32_e32 v54, v54
	v_mul_f32_e32 v55, 0xbfb8aa3b, v55
	v_fma_f32 v59, v59, s21, 0.5
	v_exp_f32_e32 v55, v55
	v_max_f32_e32 v59, 1.0, v59
	v_fma_f32 v58, v58, s21, 0.5
	v_cvt_pk_u8_f32 v0, v59, 2, v0
	v_max_f32_e32 v58, 1.0, v58
	v_cvt_pk_u8_f32 v0, v58, 3, v0
	v_add_f32_e32 v54, 1.0, v54
	v_rcp_f32_e32 v54, v54
	global_store_dword v[62:63], v0, off offset:256
	v_add_f32_e32 v0, 1.0, v55
	v_rcp_f32_e32 v0, v0
	v_mul_f32_e32 v55, 0xbfb8aa3b, v56
	v_exp_f32_e32 v55, v55
	v_mul_f32_e32 v56, 0xbfb8aa3b, v57
	v_exp_f32_e32 v56, v56
	v_fma_f32 v54, v54, s21, 0.5
	v_max_f32_e32 v54, 1.0, v54
	v_fma_f32 v0, v0, s21, 0.5
	v_cvt_pk_u8_f32 v54, v54, 0, 0
	v_max_f32_e32 v0, 1.0, v0
	v_add_f32_e32 v55, 1.0, v55
	v_rcp_f32_e32 v55, v55
	v_cvt_pk_u8_f32 v0, v0, 1, v54
	v_add_f32_e32 v54, 1.0, v56
	v_rcp_f32_e32 v54, v54
	v_mul_f32_e32 v50, 0xbfb8aa3b, v50
	v_exp_f32_e32 v50, v50
	v_mul_f32_e32 v51, 0xbfb8aa3b, v51
	v_fma_f32 v55, v55, s21, 0.5
	v_exp_f32_e32 v51, v51
	v_max_f32_e32 v55, 1.0, v55
	v_fma_f32 v54, v54, s21, 0.5
	v_cvt_pk_u8_f32 v0, v55, 2, v0
	v_max_f32_e32 v54, 1.0, v54
	v_cvt_pk_u8_f32 v0, v54, 3, v0
	v_add_f32_e32 v50, 1.0, v50
	v_rcp_f32_e32 v50, v50
	global_store_dword v[62:63], v0, off offset:512
	v_add_f32_e32 v0, 1.0, v51
	v_rcp_f32_e32 v0, v0
	v_mul_f32_e32 v51, 0xbfb8aa3b, v52
	v_exp_f32_e32 v51, v51
	v_mul_f32_e32 v52, 0xbfb8aa3b, v53
	v_exp_f32_e32 v52, v52
	v_fma_f32 v50, v50, s21, 0.5
	v_max_f32_e32 v50, 1.0, v50
	v_fma_f32 v0, v0, s21, 0.5
	v_cvt_pk_u8_f32 v50, v50, 0, 0
	v_max_f32_e32 v0, 1.0, v0
	v_add_f32_e32 v51, 1.0, v51
	v_rcp_f32_e32 v51, v51
	v_cvt_pk_u8_f32 v0, v0, 1, v50
	v_add_f32_e32 v50, 1.0, v52
	v_rcp_f32_e32 v50, v50
	v_mul_f32_e32 v46, 0xbfb8aa3b, v46
	v_exp_f32_e32 v46, v46
	v_mul_f32_e32 v47, 0xbfb8aa3b, v47
	v_fma_f32 v51, v51, s21, 0.5
	v_exp_f32_e32 v47, v47
	v_max_f32_e32 v51, 1.0, v51
	v_fma_f32 v50, v50, s21, 0.5
	v_cvt_pk_u8_f32 v0, v51, 2, v0
	v_max_f32_e32 v50, 1.0, v50
	v_cvt_pk_u8_f32 v0, v50, 3, v0
	v_add_f32_e32 v46, 1.0, v46
	v_rcp_f32_e32 v46, v46
	global_store_dword v[62:63], v0, off offset:768
	v_add_f32_e32 v0, 1.0, v47
	v_rcp_f32_e32 v0, v0
	v_mul_f32_e32 v47, 0xbfb8aa3b, v48
	v_exp_f32_e32 v47, v47
	v_mul_f32_e32 v48, 0xbfb8aa3b, v49
	v_exp_f32_e32 v48, v48
	v_fma_f32 v46, v46, s21, 0.5
	v_max_f32_e32 v46, 1.0, v46
	v_fma_f32 v0, v0, s21, 0.5
	v_cvt_pk_u8_f32 v46, v46, 0, 0
	v_max_f32_e32 v0, 1.0, v0
	v_add_f32_e32 v47, 1.0, v47
	v_rcp_f32_e32 v47, v47
	v_cvt_pk_u8_f32 v0, v0, 1, v46
	v_add_f32_e32 v46, 1.0, v48
	v_rcp_f32_e32 v46, v46
	v_mul_f32_e32 v42, 0xbfb8aa3b, v42
	v_exp_f32_e32 v42, v42
	v_mul_f32_e32 v43, 0xbfb8aa3b, v43
	v_fma_f32 v47, v47, s21, 0.5
	v_exp_f32_e32 v43, v43
	v_max_f32_e32 v47, 1.0, v47
	v_fma_f32 v46, v46, s21, 0.5
	v_cvt_pk_u8_f32 v0, v47, 2, v0
	v_max_f32_e32 v46, 1.0, v46
	v_cvt_pk_u8_f32 v0, v46, 3, v0
	v_add_f32_e32 v42, 1.0, v42
	v_rcp_f32_e32 v42, v42
	global_store_dword v[62:63], v0, off offset:1024
	v_add_f32_e32 v0, 1.0, v43
	v_rcp_f32_e32 v0, v0
	v_mul_f32_e32 v43, 0xbfb8aa3b, v44
	v_exp_f32_e32 v43, v43
	v_mul_f32_e32 v44, 0xbfb8aa3b, v45
	v_exp_f32_e32 v44, v44
	v_fma_f32 v42, v42, s21, 0.5
	v_max_f32_e32 v42, 1.0, v42
	v_fma_f32 v0, v0, s21, 0.5
	v_cvt_pk_u8_f32 v42, v42, 0, 0
	v_max_f32_e32 v0, 1.0, v0
	v_add_f32_e32 v43, 1.0, v43
	v_rcp_f32_e32 v43, v43
	v_cvt_pk_u8_f32 v0, v0, 1, v42
	v_add_f32_e32 v42, 1.0, v44
	v_rcp_f32_e32 v42, v42
	v_mul_f32_e32 v38, 0xbfb8aa3b, v38
	v_exp_f32_e32 v38, v38
	v_mul_f32_e32 v39, 0xbfb8aa3b, v39
	v_fma_f32 v43, v43, s21, 0.5
	v_exp_f32_e32 v39, v39
	v_max_f32_e32 v43, 1.0, v43
	v_fma_f32 v42, v42, s21, 0.5
	v_cvt_pk_u8_f32 v0, v43, 2, v0
	v_max_f32_e32 v42, 1.0, v42
	v_cvt_pk_u8_f32 v0, v42, 3, v0
	v_add_f32_e32 v38, 1.0, v38
	v_rcp_f32_e32 v38, v38
	global_store_dword v[62:63], v0, off offset:1280
	v_add_f32_e32 v0, 1.0, v39
	v_rcp_f32_e32 v0, v0
	v_mul_f32_e32 v39, 0xbfb8aa3b, v40
	v_exp_f32_e32 v39, v39
	v_mul_f32_e32 v40, 0xbfb8aa3b, v41
	v_exp_f32_e32 v40, v40
	v_fma_f32 v38, v38, s21, 0.5
	v_max_f32_e32 v38, 1.0, v38
	v_fma_f32 v0, v0, s21, 0.5
	v_cvt_pk_u8_f32 v38, v38, 0, 0
	v_max_f32_e32 v0, 1.0, v0
	v_add_f32_e32 v39, 1.0, v39
	v_rcp_f32_e32 v39, v39
	v_cvt_pk_u8_f32 v0, v0, 1, v38
	v_add_f32_e32 v38, 1.0, v40
	v_rcp_f32_e32 v38, v38
	v_mul_f32_e32 v34, 0xbfb8aa3b, v34
	v_exp_f32_e32 v34, v34
	v_mul_f32_e32 v35, 0xbfb8aa3b, v35
	v_fma_f32 v39, v39, s21, 0.5
	v_exp_f32_e32 v35, v35
	v_max_f32_e32 v39, 1.0, v39
	v_fma_f32 v38, v38, s21, 0.5
	v_cvt_pk_u8_f32 v0, v39, 2, v0
	v_max_f32_e32 v38, 1.0, v38
	v_cvt_pk_u8_f32 v0, v38, 3, v0
	v_add_f32_e32 v34, 1.0, v34
	v_rcp_f32_e32 v34, v34
	global_store_dword v[62:63], v0, off offset:1536
	v_add_f32_e32 v0, 1.0, v35
	v_rcp_f32_e32 v0, v0
	v_mul_f32_e32 v35, 0xbfb8aa3b, v36
	v_exp_f32_e32 v35, v35
	v_mul_f32_e32 v36, 0xbfb8aa3b, v37
	v_exp_f32_e32 v36, v36
	v_fma_f32 v34, v34, s21, 0.5
	v_max_f32_e32 v34, 1.0, v34
	v_fma_f32 v0, v0, s21, 0.5
	v_cvt_pk_u8_f32 v34, v34, 0, 0
	v_max_f32_e32 v0, 1.0, v0
	v_add_f32_e32 v35, 1.0, v35
	v_rcp_f32_e32 v35, v35
	v_cvt_pk_u8_f32 v0, v0, 1, v34
	v_add_f32_e32 v34, 1.0, v36
	v_rcp_f32_e32 v34, v34
	v_mul_f32_e32 v30, 0xbfb8aa3b, v30
	v_exp_f32_e32 v30, v30
	v_mul_f32_e32 v31, 0xbfb8aa3b, v31
	v_fma_f32 v35, v35, s21, 0.5
	v_exp_f32_e32 v31, v31
	v_max_f32_e32 v35, 1.0, v35
	v_fma_f32 v34, v34, s21, 0.5
	v_cvt_pk_u8_f32 v0, v35, 2, v0
	v_max_f32_e32 v34, 1.0, v34
	v_cvt_pk_u8_f32 v0, v34, 3, v0
	v_add_f32_e32 v30, 1.0, v30
	v_rcp_f32_e32 v30, v30
	global_store_dword v[62:63], v0, off offset:1792
	v_add_f32_e32 v0, 1.0, v31
	v_rcp_f32_e32 v0, v0
	v_mul_f32_e32 v31, 0xbfb8aa3b, v32
	v_exp_f32_e32 v31, v31
	v_mul_f32_e32 v32, 0xbfb8aa3b, v33
	v_exp_f32_e32 v32, v32
	v_fma_f32 v30, v30, s21, 0.5
	v_max_f32_e32 v30, 1.0, v30
	v_fma_f32 v0, v0, s21, 0.5
	v_cvt_pk_u8_f32 v30, v30, 0, 0
	v_max_f32_e32 v0, 1.0, v0
	v_add_f32_e32 v31, 1.0, v31
	v_rcp_f32_e32 v31, v31
	v_cvt_pk_u8_f32 v0, v0, 1, v30
	v_add_f32_e32 v30, 1.0, v32
	v_rcp_f32_e32 v30, v30
	v_mul_f32_e32 v26, 0xbfb8aa3b, v26
	v_exp_f32_e32 v26, v26
	v_mul_f32_e32 v27, 0xbfb8aa3b, v27
	v_fma_f32 v31, v31, s21, 0.5
	v_exp_f32_e32 v27, v27
	v_max_f32_e32 v31, 1.0, v31
	v_fma_f32 v30, v30, s21, 0.5
	v_cvt_pk_u8_f32 v0, v31, 2, v0
	v_max_f32_e32 v30, 1.0, v30
	v_cvt_pk_u8_f32 v0, v30, 3, v0
	v_add_f32_e32 v26, 1.0, v26
	v_rcp_f32_e32 v26, v26
	global_store_dword v[62:63], v0, off offset:2048
	v_add_f32_e32 v0, 1.0, v27
	v_rcp_f32_e32 v0, v0
	v_mul_f32_e32 v27, 0xbfb8aa3b, v28
	v_exp_f32_e32 v27, v27
	v_mul_f32_e32 v28, 0xbfb8aa3b, v29
	v_exp_f32_e32 v28, v28
	v_fma_f32 v26, v26, s21, 0.5
	v_max_f32_e32 v26, 1.0, v26
	v_fma_f32 v0, v0, s21, 0.5
	v_cvt_pk_u8_f32 v26, v26, 0, 0
	v_max_f32_e32 v0, 1.0, v0
	v_add_f32_e32 v27, 1.0, v27
	v_rcp_f32_e32 v27, v27
	v_cvt_pk_u8_f32 v0, v0, 1, v26
	v_add_f32_e32 v26, 1.0, v28
	v_rcp_f32_e32 v26, v26
	v_mul_f32_e32 v22, 0xbfb8aa3b, v22
	v_exp_f32_e32 v22, v22
	v_mul_f32_e32 v23, 0xbfb8aa3b, v23
	v_fma_f32 v27, v27, s21, 0.5
	v_exp_f32_e32 v23, v23
	v_max_f32_e32 v27, 1.0, v27
	v_fma_f32 v26, v26, s21, 0.5
	v_cvt_pk_u8_f32 v0, v27, 2, v0
	v_max_f32_e32 v26, 1.0, v26
	v_cvt_pk_u8_f32 v0, v26, 3, v0
	v_add_f32_e32 v22, 1.0, v22
	v_rcp_f32_e32 v22, v22
	global_store_dword v[62:63], v0, off offset:2304
	v_add_f32_e32 v0, 1.0, v23
	v_rcp_f32_e32 v0, v0
	v_mul_f32_e32 v23, 0xbfb8aa3b, v24
	v_exp_f32_e32 v23, v23
	v_mul_f32_e32 v24, 0xbfb8aa3b, v25
	v_exp_f32_e32 v24, v24
	v_fma_f32 v22, v22, s21, 0.5
	v_max_f32_e32 v22, 1.0, v22
	v_fma_f32 v0, v0, s21, 0.5
	v_cvt_pk_u8_f32 v22, v22, 0, 0
	v_max_f32_e32 v0, 1.0, v0
	v_add_f32_e32 v23, 1.0, v23
	v_rcp_f32_e32 v23, v23
	v_cvt_pk_u8_f32 v0, v0, 1, v22
	v_add_f32_e32 v22, 1.0, v24
	v_rcp_f32_e32 v22, v22
	v_mul_f32_e32 v18, 0xbfb8aa3b, v18
	v_exp_f32_e32 v18, v18
	v_mul_f32_e32 v19, 0xbfb8aa3b, v19
	v_fma_f32 v23, v23, s21, 0.5
	v_exp_f32_e32 v19, v19
	v_max_f32_e32 v23, 1.0, v23
	v_fma_f32 v22, v22, s21, 0.5
	v_cvt_pk_u8_f32 v0, v23, 2, v0
	v_max_f32_e32 v22, 1.0, v22
	v_cvt_pk_u8_f32 v0, v22, 3, v0
	v_add_f32_e32 v18, 1.0, v18
	v_rcp_f32_e32 v18, v18
	global_store_dword v[62:63], v0, off offset:2560
	v_add_f32_e32 v0, 1.0, v19
	v_rcp_f32_e32 v0, v0
	v_mul_f32_e32 v19, 0xbfb8aa3b, v20
	v_exp_f32_e32 v19, v19
	v_mul_f32_e32 v20, 0xbfb8aa3b, v21
	v_exp_f32_e32 v20, v20
	v_fma_f32 v18, v18, s21, 0.5
	v_max_f32_e32 v18, 1.0, v18
	v_fma_f32 v0, v0, s21, 0.5
	v_cvt_pk_u8_f32 v18, v18, 0, 0
	v_max_f32_e32 v0, 1.0, v0
	v_add_f32_e32 v19, 1.0, v19
	v_rcp_f32_e32 v19, v19
	v_cvt_pk_u8_f32 v0, v0, 1, v18
	v_add_f32_e32 v18, 1.0, v20
	v_rcp_f32_e32 v18, v18
	v_mul_f32_e32 v14, 0xbfb8aa3b, v14
	v_exp_f32_e32 v14, v14
	v_mul_f32_e32 v15, 0xbfb8aa3b, v15
	v_fma_f32 v19, v19, s21, 0.5
	v_exp_f32_e32 v15, v15
	v_max_f32_e32 v19, 1.0, v19
	v_fma_f32 v18, v18, s21, 0.5
	v_cvt_pk_u8_f32 v0, v19, 2, v0
	v_max_f32_e32 v18, 1.0, v18
	v_cvt_pk_u8_f32 v0, v18, 3, v0
	v_add_f32_e32 v14, 1.0, v14
	v_rcp_f32_e32 v14, v14
	global_store_dword v[62:63], v0, off offset:2816
	v_add_f32_e32 v0, 1.0, v15
	v_rcp_f32_e32 v0, v0
	v_mul_f32_e32 v15, 0xbfb8aa3b, v16
	v_exp_f32_e32 v15, v15
	v_mul_f32_e32 v16, 0xbfb8aa3b, v17
	v_exp_f32_e32 v16, v16
	v_fma_f32 v14, v14, s21, 0.5
	v_max_f32_e32 v14, 1.0, v14
	v_fma_f32 v0, v0, s21, 0.5
	v_cvt_pk_u8_f32 v14, v14, 0, 0
	v_max_f32_e32 v0, 1.0, v0
	v_add_f32_e32 v15, 1.0, v15
	v_rcp_f32_e32 v15, v15
	v_cvt_pk_u8_f32 v0, v0, 1, v14
	v_add_f32_e32 v14, 1.0, v16
	v_rcp_f32_e32 v14, v14
	v_mul_f32_e32 v10, 0xbfb8aa3b, v10
	v_exp_f32_e32 v10, v10
	v_mul_f32_e32 v11, 0xbfb8aa3b, v11
	v_fma_f32 v15, v15, s21, 0.5
	v_exp_f32_e32 v11, v11
	v_max_f32_e32 v15, 1.0, v15
	v_fma_f32 v14, v14, s21, 0.5
	v_cvt_pk_u8_f32 v0, v15, 2, v0
	v_max_f32_e32 v14, 1.0, v14
	v_cvt_pk_u8_f32 v0, v14, 3, v0
	v_add_f32_e32 v10, 1.0, v10
	v_rcp_f32_e32 v10, v10
	global_store_dword v[62:63], v0, off offset:3072
	v_add_f32_e32 v0, 1.0, v11
	v_rcp_f32_e32 v0, v0
	v_mul_f32_e32 v11, 0xbfb8aa3b, v12
	v_exp_f32_e32 v11, v11
	v_mul_f32_e32 v12, 0xbfb8aa3b, v13
	v_exp_f32_e32 v12, v12
	v_fma_f32 v10, v10, s21, 0.5
	v_max_f32_e32 v10, 1.0, v10
	v_fma_f32 v0, v0, s21, 0.5
	v_cvt_pk_u8_f32 v10, v10, 0, 0
	v_max_f32_e32 v0, 1.0, v0
	v_add_f32_e32 v11, 1.0, v11
	v_rcp_f32_e32 v11, v11
	v_cvt_pk_u8_f32 v0, v0, 1, v10
	v_add_f32_e32 v10, 1.0, v12
	v_rcp_f32_e32 v10, v10
	v_mul_f32_e32 v6, 0xbfb8aa3b, v6
	v_exp_f32_e32 v6, v6
	v_mul_f32_e32 v7, 0xbfb8aa3b, v7
	v_fma_f32 v11, v11, s21, 0.5
	v_exp_f32_e32 v7, v7
	v_max_f32_e32 v11, 1.0, v11
	v_fma_f32 v10, v10, s21, 0.5
	v_cvt_pk_u8_f32 v0, v11, 2, v0
	v_max_f32_e32 v10, 1.0, v10
	v_cvt_pk_u8_f32 v0, v10, 3, v0
	v_add_f32_e32 v6, 1.0, v6
	v_rcp_f32_e32 v6, v6
	global_store_dword v[62:63], v0, off offset:3328
	v_add_f32_e32 v0, 1.0, v7
	v_rcp_f32_e32 v0, v0
	v_mul_f32_e32 v7, 0xbfb8aa3b, v8
	v_exp_f32_e32 v7, v7
	v_mul_f32_e32 v8, 0xbfb8aa3b, v9
	v_exp_f32_e32 v8, v8
	v_fma_f32 v6, v6, s21, 0.5
	v_max_f32_e32 v6, 1.0, v6
	v_fma_f32 v0, v0, s21, 0.5
	v_cvt_pk_u8_f32 v6, v6, 0, 0
	v_max_f32_e32 v0, 1.0, v0
	v_add_f32_e32 v7, 1.0, v7
	v_rcp_f32_e32 v7, v7
	v_cvt_pk_u8_f32 v0, v0, 1, v6
	v_add_f32_e32 v6, 1.0, v8
	v_rcp_f32_e32 v6, v6
	v_mul_f32_e32 v2, 0xbfb8aa3b, v2
	v_exp_f32_e32 v2, v2
	v_mul_f32_e32 v3, 0xbfb8aa3b, v3
	v_fma_f32 v7, v7, s21, 0.5
	v_exp_f32_e32 v3, v3
	v_max_f32_e32 v7, 1.0, v7
	v_fma_f32 v6, v6, s21, 0.5
	v_cvt_pk_u8_f32 v0, v7, 2, v0
	v_max_f32_e32 v6, 1.0, v6
	v_cvt_pk_u8_f32 v0, v6, 3, v0
	v_add_f32_e32 v2, 1.0, v2
	v_rcp_f32_e32 v2, v2
	global_store_dword v[62:63], v0, off offset:3584
	v_add_f32_e32 v0, 1.0, v3
	v_rcp_f32_e32 v0, v0
	v_mul_f32_e32 v3, 0xbfb8aa3b, v4
	v_exp_f32_e32 v3, v3
	v_mul_f32_e32 v4, 0xbfb8aa3b, v5
	v_exp_f32_e32 v4, v4
	v_fma_f32 v2, v2, s21, 0.5
	v_max_f32_e32 v2, 1.0, v2
	v_fma_f32 v0, v0, s21, 0.5
	v_cvt_pk_u8_f32 v2, v2, 0, 0
	v_max_f32_e32 v0, 1.0, v0
	v_add_f32_e32 v3, 1.0, v3
	v_rcp_f32_e32 v3, v3
	v_cvt_pk_u8_f32 v0, v0, 1, v2
	v_add_f32_e32 v2, 1.0, v4
	v_rcp_f32_e32 v2, v2
	v_fma_f32 v3, v3, s21, 0.5
	s_add_i32 s96, s96, 1
	v_max_f32_e32 v3, 1.0, v3
	v_fma_f32 v2, v2, s21, 0.5
	s_add_u32 s12, s12, 0x200000
	v_cvt_pk_u8_f32 v0, v3, 2, v0
	v_max_f32_e32 v2, 1.0, v2
	s_addc_u32 s13, s13, 0
	v_cvt_pk_u8_f32 v0, v2, 3, v0
	s_cmp_lg_u32 s96, 3
	s_mov_b32 s97, 0x12000
	global_store_dword v[62:63], v0, off offset:3840
	s_cbranch_scc1 .LBB0_328
	s_lshl_b64 s[2:3], s[8:9], 10
	s_add_u32 s12, s72, s18
	s_addc_u32 s13, s73, s19
	v_mov_b32_e32 v2, v1
	v_mov_b32_e32 v3, v1
	s_add_u32 s16, s72, s2
	v_mov_b32_e32 v0, v1
	v_mov_b64_e32 v[6:7], v[2:3]
	v_mov_b64_e32 v[10:11], v[2:3]
	v_mov_b64_e32 v[22:23], v[2:3]
	v_mov_b64_e32 v[26:27], v[2:3]
	v_mov_b64_e32 v[38:39], v[2:3]
	v_mov_b64_e32 v[42:43], v[2:3]
	v_mov_b64_e32 v[54:55], v[2:3]
	v_mov_b64_e32 v[58:59], v[2:3]
	v_mov_b64_e32 v[14:15], v[2:3]
	v_mov_b64_e32 v[18:19], v[2:3]
	v_mov_b64_e32 v[30:31], v[2:3]
	v_mov_b64_e32 v[34:35], v[2:3]
	v_mov_b64_e32 v[46:47], v[2:3]
	v_mov_b64_e32 v[50:51], v[2:3]
	v_mov_b64_e32 v[62:63], v[2:3]
	v_mov_b64_e32 v[66:67], v[2:3]
	v_mov_b64_e32 v[70:71], v[2:3]
	v_mov_b64_e32 v[74:75], v[2:3]
	v_mov_b64_e32 v[86:87], v[2:3]
	v_mov_b64_e32 v[90:91], v[2:3]
	v_mov_b64_e32 v[102:103], v[2:3]
	v_mov_b64_e32 v[106:107], v[2:3]
	v_mov_b64_e32 v[118:119], v[2:3]
	v_mov_b64_e32 v[122:123], v[2:3]
	v_mov_b64_e32 v[78:79], v[2:3]
	v_mov_b64_e32 v[82:83], v[2:3]
	v_mov_b64_e32 v[94:95], v[2:3]
	v_mov_b64_e32 v[98:99], v[2:3]
	v_mov_b64_e32 v[110:111], v[2:3]
	v_mov_b64_e32 v[114:115], v[2:3]
	v_mov_b64_e32 v[126:127], v[2:3]
	v_mov_b64_e32 v[130:131], v[2:3]
	s_addc_u32 s17, s73, s3
	s_mov_b32 s56, 0
	v_mov_b64_e32 v[4:5], v[0:1]
	v_mov_b64_e32 v[8:9], v[0:1]
	v_mov_b64_e32 v[20:21], v[0:1]
	v_mov_b64_e32 v[24:25], v[0:1]
	v_mov_b64_e32 v[36:37], v[0:1]
	v_mov_b64_e32 v[40:41], v[0:1]
	v_mov_b64_e32 v[52:53], v[0:1]
	v_mov_b64_e32 v[56:57], v[0:1]
	v_mov_b64_e32 v[12:13], v[0:1]
	v_mov_b64_e32 v[16:17], v[0:1]
	v_mov_b64_e32 v[28:29], v[0:1]
	v_mov_b64_e32 v[32:33], v[0:1]
	v_mov_b64_e32 v[44:45], v[0:1]
	v_mov_b64_e32 v[48:49], v[0:1]
	v_mov_b64_e32 v[60:61], v[0:1]
	v_mov_b64_e32 v[64:65], v[0:1]
	v_mov_b64_e32 v[68:69], v[0:1]
	v_mov_b64_e32 v[72:73], v[0:1]
	v_mov_b64_e32 v[84:85], v[0:1]
	v_mov_b64_e32 v[88:89], v[0:1]
	v_mov_b64_e32 v[100:101], v[0:1]
	v_mov_b64_e32 v[104:105], v[0:1]
	v_mov_b64_e32 v[116:117], v[0:1]
	v_mov_b64_e32 v[120:121], v[0:1]
	v_mov_b64_e32 v[76:77], v[0:1]
	v_mov_b64_e32 v[80:81], v[0:1]
	v_mov_b64_e32 v[92:93], v[0:1]
	v_mov_b64_e32 v[96:97], v[0:1]
	v_mov_b64_e32 v[108:109], v[0:1]
	v_mov_b64_e32 v[112:113], v[0:1]
	v_mov_b64_e32 v[124:125], v[0:1]
	v_mov_b64_e32 v[128:129], v[0:1]
	s_movk_i32 s96, 0x5000
	s_branch .LBB0_340

.LBB0_341:
	s_cmpk_eq_i32 s40, 0x400
	s_cselect_b64 s[52:53], -1, 0
	s_and_b64 s[52:53], s[2:3], s[52:53]
	s_and_b64 s[54:55], s[52:53], exec
	s_cselect_b32 s82, s63, s57
	s_add_u32 s83, s18, s40
	s_addc_u32 s87, s19, s41
	s_cmpk_eq_i32 s40, 0x400
	s_cselect_b64 s[54:55], -1, 0
	s_and_b64 s[54:55], s[54:55], exec
	s_cselect_b32 s54, s82, s83
	s_and_b64 s[82:83], s[52:53], exec
	s_cselect_b32 s55, s66, s58
	s_cmpk_eq_i32 s40, 0x400
	v_add_u32_e32 v145, s6, v143
	s_cselect_b64 s[82:83], -1, 0
	ds_read_b128 v[146:149], v145
	ds_read_b128 v[150:153], v145 offset:1024
	ds_read_b128 v[158:161], v145 offset:2048
	ds_read_b128 v[162:165], v145 offset:3072
	v_add_u32_e32 v145, s7, v143
	s_and_b64 s[94:95], s[82:83], exec
	ds_read_b128 v[196:199], v145
	ds_read_b128 v[200:203], v145 offset:1024
	ds_read_b128 v[204:207], v145 offset:2048
	ds_read_b128 v[208:211], v145 offset:3072
	s_cselect_b32 s55, s55, s87
	s_and_b64 s[82:83], s[82:83], s[8:9]
	s_and_b64 s[82:83], s[82:83], exec
	s_cselect_b32 s83, 0, s40
	s_cselect_b32 s82, 0, s41
	s_add_u32 s83, s59, s83
	s_addc_u32 s82, s62, s82
	s_and_b64 s[52:53], s[52:53], exec
	s_cselect_b32 s53, s84, s82
	s_cselect_b32 s52, s70, s83
	v_lshl_add_u64 v[154:155], v[138:139], 0, s[40:41]
	s_add_i32 s87, s85, 0
	v_lshl_add_u64 v[154:155], v[154:155], 0, s[78:79]
	s_add_i32 m0, s87, 0xc000
	ds_read_b128 v[212:215], v144
	ds_read_b128 v[216:219], v144 offset:1024
	ds_read_b128 v[220:223], v144 offset:2048
	ds_read_b128 v[224:227], v144 offset:3072
	ds_read_b128 v[228:231], v144 offset:4096
	ds_read_b128 v[232:235], v144 offset:5120
	ds_read_b128 v[236:239], v144 offset:6144
	ds_read_b128 v[240:243], v144 offset:7168
	global_load_lds_dwordx4 v[154:155], off
	v_lshl_add_u64 v[154:155], v[136:137], 0, s[40:41]
	v_lshl_add_u64 v[154:155], v[154:155], 0, s[78:79]
	s_add_i32 m0, s87, 0xe000
	s_nop 0
	global_load_lds_dwordx4 v[154:155], off
	s_waitcnt vmcnt(8)
	s_waitcnt lgkmcnt(0)
	s_barrier
	s_setprio 1
	s_waitcnt lgkmcnt(0)
	v_mfma_f32_16x16x32_bf16 v[128:131], v[146:149], v[212:215], v[128:131]
	v_mfma_f32_16x16x32_bf16 v[124:127], v[158:161], v[212:215], v[124:127]
	v_mfma_f32_16x16x32_bf16 v[112:115], v[146:149], v[220:223], v[112:115]
	v_mfma_f32_16x16x32_bf16 v[108:111], v[158:161], v[220:223], v[108:111]
	s_setprio 0
	s_setprio 1
	v_mfma_f32_16x16x32_bf16 v[96:99], v[146:149], v[228:231], v[96:99]
	v_mfma_f32_16x16x32_bf16 v[92:95], v[158:161], v[228:231], v[92:95]
	v_mfma_f32_16x16x32_bf16 v[80:83], v[146:149], v[236:239], v[80:83]
	v_mfma_f32_16x16x32_bf16 v[76:79], v[158:161], v[236:239], v[76:79]
	s_setprio 0
	s_setprio 1
	v_mfma_f32_16x16x32_bf16 v[128:131], v[150:153], v[216:219], v[128:131]
	v_mfma_f32_16x16x32_bf16 v[124:127], v[162:165], v[216:219], v[124:127]
	v_mfma_f32_16x16x32_bf16 v[112:115], v[150:153], v[224:227], v[112:115]
	v_mfma_f32_16x16x32_bf16 v[108:111], v[162:165], v[224:227], v[108:111]
	s_setprio 0
	s_setprio 1
	v_mfma_f32_16x16x32_bf16 v[96:99], v[150:153], v[232:235], v[96:99]
	v_mfma_f32_16x16x32_bf16 v[92:95], v[162:165], v[232:235], v[92:95]
	v_mfma_f32_16x16x32_bf16 v[80:83], v[150:153], v[240:243], v[80:83]
	v_mfma_f32_16x16x32_bf16 v[76:79], v[162:165], v[240:243], v[76:79]
	s_setprio 0
	s_setprio 1
	v_mfma_f32_16x16x32_bf16 v[120:123], v[196:199], v[212:215], v[120:123]
	v_mfma_f32_16x16x32_bf16 v[116:119], v[204:207], v[212:215], v[116:119]
	v_mfma_f32_16x16x32_bf16 v[104:107], v[196:199], v[220:223], v[104:107]
	v_mfma_f32_16x16x32_bf16 v[100:103], v[204:207], v[220:223], v[100:103]
	s_setprio 0
	s_setprio 1
	v_mfma_f32_16x16x32_bf16 v[88:91], v[196:199], v[228:231], v[88:91]
	v_mfma_f32_16x16x32_bf16 v[84:87], v[204:207], v[228:231], v[84:87]
	v_mfma_f32_16x16x32_bf16 v[72:75], v[196:199], v[236:239], v[72:75]
	v_mfma_f32_16x16x32_bf16 v[68:71], v[204:207], v[236:239], v[68:71]
	s_setprio 0
	s_setprio 1
	v_mfma_f32_16x16x32_bf16 v[120:123], v[200:203], v[216:219], v[120:123]
	v_mfma_f32_16x16x32_bf16 v[116:119], v[208:211], v[216:219], v[116:119]
	v_mfma_f32_16x16x32_bf16 v[104:107], v[200:203], v[224:227], v[104:107]
	v_mfma_f32_16x16x32_bf16 v[100:103], v[208:211], v[224:227], v[100:103]
	s_setprio 0
	s_setprio 1
	v_mfma_f32_16x16x32_bf16 v[88:91], v[200:203], v[232:235], v[88:91]
	v_mfma_f32_16x16x32_bf16 v[84:87], v[208:211], v[232:235], v[84:87]
	v_mfma_f32_16x16x32_bf16 v[72:75], v[200:203], v[240:243], v[72:75]
	v_mfma_f32_16x16x32_bf16 v[68:71], v[208:211], v[240:243], v[68:71]
	s_setprio 0
	s_barrier
	s_add_i32 s82, s6, s85
	v_lshl_add_u64 v[154:155], s[52:53], 0, v[132:133]
	s_mov_b32 m0, s82
	ds_read_b128 v[212:215], v144 offset:16384
	ds_read_b128 v[216:219], v144 offset:17408
	ds_read_b128 v[220:223], v144 offset:18432
	ds_read_b128 v[224:227], v144 offset:19456
	ds_read_b128 v[228:231], v144 offset:20480
	ds_read_b128 v[232:235], v144 offset:21504
	ds_read_b128 v[236:239], v144 offset:22528
	ds_read_b128 v[240:243], v144 offset:23552
	global_load_lds_dwordx4 v[154:155], off
	s_add_i32 m0, s82, 0x2000
	s_add_u32 s82, s52, 0x20000
	v_lshl_add_u64 v[176:177], s[52:53], 0, v[134:135]
	s_addc_u32 s83, s53, 0
	s_add_i32 s93, s7, s85
	global_load_lds_dwordx4 v[176:177], off
	v_lshl_add_u64 v[178:179], s[82:83], 0, v[132:133]
	s_mov_b32 m0, s93
	v_lshl_add_u64 v[194:195], s[54:55], 0, v[2:3]
	global_load_lds_dwordx4 v[178:179], off
	v_lshl_add_u64 v[178:179], s[82:83], 0, v[134:135]
	s_add_i32 m0, s93, 0x2000
	s_nop 0
	global_load_lds_dwordx4 v[178:179], off
	v_lshl_add_u64 v[178:179], s[54:55], 0, v[0:1]
	s_mov_b32 m0, s87
	s_nop 0
	global_load_lds_dwordx4 v[178:179], off
	s_add_i32 m0, s87, 0x2000
	s_nop 0
	global_load_lds_dwordx4 v[194:195], off
	s_waitcnt vmcnt(8)
	s_waitcnt lgkmcnt(0)
	s_barrier
	s_setprio 1
	s_waitcnt lgkmcnt(0)
	v_mfma_f32_16x16x32_bf16 v[64:67], v[146:149], v[212:215], v[64:67]
	v_mfma_f32_16x16x32_bf16 v[60:63], v[158:161], v[212:215], v[60:63]
	v_mfma_f32_16x16x32_bf16 v[48:51], v[146:149], v[220:223], v[48:51]
	v_mfma_f32_16x16x32_bf16 v[44:47], v[158:161], v[220:223], v[44:47]
	s_setprio 0
	s_setprio 1
	v_mfma_f32_16x16x32_bf16 v[32:35], v[146:149], v[228:231], v[32:35]
	v_mfma_f32_16x16x32_bf16 v[28:31], v[158:161], v[228:231], v[28:31]
	v_mfma_f32_16x16x32_bf16 v[16:19], v[146:149], v[236:239], v[16:19]
	v_mfma_f32_16x16x32_bf16 v[12:15], v[158:161], v[236:239], v[12:15]
	s_setprio 0
	s_setprio 1
	v_mfma_f32_16x16x32_bf16 v[64:67], v[150:153], v[216:219], v[64:67]
	v_mfma_f32_16x16x32_bf16 v[60:63], v[162:165], v[216:219], v[60:63]
	v_mfma_f32_16x16x32_bf16 v[48:51], v[150:153], v[224:227], v[48:51]
	v_mfma_f32_16x16x32_bf16 v[44:47], v[162:165], v[224:227], v[44:47]
	s_setprio 0
	s_setprio 1
	v_mfma_f32_16x16x32_bf16 v[32:35], v[150:153], v[232:235], v[32:35]
	v_mfma_f32_16x16x32_bf16 v[28:31], v[162:165], v[232:235], v[28:31]
	v_mfma_f32_16x16x32_bf16 v[16:19], v[150:153], v[240:243], v[16:19]
	v_mfma_f32_16x16x32_bf16 v[12:15], v[162:165], v[240:243], v[12:15]
	s_setprio 0
	s_setprio 1
	v_mfma_f32_16x16x32_bf16 v[56:59], v[196:199], v[212:215], v[56:59]
	v_mfma_f32_16x16x32_bf16 v[52:55], v[204:207], v[212:215], v[52:55]
	v_mfma_f32_16x16x32_bf16 v[40:43], v[196:199], v[220:223], v[40:43]
	v_mfma_f32_16x16x32_bf16 v[36:39], v[204:207], v[220:223], v[36:39]
	s_setprio 0
	s_setprio 1
	v_mfma_f32_16x16x32_bf16 v[24:27], v[196:199], v[228:231], v[24:27]
	v_mfma_f32_16x16x32_bf16 v[20:23], v[204:207], v[228:231], v[20:23]
	v_mfma_f32_16x16x32_bf16 v[8:11], v[196:199], v[236:239], v[8:11]
	v_mfma_f32_16x16x32_bf16 v[4:7], v[204:207], v[236:239], v[4:7]
	s_setprio 0
	s_setprio 1
	v_mfma_f32_16x16x32_bf16 v[56:59], v[200:203], v[216:219], v[56:59]
	v_mfma_f32_16x16x32_bf16 v[52:55], v[208:211], v[216:219], v[52:55]
	v_mfma_f32_16x16x32_bf16 v[40:43], v[200:203], v[224:227], v[40:43]
	v_mfma_f32_16x16x32_bf16 v[36:39], v[208:211], v[224:227], v[36:39]
	s_setprio 0
	s_setprio 1
	v_mfma_f32_16x16x32_bf16 v[24:27], v[200:203], v[232:235], v[24:27]
	v_mfma_f32_16x16x32_bf16 v[20:23], v[208:211], v[232:235], v[20:23]
	v_mfma_f32_16x16x32_bf16 v[8:11], v[200:203], v[240:243], v[8:11]
	v_mfma_f32_16x16x32_bf16 v[4:7], v[208:211], v[240:243], v[4:7]
	s_setprio 0
	s_barrier
	v_add_u32_e32 v145, s10, v143
	ds_read_b128 v[146:149], v145
	ds_read_b128 v[150:153], v145 offset:1024
	ds_read_b128 v[158:161], v145 offset:2048
	ds_read_b128 v[162:165], v145 offset:3072
	v_add_u32_e32 v145, s11, v143
	ds_read_b128 v[196:199], v145
	ds_read_b128 v[200:203], v145 offset:1024
	ds_read_b128 v[204:207], v145 offset:2048
	ds_read_b128 v[208:211], v145 offset:3072
	s_add_u32 s54, s54, 0x20000
	s_addc_u32 s55, s55, 0
	v_lshl_add_u64 v[244:245], s[54:55], 0, v[0:1]
	s_add_i32 m0, s87, 0x4000
	ds_read_b128 v[212:215], v144 offset:32768
	ds_read_b128 v[216:219], v144 offset:33792
	ds_read_b128 v[220:223], v144 offset:34816
	ds_read_b128 v[224:227], v144 offset:35840
	ds_read_b128 v[228:231], v144 offset:36864
	ds_read_b128 v[232:235], v144 offset:37888
	ds_read_b128 v[236:239], v144 offset:38912
	ds_read_b128 v[240:243], v144 offset:39936
	global_load_lds_dwordx4 v[244:245], off
	v_lshl_add_u64 v[244:245], s[54:55], 0, v[2:3]
	s_add_i32 m0, s87, 0x6000
	s_nop 0
	global_load_lds_dwordx4 v[244:245], off
	s_waitcnt vmcnt(8)
	s_waitcnt lgkmcnt(0)
	s_barrier
	s_setprio 1
	s_waitcnt lgkmcnt(0)
	v_mfma_f32_16x16x32_bf16 v[128:131], v[146:149], v[212:215], v[128:131]
	v_mfma_f32_16x16x32_bf16 v[124:127], v[158:161], v[212:215], v[124:127]
	v_mfma_f32_16x16x32_bf16 v[112:115], v[146:149], v[220:223], v[112:115]
	v_mfma_f32_16x16x32_bf16 v[108:111], v[158:161], v[220:223], v[108:111]
	s_setprio 0
	s_setprio 1
	v_mfma_f32_16x16x32_bf16 v[96:99], v[146:149], v[228:231], v[96:99]
	v_mfma_f32_16x16x32_bf16 v[92:95], v[158:161], v[228:231], v[92:95]
	v_mfma_f32_16x16x32_bf16 v[80:83], v[146:149], v[236:239], v[80:83]
	v_mfma_f32_16x16x32_bf16 v[76:79], v[158:161], v[236:239], v[76:79]
	s_setprio 0
	s_setprio 1
	v_mfma_f32_16x16x32_bf16 v[128:131], v[150:153], v[216:219], v[128:131]
	v_mfma_f32_16x16x32_bf16 v[124:127], v[162:165], v[216:219], v[124:127]
	v_mfma_f32_16x16x32_bf16 v[112:115], v[150:153], v[224:227], v[112:115]
	v_mfma_f32_16x16x32_bf16 v[108:111], v[162:165], v[224:227], v[108:111]
	s_setprio 0
	s_setprio 1
	v_mfma_f32_16x16x32_bf16 v[96:99], v[150:153], v[232:235], v[96:99]
	v_mfma_f32_16x16x32_bf16 v[92:95], v[162:165], v[232:235], v[92:95]
	v_mfma_f32_16x16x32_bf16 v[80:83], v[150:153], v[240:243], v[80:83]
	v_mfma_f32_16x16x32_bf16 v[76:79], v[162:165], v[240:243], v[76:79]
	s_setprio 0
	s_setprio 1
	v_mfma_f32_16x16x32_bf16 v[120:123], v[196:199], v[212:215], v[120:123]
	v_mfma_f32_16x16x32_bf16 v[116:119], v[204:207], v[212:215], v[116:119]
	v_mfma_f32_16x16x32_bf16 v[104:107], v[196:199], v[220:223], v[104:107]
	v_mfma_f32_16x16x32_bf16 v[100:103], v[204:207], v[220:223], v[100:103]
	s_setprio 0
	s_setprio 1
	v_mfma_f32_16x16x32_bf16 v[88:91], v[196:199], v[228:231], v[88:91]
	v_mfma_f32_16x16x32_bf16 v[84:87], v[204:207], v[228:231], v[84:87]
	v_mfma_f32_16x16x32_bf16 v[72:75], v[196:199], v[236:239], v[72:75]
	v_mfma_f32_16x16x32_bf16 v[68:71], v[204:207], v[236:239], v[68:71]
	s_setprio 0
	s_setprio 1
	v_mfma_f32_16x16x32_bf16 v[120:123], v[200:203], v[216:219], v[120:123]
	v_mfma_f32_16x16x32_bf16 v[116:119], v[208:211], v[216:219], v[116:119]
	v_mfma_f32_16x16x32_bf16 v[104:107], v[200:203], v[224:227], v[104:107]
	v_mfma_f32_16x16x32_bf16 v[100:103], v[208:211], v[224:227], v[100:103]
	s_setprio 0
	s_setprio 1
	v_mfma_f32_16x16x32_bf16 v[88:91], v[200:203], v[232:235], v[88:91]
	v_mfma_f32_16x16x32_bf16 v[84:87], v[208:211], v[232:235], v[84:87]
	v_mfma_f32_16x16x32_bf16 v[72:75], v[200:203], v[240:243], v[72:75]
	v_mfma_f32_16x16x32_bf16 v[68:71], v[208:211], v[240:243], v[68:71]
	s_setprio 0
	s_barrier
	s_add_i32 s54, s10, s85
	v_lshl_add_u64 v[154:155], v[154:155], 0, s[24:25]
	s_mov_b32 m0, s54
	ds_read_b128 v[212:215], v144 offset:49152
	ds_read_b128 v[216:219], v144 offset:50176
	ds_read_b128 v[220:223], v144 offset:51200
	ds_read_b128 v[224:227], v144 offset:52224
	ds_read_b128 v[228:231], v144 offset:53248
	ds_read_b128 v[232:235], v144 offset:54272
	ds_read_b128 v[236:239], v144 offset:55296
	ds_read_b128 v[240:243], v144 offset:56320
	global_load_lds_dwordx4 v[154:155], off
	s_add_i32 m0, s54, 0x2000
	s_add_u32 s52, s52, 0x20080
	v_lshl_add_u64 v[154:155], v[176:177], 0, s[24:25]
	s_addc_u32 s53, s53, 0
	s_add_i32 s54, s11, s85
	global_load_lds_dwordx4 v[154:155], off
	v_lshl_add_u64 v[154:155], s[52:53], 0, v[132:133]
	s_mov_b32 m0, s54
	s_nop 0
	global_load_lds_dwordx4 v[154:155], off
	v_lshl_add_u64 v[154:155], s[52:53], 0, v[134:135]
	s_add_i32 m0, s54, 0x2000
	s_nop 0
	global_load_lds_dwordx4 v[154:155], off
	v_lshl_add_u64 v[154:155], v[178:179], 0, s[24:25]
	s_add_i32 m0, s87, 0x8000
	s_nop 0
	global_load_lds_dwordx4 v[154:155], off
	v_lshl_add_u64 v[154:155], v[194:195], 0, s[24:25]
	s_add_i32 m0, s87, 0xa000
	s_nop 0
	global_load_lds_dwordx4 v[154:155], off
	s_waitcnt vmcnt(8)
	s_waitcnt lgkmcnt(0)
	s_barrier
	s_setprio 1
	s_waitcnt lgkmcnt(0)
	v_mfma_f32_16x16x32_bf16 v[64:67], v[146:149], v[212:215], v[64:67]
	v_mfma_f32_16x16x32_bf16 v[60:63], v[158:161], v[212:215], v[60:63]
	v_mfma_f32_16x16x32_bf16 v[48:51], v[146:149], v[220:223], v[48:51]
	v_mfma_f32_16x16x32_bf16 v[44:47], v[158:161], v[220:223], v[44:47]
	s_setprio 0
	s_setprio 1
	v_mfma_f32_16x16x32_bf16 v[32:35], v[146:149], v[228:231], v[32:35]
	v_mfma_f32_16x16x32_bf16 v[28:31], v[158:161], v[228:231], v[28:31]
	v_mfma_f32_16x16x32_bf16 v[16:19], v[146:149], v[236:239], v[16:19]
	v_mfma_f32_16x16x32_bf16 v[12:15], v[158:161], v[236:239], v[12:15]
	s_setprio 0
	s_setprio 1
	v_mfma_f32_16x16x32_bf16 v[64:67], v[150:153], v[216:219], v[64:67]
	v_mfma_f32_16x16x32_bf16 v[60:63], v[162:165], v[216:219], v[60:63]
	v_mfma_f32_16x16x32_bf16 v[48:51], v[150:153], v[224:227], v[48:51]
	v_mfma_f32_16x16x32_bf16 v[44:47], v[162:165], v[224:227], v[44:47]
	s_setprio 0
	s_setprio 1
	v_mfma_f32_16x16x32_bf16 v[32:35], v[150:153], v[232:235], v[32:35]
	v_mfma_f32_16x16x32_bf16 v[28:31], v[162:165], v[232:235], v[28:31]
	v_mfma_f32_16x16x32_bf16 v[16:19], v[150:153], v[240:243], v[16:19]
	v_mfma_f32_16x16x32_bf16 v[12:15], v[162:165], v[240:243], v[12:15]
	s_setprio 0
	s_setprio 1
	v_mfma_f32_16x16x32_bf16 v[56:59], v[196:199], v[212:215], v[56:59]
	v_mfma_f32_16x16x32_bf16 v[52:55], v[204:207], v[212:215], v[52:55]
	v_mfma_f32_16x16x32_bf16 v[40:43], v[196:199], v[220:223], v[40:43]
	v_mfma_f32_16x16x32_bf16 v[36:39], v[204:207], v[220:223], v[36:39]
	s_setprio 0
	s_setprio 1
	v_mfma_f32_16x16x32_bf16 v[24:27], v[196:199], v[228:231], v[24:27]
	v_mfma_f32_16x16x32_bf16 v[20:23], v[204:207], v[228:231], v[20:23]
	v_mfma_f32_16x16x32_bf16 v[8:11], v[196:199], v[236:239], v[8:11]
	v_mfma_f32_16x16x32_bf16 v[4:7], v[204:207], v[236:239], v[4:7]
	s_setprio 0
	s_setprio 1
	v_mfma_f32_16x16x32_bf16 v[56:59], v[200:203], v[216:219], v[56:59]
	v_mfma_f32_16x16x32_bf16 v[52:55], v[208:211], v[216:219], v[52:55]
	v_mfma_f32_16x16x32_bf16 v[40:43], v[200:203], v[224:227], v[40:43]
	v_mfma_f32_16x16x32_bf16 v[36:39], v[208:211], v[224:227], v[36:39]
	s_setprio 0
	s_setprio 1
	v_mfma_f32_16x16x32_bf16 v[24:27], v[200:203], v[232:235], v[24:27]
	v_mfma_f32_16x16x32_bf16 v[20:23], v[208:211], v[232:235], v[20:23]
	v_mfma_f32_16x16x32_bf16 v[8:11], v[200:203], v[240:243], v[8:11]
	v_mfma_f32_16x16x32_bf16 v[4:7], v[208:211], v[240:243], v[4:7]
	s_setprio 0
	s_barrier
	s_add_i32 s86, s86, 2
	s_add_u32 s40, s40, 0x100
	s_addc_u32 s41, s41, 0
	s_cmp_gt_u32 s86, 5
	s_cbranch_scc0 .LBB0_341
	s_cmp_eq_u32 s20, 2
	s_movk_i32 s58, 0x21ff
	s_mov_b64 s[8:9], 0x800
	s_mov_b64 s[18:19], 0x200
	s_cbranch_scc0 .LBB0_346
	s_waitcnt vmcnt(0)
	s_cmpk_gt_u32 s67, 0xff
	s_cbranch_scc1 .LBB0_345
	s_barrier

.LBB0_465:
	s_add_u32 s17, s18, 0xf1598080
	s_addc_u32 s20, s19, -1
	s_cmp_lg_u32 s16, 4
	s_cselect_b32 s17, s17, 0
	s_cselect_b32 s20, s20, 0
	s_add_u32 s42, s2, s17
	s_addc_u32 s43, s3, s20
	s_add_i32 s48, 0, 0x10000
	s_add_u32 s40, s8, s17
	v_add_u32_e32 v143, s48, v141
	s_addc_u32 s41, s9, s20
	s_add_i32 s17, 0, 0x14000
	ds_read_b128 v[144:147], v143
	ds_read_b128 v[148:151], v143 offset:1024
	ds_read_b128 v[152:155], v143 offset:2048
	ds_read_b128 v[158:161], v143 offset:3072
	v_add_u32_e32 v143, s17, v141
	ds_read_b128 v[162:165], v143
	ds_read_b128 v[196:199], v143 offset:1024
	ds_read_b128 v[200:203], v143 offset:2048
	ds_read_b128 v[204:207], v143 offset:3072
	v_lshl_add_u64 v[240:241], v[138:139], 0, s[18:19]
	s_add_i32 m0, s6, 0xc000
	ds_read_b128 v[208:211], v142
	ds_read_b128 v[212:215], v142 offset:1024
	ds_read_b128 v[216:219], v142 offset:2048
	ds_read_b128 v[220:223], v142 offset:3072
	ds_read_b128 v[224:227], v142 offset:4096
	ds_read_b128 v[228:231], v142 offset:5120
	ds_read_b128 v[232:235], v142 offset:6144
	ds_read_b128 v[236:239], v142 offset:7168
	global_load_lds_dwordx4 v[240:241], off
	v_lshl_add_u64 v[240:241], v[136:137], 0, s[18:19]
	s_add_i32 m0, s6, 0xe000
	s_nop 0
	global_load_lds_dwordx4 v[240:241], off
	s_waitcnt vmcnt(8)
	s_waitcnt lgkmcnt(0)
	s_barrier
	s_setprio 1
	s_waitcnt lgkmcnt(0)
	v_mfma_f32_16x16x32_bf16 v[126:129], v[144:147], v[208:211], v[126:129]
	v_mfma_f32_16x16x32_bf16 v[122:125], v[152:155], v[208:211], v[122:125]
	v_mfma_f32_16x16x32_bf16 v[110:113], v[144:147], v[216:219], v[110:113]
	v_mfma_f32_16x16x32_bf16 v[106:109], v[152:155], v[216:219], v[106:109]
	s_setprio 0
	s_setprio 1
	v_mfma_f32_16x16x32_bf16 v[94:97], v[144:147], v[224:227], v[94:97]
	v_mfma_f32_16x16x32_bf16 v[90:93], v[152:155], v[224:227], v[90:93]
	v_mfma_f32_16x16x32_bf16 v[78:81], v[144:147], v[232:235], v[78:81]
	v_mfma_f32_16x16x32_bf16 v[74:77], v[152:155], v[232:235], v[74:77]
	s_setprio 0
	s_setprio 1
	v_mfma_f32_16x16x32_bf16 v[126:129], v[148:151], v[212:215], v[126:129]
	v_mfma_f32_16x16x32_bf16 v[122:125], v[158:161], v[212:215], v[122:125]
	v_mfma_f32_16x16x32_bf16 v[110:113], v[148:151], v[220:223], v[110:113]
	v_mfma_f32_16x16x32_bf16 v[106:109], v[158:161], v[220:223], v[106:109]
	s_setprio 0
	s_setprio 1
	v_mfma_f32_16x16x32_bf16 v[94:97], v[148:151], v[228:231], v[94:97]
	v_mfma_f32_16x16x32_bf16 v[90:93], v[158:161], v[228:231], v[90:93]
	v_mfma_f32_16x16x32_bf16 v[78:81], v[148:151], v[236:239], v[78:81]
	v_mfma_f32_16x16x32_bf16 v[74:77], v[158:161], v[236:239], v[74:77]
	s_setprio 0
	s_setprio 1
	v_mfma_f32_16x16x32_bf16 v[118:121], v[162:165], v[208:211], v[118:121]
	v_mfma_f32_16x16x32_bf16 v[114:117], v[200:203], v[208:211], v[114:117]
	v_mfma_f32_16x16x32_bf16 v[102:105], v[162:165], v[216:219], v[102:105]
	v_mfma_f32_16x16x32_bf16 v[98:101], v[200:203], v[216:219], v[98:101]
	s_setprio 0
	s_setprio 1
	v_mfma_f32_16x16x32_bf16 v[86:89], v[162:165], v[224:227], v[86:89]
	v_mfma_f32_16x16x32_bf16 v[82:85], v[200:203], v[224:227], v[82:85]
	v_mfma_f32_16x16x32_bf16 v[70:73], v[162:165], v[232:235], v[70:73]
	v_mfma_f32_16x16x32_bf16 v[66:69], v[200:203], v[232:235], v[66:69]
	s_setprio 0
	s_setprio 1
	v_mfma_f32_16x16x32_bf16 v[118:121], v[196:199], v[212:215], v[118:121]
	v_mfma_f32_16x16x32_bf16 v[114:117], v[204:207], v[212:215], v[114:117]
	v_mfma_f32_16x16x32_bf16 v[102:105], v[196:199], v[220:223], v[102:105]
	v_mfma_f32_16x16x32_bf16 v[98:101], v[204:207], v[220:223], v[98:101]
	s_setprio 0
	s_setprio 1
	v_mfma_f32_16x16x32_bf16 v[86:89], v[196:199], v[228:231], v[86:89]
	v_mfma_f32_16x16x32_bf16 v[82:85], v[204:207], v[228:231], v[82:85]
	v_mfma_f32_16x16x32_bf16 v[70:73], v[196:199], v[236:239], v[70:73]
	v_mfma_f32_16x16x32_bf16 v[66:69], v[204:207], v[236:239], v[66:69]
	s_setprio 0
	s_barrier
	s_add_i32 s20, s48, s5
	v_lshl_add_u64 v[240:241], s[40:41], 0, v[0:1]
	s_mov_b32 m0, s20
	ds_read_b128 v[208:211], v142 offset:16384
	ds_read_b128 v[212:215], v142 offset:17408
	ds_read_b128 v[216:219], v142 offset:18432
	ds_read_b128 v[220:223], v142 offset:19456
	ds_read_b128 v[224:227], v142 offset:20480
	ds_read_b128 v[228:231], v142 offset:21504
	ds_read_b128 v[232:235], v142 offset:22528
	ds_read_b128 v[236:239], v142 offset:23552
	global_load_lds_dwordx4 v[240:241], off
	s_add_i32 m0, s20, 0x2000
	s_add_u32 s48, s40, 0x20000
	v_lshl_add_u64 v[242:243], s[40:41], 0, v[134:135]
	s_addc_u32 s49, s41, 0
	s_add_i32 s17, s17, s5
	global_load_lds_dwordx4 v[242:243], off
	v_lshl_add_u64 v[244:245], s[48:49], 0, v[0:1]
	s_mov_b32 m0, s17
	v_lshl_add_u64 v[246:247], s[42:43], 0, v[132:133]
	global_load_lds_dwordx4 v[244:245], off
	v_lshl_add_u64 v[244:245], s[48:49], 0, v[134:135]
	s_add_i32 m0, s17, 0x2000
	s_nop 0
	global_load_lds_dwordx4 v[244:245], off
	v_lshl_add_u64 v[244:245], s[42:43], 0, v[130:131]
	s_mov_b32 m0, s6
	s_nop 0
	global_load_lds_dwordx4 v[244:245], off
	s_mov_b32 m0, s7
	s_nop 0
	global_load_lds_dwordx4 v[246:247], off
	s_waitcnt vmcnt(8)
	s_waitcnt lgkmcnt(0)
	s_barrier
	s_setprio 1
	s_waitcnt lgkmcnt(0)
	v_mfma_f32_16x16x32_bf16 v[62:65], v[144:147], v[208:211], v[62:65]
	v_mfma_f32_16x16x32_bf16 v[58:61], v[152:155], v[208:211], v[58:61]
	v_mfma_f32_16x16x32_bf16 v[46:49], v[144:147], v[216:219], v[46:49]
	v_mfma_f32_16x16x32_bf16 v[42:45], v[152:155], v[216:219], v[42:45]
	s_setprio 0
	s_setprio 1
	v_mfma_f32_16x16x32_bf16 v[30:33], v[144:147], v[224:227], v[30:33]
	v_mfma_f32_16x16x32_bf16 v[26:29], v[152:155], v[224:227], v[26:29]
	v_mfma_f32_16x16x32_bf16 v[14:17], v[144:147], v[232:235], v[14:17]
	v_mfma_f32_16x16x32_bf16 v[10:13], v[152:155], v[232:235], v[10:13]
	s_setprio 0
	s_setprio 1
	v_mfma_f32_16x16x32_bf16 v[62:65], v[148:151], v[212:215], v[62:65]
	v_mfma_f32_16x16x32_bf16 v[58:61], v[158:161], v[212:215], v[58:61]
	v_mfma_f32_16x16x32_bf16 v[46:49], v[148:151], v[220:223], v[46:49]
	v_mfma_f32_16x16x32_bf16 v[42:45], v[158:161], v[220:223], v[42:45]
	s_setprio 0
	s_setprio 1
	v_mfma_f32_16x16x32_bf16 v[30:33], v[148:151], v[228:231], v[30:33]
	v_mfma_f32_16x16x32_bf16 v[26:29], v[158:161], v[228:231], v[26:29]
	v_mfma_f32_16x16x32_bf16 v[14:17], v[148:151], v[236:239], v[14:17]
	v_mfma_f32_16x16x32_bf16 v[10:13], v[158:161], v[236:239], v[10:13]
	s_setprio 0
	s_setprio 1
	v_mfma_f32_16x16x32_bf16 v[54:57], v[162:165], v[208:211], v[54:57]
	v_mfma_f32_16x16x32_bf16 v[50:53], v[200:203], v[208:211], v[50:53]
	v_mfma_f32_16x16x32_bf16 v[38:41], v[162:165], v[216:219], v[38:41]
	v_mfma_f32_16x16x32_bf16 v[34:37], v[200:203], v[216:219], v[34:37]
	s_setprio 0
	s_setprio 1
	v_mfma_f32_16x16x32_bf16 v[22:25], v[162:165], v[224:227], v[22:25]
	v_mfma_f32_16x16x32_bf16 v[18:21], v[200:203], v[224:227], v[18:21]
	v_mfma_f32_16x16x32_bf16 v[6:9], v[162:165], v[232:235], v[6:9]
	v_mfma_f32_16x16x32_bf16 v[2:5], v[200:203], v[232:235], v[2:5]
	s_setprio 0
	s_setprio 1
	v_mfma_f32_16x16x32_bf16 v[54:57], v[196:199], v[212:215], v[54:57]
	v_mfma_f32_16x16x32_bf16 v[50:53], v[204:207], v[212:215], v[50:53]
	v_mfma_f32_16x16x32_bf16 v[38:41], v[196:199], v[220:223], v[38:41]
	v_mfma_f32_16x16x32_bf16 v[34:37], v[204:207], v[220:223], v[34:37]
	s_setprio 0
	s_setprio 1
	v_mfma_f32_16x16x32_bf16 v[22:25], v[196:199], v[228:231], v[22:25]
	v_mfma_f32_16x16x32_bf16 v[18:21], v[204:207], v[228:231], v[18:21]
	v_mfma_f32_16x16x32_bf16 v[6:9], v[196:199], v[236:239], v[6:9]
	v_mfma_f32_16x16x32_bf16 v[2:5], v[204:207], v[236:239], v[2:5]
	s_setprio 0
	s_barrier
	s_add_i32 s17, 0, 0x18000
	v_add_u32_e32 v143, s17, v141
	s_add_i32 s20, 0, 0x1c000
	ds_read_b128 v[144:147], v143
	ds_read_b128 v[148:151], v143 offset:1024
	ds_read_b128 v[152:155], v143 offset:2048
	ds_read_b128 v[158:161], v143 offset:3072
	v_add_u32_e32 v143, s20, v141
	ds_read_b128 v[162:165], v143
	ds_read_b128 v[196:199], v143 offset:1024
	ds_read_b128 v[200:203], v143 offset:2048
	ds_read_b128 v[204:207], v143 offset:3072
	s_add_u32 s42, s42, 0x20000
	s_addc_u32 s43, s43, 0
	s_mov_b32 m0, s10
	v_lshl_add_u64 v[248:249], s[42:43], 0, v[130:131]
	ds_read_b128 v[208:211], v142 offset:32768
	ds_read_b128 v[212:215], v142 offset:33792
	ds_read_b128 v[216:219], v142 offset:34816
	ds_read_b128 v[220:223], v142 offset:35840
	ds_read_b128 v[224:227], v142 offset:36864
	ds_read_b128 v[228:231], v142 offset:37888
	ds_read_b128 v[232:235], v142 offset:38912
	ds_read_b128 v[236:239], v142 offset:39936
	global_load_lds_dwordx4 v[248:249], off
	v_lshl_add_u64 v[248:249], s[42:43], 0, v[132:133]
	s_mov_b32 m0, s11
	s_nop 0
	global_load_lds_dwordx4 v[248:249], off
	s_waitcnt vmcnt(8)
	s_waitcnt lgkmcnt(0)
	s_barrier
	s_setprio 1
	s_waitcnt lgkmcnt(0)
	v_mfma_f32_16x16x32_bf16 v[126:129], v[144:147], v[208:211], v[126:129]
	v_mfma_f32_16x16x32_bf16 v[122:125], v[152:155], v[208:211], v[122:125]
	v_mfma_f32_16x16x32_bf16 v[110:113], v[144:147], v[216:219], v[110:113]
	v_mfma_f32_16x16x32_bf16 v[106:109], v[152:155], v[216:219], v[106:109]
	s_setprio 0
	s_setprio 1
	v_mfma_f32_16x16x32_bf16 v[94:97], v[144:147], v[224:227], v[94:97]
	v_mfma_f32_16x16x32_bf16 v[90:93], v[152:155], v[224:227], v[90:93]
	v_mfma_f32_16x16x32_bf16 v[78:81], v[144:147], v[232:235], v[78:81]
	v_mfma_f32_16x16x32_bf16 v[74:77], v[152:155], v[232:235], v[74:77]
	s_setprio 0
	s_setprio 1
	v_mfma_f32_16x16x32_bf16 v[126:129], v[148:151], v[212:215], v[126:129]
	v_mfma_f32_16x16x32_bf16 v[122:125], v[158:161], v[212:215], v[122:125]
	v_mfma_f32_16x16x32_bf16 v[110:113], v[148:151], v[220:223], v[110:113]
	v_mfma_f32_16x16x32_bf16 v[106:109], v[158:161], v[220:223], v[106:109]
	s_setprio 0
	s_setprio 1
	v_mfma_f32_16x16x32_bf16 v[94:97], v[148:151], v[228:231], v[94:97]
	v_mfma_f32_16x16x32_bf16 v[90:93], v[158:161], v[228:231], v[90:93]
	v_mfma_f32_16x16x32_bf16 v[78:81], v[148:151], v[236:239], v[78:81]
	v_mfma_f32_16x16x32_bf16 v[74:77], v[158:161], v[236:239], v[74:77]
	s_setprio 0
	s_setprio 1
	v_mfma_f32_16x16x32_bf16 v[118:121], v[162:165], v[208:211], v[118:121]
	v_mfma_f32_16x16x32_bf16 v[114:117], v[200:203], v[208:211], v[114:117]
	v_mfma_f32_16x16x32_bf16 v[102:105], v[162:165], v[216:219], v[102:105]
	v_mfma_f32_16x16x32_bf16 v[98:101], v[200:203], v[216:219], v[98:101]
	s_setprio 0
	s_setprio 1
	v_mfma_f32_16x16x32_bf16 v[86:89], v[162:165], v[224:227], v[86:89]
	v_mfma_f32_16x16x32_bf16 v[82:85], v[200:203], v[224:227], v[82:85]
	v_mfma_f32_16x16x32_bf16 v[70:73], v[162:165], v[232:235], v[70:73]
	v_mfma_f32_16x16x32_bf16 v[66:69], v[200:203], v[232:235], v[66:69]
	s_setprio 0
	s_setprio 1
	v_mfma_f32_16x16x32_bf16 v[118:121], v[196:199], v[212:215], v[118:121]
	v_mfma_f32_16x16x32_bf16 v[114:117], v[204:207], v[212:215], v[114:117]
	v_mfma_f32_16x16x32_bf16 v[102:105], v[196:199], v[220:223], v[102:105]
	v_mfma_f32_16x16x32_bf16 v[98:101], v[204:207], v[220:223], v[98:101]
	s_setprio 0
	s_setprio 1
	v_mfma_f32_16x16x32_bf16 v[86:89], v[196:199], v[228:231], v[86:89]
	v_mfma_f32_16x16x32_bf16 v[82:85], v[204:207], v[228:231], v[82:85]
	v_mfma_f32_16x16x32_bf16 v[70:73], v[196:199], v[236:239], v[70:73]
	v_mfma_f32_16x16x32_bf16 v[66:69], v[204:207], v[236:239], v[66:69]
	s_setprio 0
	s_barrier
	s_add_i32 s17, s17, s5
	v_lshl_add_u64 v[240:241], v[240:241], 0, s[24:25]
	s_mov_b32 m0, s17
	ds_read_b128 v[208:211], v142 offset:49152
	ds_read_b128 v[212:215], v142 offset:50176
	ds_read_b128 v[216:219], v142 offset:51200
	ds_read_b128 v[220:223], v142 offset:52224
	ds_read_b128 v[224:227], v142 offset:53248
	ds_read_b128 v[228:231], v142 offset:54272
	ds_read_b128 v[232:235], v142 offset:55296
	ds_read_b128 v[236:239], v142 offset:56320
	global_load_lds_dwordx4 v[240:241], off
	s_add_i32 m0, s17, 0x2000
	s_add_u32 s40, s40, 0x20080
	v_lshl_add_u64 v[240:241], v[242:243], 0, s[24:25]
	s_addc_u32 s41, s41, 0
	s_add_i32 s17, s20, s5
	global_load_lds_dwordx4 v[240:241], off
	v_lshl_add_u64 v[240:241], s[40:41], 0, v[0:1]
	s_mov_b32 m0, s17
	s_nop 0
	global_load_lds_dwordx4 v[240:241], off
	v_lshl_add_u64 v[240:241], s[40:41], 0, v[134:135]
	s_add_i32 m0, s17, 0x2000
	s_nop 0
	global_load_lds_dwordx4 v[240:241], off
	v_lshl_add_u64 v[240:241], v[244:245], 0, s[24:25]
	s_mov_b32 m0, s12
	s_nop 0
	global_load_lds_dwordx4 v[240:241], off
	v_lshl_add_u64 v[240:241], v[246:247], 0, s[24:25]
	s_mov_b32 m0, s13
	s_nop 0
	global_load_lds_dwordx4 v[240:241], off
	s_waitcnt vmcnt(8)
	s_waitcnt lgkmcnt(0)
	s_barrier
	s_setprio 1
	s_waitcnt lgkmcnt(0)
	v_mfma_f32_16x16x32_bf16 v[62:65], v[144:147], v[208:211], v[62:65]
	v_mfma_f32_16x16x32_bf16 v[58:61], v[152:155], v[208:211], v[58:61]
	v_mfma_f32_16x16x32_bf16 v[46:49], v[144:147], v[216:219], v[46:49]
	v_mfma_f32_16x16x32_bf16 v[42:45], v[152:155], v[216:219], v[42:45]
	s_setprio 0
	s_setprio 1
	v_mfma_f32_16x16x32_bf16 v[30:33], v[144:147], v[224:227], v[30:33]
	v_mfma_f32_16x16x32_bf16 v[26:29], v[152:155], v[224:227], v[26:29]
	v_mfma_f32_16x16x32_bf16 v[14:17], v[144:147], v[232:235], v[14:17]
	v_mfma_f32_16x16x32_bf16 v[10:13], v[152:155], v[232:235], v[10:13]
	s_setprio 0
	s_setprio 1
	v_mfma_f32_16x16x32_bf16 v[62:65], v[148:151], v[212:215], v[62:65]
	v_mfma_f32_16x16x32_bf16 v[58:61], v[158:161], v[212:215], v[58:61]
	v_mfma_f32_16x16x32_bf16 v[46:49], v[148:151], v[220:223], v[46:49]
	v_mfma_f32_16x16x32_bf16 v[42:45], v[158:161], v[220:223], v[42:45]
	s_setprio 0
	s_setprio 1
	v_mfma_f32_16x16x32_bf16 v[30:33], v[148:151], v[228:231], v[30:33]
	v_mfma_f32_16x16x32_bf16 v[26:29], v[158:161], v[228:231], v[26:29]
	v_mfma_f32_16x16x32_bf16 v[14:17], v[148:151], v[236:239], v[14:17]
	v_mfma_f32_16x16x32_bf16 v[10:13], v[158:161], v[236:239], v[10:13]
	s_setprio 0
	s_setprio 1
	v_mfma_f32_16x16x32_bf16 v[54:57], v[162:165], v[208:211], v[54:57]
	v_mfma_f32_16x16x32_bf16 v[50:53], v[200:203], v[208:211], v[50:53]
	v_mfma_f32_16x16x32_bf16 v[38:41], v[162:165], v[216:219], v[38:41]
	v_mfma_f32_16x16x32_bf16 v[34:37], v[200:203], v[216:219], v[34:37]
	s_setprio 0
	s_setprio 1
	v_mfma_f32_16x16x32_bf16 v[22:25], v[162:165], v[224:227], v[22:25]
	v_mfma_f32_16x16x32_bf16 v[18:21], v[200:203], v[224:227], v[18:21]
	v_mfma_f32_16x16x32_bf16 v[6:9], v[162:165], v[232:235], v[6:9]
	v_mfma_f32_16x16x32_bf16 v[2:5], v[200:203], v[232:235], v[2:5]
	s_setprio 0
	s_setprio 1
	v_mfma_f32_16x16x32_bf16 v[54:57], v[196:199], v[212:215], v[54:57]
	v_mfma_f32_16x16x32_bf16 v[50:53], v[204:207], v[212:215], v[50:53]
	v_mfma_f32_16x16x32_bf16 v[38:41], v[196:199], v[220:223], v[38:41]
	v_mfma_f32_16x16x32_bf16 v[34:37], v[204:207], v[220:223], v[34:37]
	s_setprio 0
	s_setprio 1
	v_mfma_f32_16x16x32_bf16 v[22:25], v[196:199], v[228:231], v[22:25]
	v_mfma_f32_16x16x32_bf16 v[18:21], v[204:207], v[228:231], v[18:21]
	v_mfma_f32_16x16x32_bf16 v[6:9], v[196:199], v[236:239], v[6:9]
	v_mfma_f32_16x16x32_bf16 v[2:5], v[204:207], v[236:239], v[2:5]
	s_setprio 0
	s_barrier
	s_add_i32 s16, s16, 2
	s_add_u32 s18, s18, 0x100
	s_addc_u32 s19, s19, 0
	s_cmp_gt_u32 s16, 5
	s_cbranch_scc0 .LBB0_465
	s_waitcnt vmcnt(0)
	s_cmpk_lt_u32 s1, 0x100
	s_cbranch_scc0 .LBB0_461
	s_barrier
	s_branch .LBB0_461

.LBB0_476:
	s_add_i32 s6, s20, 0x100
	s_and_b64 s[4:5], s[46:47], exec
	s_cselect_b32 s6, 0, s6
	s_cselect_b32 s5, 0, 0
	s_add_u32 s50, s2, s6
	s_addc_u32 s51, s3, s5
	s_add_i32 s4, 0, 0x10000
	s_add_u32 s52, s40, s6
	s_addc_u32 s53, s41, s5
	s_add_i32 s5, 0, 0x14000
	s_add_u32 s56, s42, s20
	s_addc_u32 s57, s43, 0
	s_add_i32 s85, s4, s11
	s_add_i32 m0, s12, 0xc000
	s_add_i32 s86, s12, 0xe000
	s_add_i32 s67, s85, 0x2000
	s_add_u32 s54, s52, 0x20000
	v_add_u32_e32 v142, s4, v140
	s_addc_u32 s55, s53, 0
	s_add_i32 s84, s5, s11
	ds_read_b128 v[146:149], v142
	ds_read_b128 v[150:153], v142 offset:1024
	ds_read_b128 v[158:161], v142 offset:2048
	ds_read_b128 v[162:165], v142 offset:3072
	v_add_u32_e32 v142, s5, v140
	s_add_i32 s70, s84, 0x2000
	s_add_i32 s6, 0, 0x18000
	s_add_i32 s7, 0, 0x1c000
	ds_read_b128 v[196:199], v142
	ds_read_b128 v[200:203], v142 offset:1024
	ds_read_b128 v[204:207], v142 offset:2048
	ds_read_b128 v[208:211], v142 offset:3072
	s_add_u32 s48, s50, 0x10000
	s_addc_u32 s49, s51, 0
	s_add_i32 s66, s6, s11
	s_add_i32 s63, s66, 0x2000
	s_add_u32 s46, s52, 0x20080
	s_addc_u32 s47, s53, 0
	s_add_i32 s65, s7, s11
	s_add_i32 s20, s65, 0x2000
	v_lshl_add_u64 v[142:143], s[56:57], 0, v[26:27]
	v_lshl_add_u64 v[142:143], v[142:143], 0, s[24:25]
	ds_read_b128 v[212:215], v141
	ds_read_b128 v[216:219], v141 offset:1024
	ds_read_b128 v[220:223], v141 offset:2048
	ds_read_b128 v[224:227], v141 offset:3072
	ds_read_b128 v[228:231], v141 offset:4096
	ds_read_b128 v[232:235], v141 offset:5120
	ds_read_b128 v[236:239], v141 offset:6144
	ds_read_b128 v[240:243], v141 offset:7168
	global_load_lds_dwordx4 v[142:143], off
	v_lshl_add_u64 v[142:143], s[56:57], 0, v[28:29]
	v_lshl_add_u64 v[142:143], v[142:143], 0, s[24:25]
	s_mov_b32 m0, s86
	s_nop 0
	global_load_lds_dwordx4 v[142:143], off
	s_waitcnt vmcnt(8)
	s_waitcnt lgkmcnt(0)
	s_barrier
	s_setprio 1
	s_waitcnt lgkmcnt(0)
	v_mfma_f32_16x16x32_bf16 v[134:137], v[146:149], v[212:215], v[134:137]
	v_mfma_f32_16x16x32_bf16 v[130:133], v[158:161], v[212:215], v[130:133]
	v_mfma_f32_16x16x32_bf16 v[118:121], v[146:149], v[220:223], v[118:121]
	v_mfma_f32_16x16x32_bf16 v[114:117], v[158:161], v[220:223], v[114:117]
	s_setprio 0
	s_setprio 1
	v_mfma_f32_16x16x32_bf16 v[102:105], v[146:149], v[228:231], v[102:105]
	v_mfma_f32_16x16x32_bf16 v[98:101], v[158:161], v[228:231], v[98:101]
	v_mfma_f32_16x16x32_bf16 v[86:89], v[146:149], v[236:239], v[86:89]
	v_mfma_f32_16x16x32_bf16 v[82:85], v[158:161], v[236:239], v[82:85]
	s_setprio 0
	s_setprio 1
	v_mfma_f32_16x16x32_bf16 v[134:137], v[150:153], v[216:219], v[134:137]
	v_mfma_f32_16x16x32_bf16 v[130:133], v[162:165], v[216:219], v[130:133]
	v_mfma_f32_16x16x32_bf16 v[118:121], v[150:153], v[224:227], v[118:121]
	v_mfma_f32_16x16x32_bf16 v[114:117], v[162:165], v[224:227], v[114:117]
	s_setprio 0
	s_setprio 1
	v_mfma_f32_16x16x32_bf16 v[102:105], v[150:153], v[232:235], v[102:105]
	v_mfma_f32_16x16x32_bf16 v[98:101], v[162:165], v[232:235], v[98:101]
	v_mfma_f32_16x16x32_bf16 v[86:89], v[150:153], v[240:243], v[86:89]
	v_mfma_f32_16x16x32_bf16 v[82:85], v[162:165], v[240:243], v[82:85]
	s_setprio 0
	s_setprio 1
	v_mfma_f32_16x16x32_bf16 v[126:129], v[196:199], v[212:215], v[126:129]
	v_mfma_f32_16x16x32_bf16 v[122:125], v[204:207], v[212:215], v[122:125]
	v_mfma_f32_16x16x32_bf16 v[110:113], v[196:199], v[220:223], v[110:113]
	v_mfma_f32_16x16x32_bf16 v[106:109], v[204:207], v[220:223], v[106:109]
	s_setprio 0
	s_setprio 1
	v_mfma_f32_16x16x32_bf16 v[94:97], v[196:199], v[228:231], v[94:97]
	v_mfma_f32_16x16x32_bf16 v[90:93], v[204:207], v[228:231], v[90:93]
	v_mfma_f32_16x16x32_bf16 v[78:81], v[196:199], v[236:239], v[78:81]
	v_mfma_f32_16x16x32_bf16 v[74:77], v[204:207], v[236:239], v[74:77]
	s_setprio 0
	s_setprio 1
	v_mfma_f32_16x16x32_bf16 v[126:129], v[200:203], v[216:219], v[126:129]
	v_mfma_f32_16x16x32_bf16 v[122:125], v[208:211], v[216:219], v[122:125]
	v_mfma_f32_16x16x32_bf16 v[110:113], v[200:203], v[224:227], v[110:113]
	v_mfma_f32_16x16x32_bf16 v[106:109], v[208:211], v[224:227], v[106:109]
	s_setprio 0
	s_setprio 1
	v_mfma_f32_16x16x32_bf16 v[94:97], v[200:203], v[232:235], v[94:97]
	v_mfma_f32_16x16x32_bf16 v[90:93], v[208:211], v[232:235], v[90:93]
	v_mfma_f32_16x16x32_bf16 v[78:81], v[200:203], v[240:243], v[78:81]
	v_mfma_f32_16x16x32_bf16 v[74:77], v[208:211], v[240:243], v[74:77]
	s_setprio 0
	s_barrier
	s_mov_b32 m0, s85
	v_lshl_add_u64 v[142:143], s[52:53], 0, v[0:1]
	ds_read_b128 v[212:215], v141 offset:16384
	ds_read_b128 v[216:219], v141 offset:17408
	ds_read_b128 v[220:223], v141 offset:18432
	ds_read_b128 v[224:227], v141 offset:19456
	ds_read_b128 v[228:231], v141 offset:20480
	ds_read_b128 v[232:235], v141 offset:21504
	ds_read_b128 v[236:239], v141 offset:22528
	ds_read_b128 v[240:243], v141 offset:23552
	global_load_lds_dwordx4 v[142:143], off
	v_lshl_add_u64 v[154:155], s[52:53], 0, v[38:39]
	s_mov_b32 m0, s67
	v_lshl_add_u64 v[244:245], s[54:55], 0, v[0:1]
	global_load_lds_dwordx4 v[154:155], off
	s_mov_b32 m0, s84
	v_lshl_add_u64 v[246:247], s[50:51], 0, v[28:29]
	global_load_lds_dwordx4 v[244:245], off
	v_lshl_add_u64 v[244:245], s[54:55], 0, v[38:39]
	s_mov_b32 m0, s70
	s_nop 0
	global_load_lds_dwordx4 v[244:245], off
	v_lshl_add_u64 v[244:245], s[50:51], 0, v[26:27]
	s_mov_b32 m0, s12
	s_nop 0
	global_load_lds_dwordx4 v[244:245], off
	s_mov_b32 m0, s13
	s_nop 0
	global_load_lds_dwordx4 v[246:247], off
	s_waitcnt vmcnt(8)
	s_waitcnt lgkmcnt(0)
	s_barrier
	s_setprio 1
	s_waitcnt lgkmcnt(0)
	v_mfma_f32_16x16x32_bf16 v[70:73], v[146:149], v[212:215], v[70:73]
	v_mfma_f32_16x16x32_bf16 v[66:69], v[158:161], v[212:215], v[66:69]
	v_mfma_f32_16x16x32_bf16 v[54:57], v[146:149], v[220:223], v[54:57]
	v_mfma_f32_16x16x32_bf16 v[50:53], v[158:161], v[220:223], v[50:53]
	s_setprio 0
	s_setprio 1
	v_mfma_f32_16x16x32_bf16 v[34:37], v[146:149], v[228:231], v[34:37]
	v_mfma_f32_16x16x32_bf16 v[30:33], v[158:161], v[228:231], v[30:33]
	v_mfma_f32_16x16x32_bf16 v[14:17], v[146:149], v[236:239], v[14:17]
	v_mfma_f32_16x16x32_bf16 v[10:13], v[158:161], v[236:239], v[10:13]
	s_setprio 0
	s_setprio 1
	v_mfma_f32_16x16x32_bf16 v[70:73], v[150:153], v[216:219], v[70:73]
	v_mfma_f32_16x16x32_bf16 v[66:69], v[162:165], v[216:219], v[66:69]
	v_mfma_f32_16x16x32_bf16 v[54:57], v[150:153], v[224:227], v[54:57]
	v_mfma_f32_16x16x32_bf16 v[50:53], v[162:165], v[224:227], v[50:53]
	s_setprio 0
	s_setprio 1
	v_mfma_f32_16x16x32_bf16 v[34:37], v[150:153], v[232:235], v[34:37]
	v_mfma_f32_16x16x32_bf16 v[30:33], v[162:165], v[232:235], v[30:33]
	v_mfma_f32_16x16x32_bf16 v[14:17], v[150:153], v[240:243], v[14:17]
	v_mfma_f32_16x16x32_bf16 v[10:13], v[162:165], v[240:243], v[10:13]
	s_setprio 0
	s_setprio 1
	v_mfma_f32_16x16x32_bf16 v[62:65], v[196:199], v[212:215], v[62:65]
	v_mfma_f32_16x16x32_bf16 v[58:61], v[204:207], v[212:215], v[58:61]
	v_mfma_f32_16x16x32_bf16 v[46:49], v[196:199], v[220:223], v[46:49]
	v_mfma_f32_16x16x32_bf16 v[42:45], v[204:207], v[220:223], v[42:45]
	s_setprio 0
	s_setprio 1
	v_mfma_f32_16x16x32_bf16 v[22:25], v[196:199], v[228:231], v[22:25]
	v_mfma_f32_16x16x32_bf16 v[18:21], v[204:207], v[228:231], v[18:21]
	v_mfma_f32_16x16x32_bf16 v[6:9], v[196:199], v[236:239], v[6:9]
	v_mfma_f32_16x16x32_bf16 v[2:5], v[204:207], v[236:239], v[2:5]
	s_setprio 0
	s_setprio 1
	v_mfma_f32_16x16x32_bf16 v[62:65], v[200:203], v[216:219], v[62:65]
	v_mfma_f32_16x16x32_bf16 v[58:61], v[208:211], v[216:219], v[58:61]
	v_mfma_f32_16x16x32_bf16 v[46:49], v[200:203], v[224:227], v[46:49]
	v_mfma_f32_16x16x32_bf16 v[42:45], v[208:211], v[224:227], v[42:45]
	s_setprio 0
	s_setprio 1
	v_mfma_f32_16x16x32_bf16 v[22:25], v[200:203], v[232:235], v[22:25]
	v_mfma_f32_16x16x32_bf16 v[18:21], v[208:211], v[232:235], v[18:21]
	v_mfma_f32_16x16x32_bf16 v[6:9], v[200:203], v[240:243], v[6:9]
	v_mfma_f32_16x16x32_bf16 v[2:5], v[208:211], v[240:243], v[2:5]
	s_setprio 0
	s_barrier
	v_add_u32_e32 v145, s6, v140
	ds_read_b128 v[146:149], v145
	ds_read_b128 v[150:153], v145 offset:1024
	ds_read_b128 v[158:161], v145 offset:2048
	ds_read_b128 v[162:165], v145 offset:3072
	v_add_u32_e32 v145, s7, v140
	ds_read_b128 v[196:199], v145
	ds_read_b128 v[200:203], v145 offset:1024
	ds_read_b128 v[204:207], v145 offset:2048
	ds_read_b128 v[208:211], v145 offset:3072
	s_mov_b32 m0, s16
	v_lshl_add_u64 v[248:249], s[48:49], 0, v[26:27]
	ds_read_b128 v[212:215], v141 offset:32768
	ds_read_b128 v[216:219], v141 offset:33792
	ds_read_b128 v[220:223], v141 offset:34816
	ds_read_b128 v[224:227], v141 offset:35840
	ds_read_b128 v[228:231], v141 offset:36864
	ds_read_b128 v[232:235], v141 offset:37888
	ds_read_b128 v[236:239], v141 offset:38912
	ds_read_b128 v[240:243], v141 offset:39936
	global_load_lds_dwordx4 v[248:249], off
	v_lshl_add_u64 v[248:249], s[48:49], 0, v[28:29]
	s_mov_b32 m0, s17
	s_nop 0
	global_load_lds_dwordx4 v[248:249], off
	s_waitcnt vmcnt(8)
	s_waitcnt lgkmcnt(0)
	s_barrier
	s_setprio 1
	s_waitcnt lgkmcnt(0)
	v_mfma_f32_16x16x32_bf16 v[134:137], v[146:149], v[212:215], v[134:137]
	v_mfma_f32_16x16x32_bf16 v[130:133], v[158:161], v[212:215], v[130:133]
	v_mfma_f32_16x16x32_bf16 v[118:121], v[146:149], v[220:223], v[118:121]
	v_mfma_f32_16x16x32_bf16 v[114:117], v[158:161], v[220:223], v[114:117]
	s_setprio 0
	s_setprio 1
	v_mfma_f32_16x16x32_bf16 v[102:105], v[146:149], v[228:231], v[102:105]
	v_mfma_f32_16x16x32_bf16 v[98:101], v[158:161], v[228:231], v[98:101]
	v_mfma_f32_16x16x32_bf16 v[86:89], v[146:149], v[236:239], v[86:89]
	v_mfma_f32_16x16x32_bf16 v[82:85], v[158:161], v[236:239], v[82:85]
	s_setprio 0
	s_setprio 1
	v_mfma_f32_16x16x32_bf16 v[134:137], v[150:153], v[216:219], v[134:137]
	v_mfma_f32_16x16x32_bf16 v[130:133], v[162:165], v[216:219], v[130:133]
	v_mfma_f32_16x16x32_bf16 v[118:121], v[150:153], v[224:227], v[118:121]
	v_mfma_f32_16x16x32_bf16 v[114:117], v[162:165], v[224:227], v[114:117]
	s_setprio 0
	s_setprio 1
	v_mfma_f32_16x16x32_bf16 v[102:105], v[150:153], v[232:235], v[102:105]
	v_mfma_f32_16x16x32_bf16 v[98:101], v[162:165], v[232:235], v[98:101]
	v_mfma_f32_16x16x32_bf16 v[86:89], v[150:153], v[240:243], v[86:89]
	v_mfma_f32_16x16x32_bf16 v[82:85], v[162:165], v[240:243], v[82:85]
	s_setprio 0
	s_setprio 1
	v_mfma_f32_16x16x32_bf16 v[126:129], v[196:199], v[212:215], v[126:129]
	v_mfma_f32_16x16x32_bf16 v[122:125], v[204:207], v[212:215], v[122:125]
	v_mfma_f32_16x16x32_bf16 v[110:113], v[196:199], v[220:223], v[110:113]
	v_mfma_f32_16x16x32_bf16 v[106:109], v[204:207], v[220:223], v[106:109]
	s_setprio 0
	s_setprio 1
	v_mfma_f32_16x16x32_bf16 v[94:97], v[196:199], v[228:231], v[94:97]
	v_mfma_f32_16x16x32_bf16 v[90:93], v[204:207], v[228:231], v[90:93]
	v_mfma_f32_16x16x32_bf16 v[78:81], v[196:199], v[236:239], v[78:81]
	v_mfma_f32_16x16x32_bf16 v[74:77], v[204:207], v[236:239], v[74:77]
	s_setprio 0
	s_setprio 1
	v_mfma_f32_16x16x32_bf16 v[126:129], v[200:203], v[216:219], v[126:129]
	v_mfma_f32_16x16x32_bf16 v[122:125], v[208:211], v[216:219], v[122:125]
	v_mfma_f32_16x16x32_bf16 v[110:113], v[200:203], v[224:227], v[110:113]
	v_mfma_f32_16x16x32_bf16 v[106:109], v[208:211], v[224:227], v[106:109]
	s_setprio 0
	s_setprio 1
	v_mfma_f32_16x16x32_bf16 v[94:97], v[200:203], v[232:235], v[94:97]
	v_mfma_f32_16x16x32_bf16 v[90:93], v[208:211], v[232:235], v[90:93]
	v_mfma_f32_16x16x32_bf16 v[78:81], v[200:203], v[240:243], v[78:81]
	v_mfma_f32_16x16x32_bf16 v[74:77], v[208:211], v[240:243], v[74:77]
	s_setprio 0
	s_barrier
	s_mov_b32 m0, s66
	v_lshl_add_u64 v[142:143], v[142:143], 0, s[24:25]
	ds_read_b128 v[212:215], v141 offset:49152
	ds_read_b128 v[216:219], v141 offset:50176
	ds_read_b128 v[220:223], v141 offset:51200
	ds_read_b128 v[224:227], v141 offset:52224
	ds_read_b128 v[228:231], v141 offset:53248
	ds_read_b128 v[232:235], v141 offset:54272
	ds_read_b128 v[236:239], v141 offset:55296
	ds_read_b128 v[240:243], v141 offset:56320
	global_load_lds_dwordx4 v[142:143], off
	v_lshl_add_u64 v[142:143], v[154:155], 0, s[24:25]
	s_mov_b32 m0, s63
	s_nop 0
	global_load_lds_dwordx4 v[142:143], off
	v_lshl_add_u64 v[142:143], s[46:47], 0, v[0:1]
	s_mov_b32 m0, s65
	s_nop 0
	global_load_lds_dwordx4 v[142:143], off
	v_lshl_add_u64 v[142:143], s[46:47], 0, v[38:39]
	s_mov_b32 m0, s20
	s_nop 0
	global_load_lds_dwordx4 v[142:143], off
	v_lshl_add_u64 v[142:143], v[244:245], 0, s[24:25]
	s_mov_b32 m0, s19
	s_nop 0
	global_load_lds_dwordx4 v[142:143], off
	v_lshl_add_u64 v[142:143], v[246:247], 0, s[24:25]
	s_mov_b32 m0, s62
	s_nop 0
	global_load_lds_dwordx4 v[142:143], off
	s_waitcnt vmcnt(8)
	s_waitcnt lgkmcnt(0)
	s_barrier
	s_setprio 1
	s_waitcnt lgkmcnt(0)
	v_mfma_f32_16x16x32_bf16 v[70:73], v[146:149], v[212:215], v[70:73]
	v_mfma_f32_16x16x32_bf16 v[66:69], v[158:161], v[212:215], v[66:69]
	v_mfma_f32_16x16x32_bf16 v[54:57], v[146:149], v[220:223], v[54:57]
	v_mfma_f32_16x16x32_bf16 v[50:53], v[158:161], v[220:223], v[50:53]
	s_setprio 0
	s_setprio 1
	v_mfma_f32_16x16x32_bf16 v[34:37], v[146:149], v[228:231], v[34:37]
	v_mfma_f32_16x16x32_bf16 v[30:33], v[158:161], v[228:231], v[30:33]
	v_mfma_f32_16x16x32_bf16 v[14:17], v[146:149], v[236:239], v[14:17]
	v_mfma_f32_16x16x32_bf16 v[10:13], v[158:161], v[236:239], v[10:13]
	s_setprio 0
	s_setprio 1
	v_mfma_f32_16x16x32_bf16 v[70:73], v[150:153], v[216:219], v[70:73]
	v_mfma_f32_16x16x32_bf16 v[66:69], v[162:165], v[216:219], v[66:69]
	v_mfma_f32_16x16x32_bf16 v[54:57], v[150:153], v[224:227], v[54:57]
	v_mfma_f32_16x16x32_bf16 v[50:53], v[162:165], v[224:227], v[50:53]
	s_setprio 0
	s_setprio 1
	v_mfma_f32_16x16x32_bf16 v[34:37], v[150:153], v[232:235], v[34:37]
	v_mfma_f32_16x16x32_bf16 v[30:33], v[162:165], v[232:235], v[30:33]
	v_mfma_f32_16x16x32_bf16 v[14:17], v[150:153], v[240:243], v[14:17]
	v_mfma_f32_16x16x32_bf16 v[10:13], v[162:165], v[240:243], v[10:13]
	s_setprio 0
	s_setprio 1
	v_mfma_f32_16x16x32_bf16 v[62:65], v[196:199], v[212:215], v[62:65]
	v_mfma_f32_16x16x32_bf16 v[58:61], v[204:207], v[212:215], v[58:61]
	v_mfma_f32_16x16x32_bf16 v[46:49], v[196:199], v[220:223], v[46:49]
	v_mfma_f32_16x16x32_bf16 v[42:45], v[204:207], v[220:223], v[42:45]
	s_setprio 0
	s_setprio 1
	v_mfma_f32_16x16x32_bf16 v[22:25], v[196:199], v[228:231], v[22:25]
	v_mfma_f32_16x16x32_bf16 v[18:21], v[204:207], v[228:231], v[18:21]
	v_mfma_f32_16x16x32_bf16 v[6:9], v[196:199], v[236:239], v[6:9]
	v_mfma_f32_16x16x32_bf16 v[2:5], v[204:207], v[236:239], v[2:5]
	s_setprio 0
	s_setprio 1
	v_mfma_f32_16x16x32_bf16 v[62:65], v[200:203], v[216:219], v[62:65]
	v_mfma_f32_16x16x32_bf16 v[58:61], v[208:211], v[216:219], v[58:61]
	v_mfma_f32_16x16x32_bf16 v[46:49], v[200:203], v[224:227], v[46:49]
	v_mfma_f32_16x16x32_bf16 v[42:45], v[208:211], v[224:227], v[42:45]
	s_setprio 0
	s_setprio 1
	v_mfma_f32_16x16x32_bf16 v[22:25], v[200:203], v[232:235], v[22:25]
	v_mfma_f32_16x16x32_bf16 v[18:21], v[208:211], v[232:235], v[18:21]
	v_mfma_f32_16x16x32_bf16 v[6:9], v[200:203], v[240:243], v[6:9]
	v_mfma_f32_16x16x32_bf16 v[2:5], v[208:211], v[240:243], v[2:5]
	s_setprio 0
	s_barrier
	s_andn2_b64 vcc, exec, s[44:45]
	s_mov_b64 s[46:47], -1
	s_mov_b64 s[44:45], 0
	s_movk_i32 s20, 0x100
	s_cbranch_vccz .LBB0_476
	s_waitcnt vmcnt(0)
	s_cmpk_lt_u32 s10, 0x100
	s_cbranch_scc0 .LBB0_479
	s_barrier

.LBB0_482:
	s_add_i32 s48, s20, 0x100
	s_and_b64 s[46:47], s[46:47], exec
	s_cselect_b32 s47, 0, s48
	s_cselect_b32 s46, 0, 0
	s_add_u32 s50, s2, s47
	s_addc_u32 s51, s3, s46
	s_add_u32 s52, s40, s47
	s_addc_u32 s53, s41, s46
	s_add_u32 s66, s42, s20
	s_addc_u32 s67, s43, 0
	s_add_i32 s65, s4, s10
	s_add_i32 m0, s11, 0xc000
	s_add_i32 s63, s11, 0xe000
	s_add_i32 s70, s65, 0x2000
	s_add_u32 s54, s52, 0x20200
	v_add_u32_e32 v142, s4, v40
	s_addc_u32 s55, s53, 0
	s_add_i32 s82, s5, s10
	ds_read_b128 v[138:141], v142
	ds_read_b128 v[146:149], v142 offset:1024
	ds_read_b128 v[150:153], v142 offset:2048
	ds_read_b128 v[158:161], v142 offset:3072
	v_add_u32_e32 v142, s5, v40
	s_add_i32 s83, s82, 0x2000
	ds_read_b128 v[162:165], v142
	ds_read_b128 v[196:199], v142 offset:1024
	ds_read_b128 v[200:203], v142 offset:2048
	ds_read_b128 v[204:207], v142 offset:3072
	s_add_u32 s48, s50, 0x10000
	s_addc_u32 s49, s51, 0
	s_add_i32 s62, s6, s10
	s_add_i32 s56, s62, 0x2000
	s_add_u32 s46, s52, 0x20280
	s_addc_u32 s47, s53, 0
	s_add_i32 s57, s7, s10
	s_add_i32 s20, s57, 0x2000
	v_lshl_add_u64 v[142:143], s[66:67], 0, v[26:27]
	v_lshl_add_u64 v[142:143], v[142:143], 0, s[24:25]
	ds_read_b128 v[208:211], v41
	ds_read_b128 v[212:215], v41 offset:1024
	ds_read_b128 v[216:219], v41 offset:2048
	ds_read_b128 v[220:223], v41 offset:3072
	ds_read_b128 v[224:227], v41 offset:4096
	ds_read_b128 v[228:231], v41 offset:5120
	ds_read_b128 v[232:235], v41 offset:6144
	ds_read_b128 v[236:239], v41 offset:7168
	global_load_lds_dwordx4 v[142:143], off
	v_lshl_add_u64 v[142:143], s[66:67], 0, v[28:29]
	v_lshl_add_u64 v[142:143], v[142:143], 0, s[24:25]
	s_mov_b32 m0, s63
	s_nop 0
	global_load_lds_dwordx4 v[142:143], off
	s_waitcnt vmcnt(8)
	s_waitcnt lgkmcnt(0)
	s_barrier
	s_setprio 1
	s_waitcnt lgkmcnt(0)
	v_mfma_f32_16x16x32_bf16 v[134:137], v[138:141], v[208:211], v[134:137]
	v_mfma_f32_16x16x32_bf16 v[130:133], v[150:153], v[208:211], v[130:133]
	v_mfma_f32_16x16x32_bf16 v[118:121], v[138:141], v[216:219], v[118:121]
	v_mfma_f32_16x16x32_bf16 v[114:117], v[150:153], v[216:219], v[114:117]
	s_setprio 0
	s_setprio 1
	v_mfma_f32_16x16x32_bf16 v[102:105], v[138:141], v[224:227], v[102:105]
	v_mfma_f32_16x16x32_bf16 v[98:101], v[150:153], v[224:227], v[98:101]
	v_mfma_f32_16x16x32_bf16 v[86:89], v[138:141], v[232:235], v[86:89]
	v_mfma_f32_16x16x32_bf16 v[82:85], v[150:153], v[232:235], v[82:85]
	s_setprio 0
	s_setprio 1
	v_mfma_f32_16x16x32_bf16 v[134:137], v[146:149], v[212:215], v[134:137]
	v_mfma_f32_16x16x32_bf16 v[130:133], v[158:161], v[212:215], v[130:133]
	v_mfma_f32_16x16x32_bf16 v[118:121], v[146:149], v[220:223], v[118:121]
	v_mfma_f32_16x16x32_bf16 v[114:117], v[158:161], v[220:223], v[114:117]
	s_setprio 0
	s_setprio 1
	v_mfma_f32_16x16x32_bf16 v[102:105], v[146:149], v[228:231], v[102:105]
	v_mfma_f32_16x16x32_bf16 v[98:101], v[158:161], v[228:231], v[98:101]
	v_mfma_f32_16x16x32_bf16 v[86:89], v[146:149], v[236:239], v[86:89]
	v_mfma_f32_16x16x32_bf16 v[82:85], v[158:161], v[236:239], v[82:85]
	s_setprio 0
	s_setprio 1
	v_mfma_f32_16x16x32_bf16 v[126:129], v[162:165], v[208:211], v[126:129]
	v_mfma_f32_16x16x32_bf16 v[122:125], v[200:203], v[208:211], v[122:125]
	v_mfma_f32_16x16x32_bf16 v[110:113], v[162:165], v[216:219], v[110:113]
	v_mfma_f32_16x16x32_bf16 v[106:109], v[200:203], v[216:219], v[106:109]
	s_setprio 0
	s_setprio 1
	v_mfma_f32_16x16x32_bf16 v[94:97], v[162:165], v[224:227], v[94:97]
	v_mfma_f32_16x16x32_bf16 v[90:93], v[200:203], v[224:227], v[90:93]
	v_mfma_f32_16x16x32_bf16 v[78:81], v[162:165], v[232:235], v[78:81]
	v_mfma_f32_16x16x32_bf16 v[74:77], v[200:203], v[232:235], v[74:77]
	s_setprio 0
	s_setprio 1
	v_mfma_f32_16x16x32_bf16 v[126:129], v[196:199], v[212:215], v[126:129]
	v_mfma_f32_16x16x32_bf16 v[122:125], v[204:207], v[212:215], v[122:125]
	v_mfma_f32_16x16x32_bf16 v[110:113], v[196:199], v[220:223], v[110:113]
	v_mfma_f32_16x16x32_bf16 v[106:109], v[204:207], v[220:223], v[106:109]
	s_setprio 0
	s_setprio 1
	v_mfma_f32_16x16x32_bf16 v[94:97], v[196:199], v[228:231], v[94:97]
	v_mfma_f32_16x16x32_bf16 v[90:93], v[204:207], v[228:231], v[90:93]
	v_mfma_f32_16x16x32_bf16 v[78:81], v[196:199], v[236:239], v[78:81]
	v_mfma_f32_16x16x32_bf16 v[74:77], v[204:207], v[236:239], v[74:77]
	s_setprio 0
	s_barrier
	v_lshl_add_u64 v[142:143], s[52:53], 0, v[0:1]
	s_mov_b32 m0, s65
	v_lshl_add_u64 v[154:155], v[142:143], 0, s[84:85]
	ds_read_b128 v[208:211], v41 offset:16384
	ds_read_b128 v[212:215], v41 offset:17408
	ds_read_b128 v[216:219], v41 offset:18432
	ds_read_b128 v[220:223], v41 offset:19456
	ds_read_b128 v[224:227], v41 offset:20480
	ds_read_b128 v[228:231], v41 offset:21504
	ds_read_b128 v[232:235], v41 offset:22528
	ds_read_b128 v[236:239], v41 offset:23552
	global_load_lds_dwordx4 v[154:155], off
	v_lshl_add_u64 v[154:155], s[52:53], 0, v[38:39]
	v_lshl_add_u64 v[240:241], v[154:155], 0, s[84:85]
	s_mov_b32 m0, s70
	v_lshl_add_u64 v[242:243], s[50:51], 0, v[28:29]
	global_load_lds_dwordx4 v[240:241], off
	v_lshl_add_u64 v[240:241], s[54:55], 0, v[0:1]
	s_mov_b32 m0, s82
	s_nop 0
	global_load_lds_dwordx4 v[240:241], off
	v_lshl_add_u64 v[240:241], s[54:55], 0, v[38:39]
	s_mov_b32 m0, s83
	s_nop 0
	global_load_lds_dwordx4 v[240:241], off
	v_lshl_add_u64 v[240:241], s[50:51], 0, v[26:27]
	s_mov_b32 m0, s11
	s_nop 0
	global_load_lds_dwordx4 v[240:241], off
	s_mov_b32 m0, s12
	s_nop 0
	global_load_lds_dwordx4 v[242:243], off
	s_waitcnt vmcnt(8)
	s_waitcnt lgkmcnt(0)
	s_barrier
	s_setprio 1
	s_waitcnt lgkmcnt(0)
	v_mfma_f32_16x16x32_bf16 v[70:73], v[138:141], v[208:211], v[70:73]
	v_mfma_f32_16x16x32_bf16 v[66:69], v[150:153], v[208:211], v[66:69]
	v_mfma_f32_16x16x32_bf16 v[54:57], v[138:141], v[216:219], v[54:57]
	v_mfma_f32_16x16x32_bf16 v[50:53], v[150:153], v[216:219], v[50:53]
	s_setprio 0
	s_setprio 1
	v_mfma_f32_16x16x32_bf16 v[34:37], v[138:141], v[224:227], v[34:37]
	v_mfma_f32_16x16x32_bf16 v[30:33], v[150:153], v[224:227], v[30:33]
	v_mfma_f32_16x16x32_bf16 v[14:17], v[138:141], v[232:235], v[14:17]
	v_mfma_f32_16x16x32_bf16 v[10:13], v[150:153], v[232:235], v[10:13]
	s_setprio 0
	s_setprio 1
	v_mfma_f32_16x16x32_bf16 v[70:73], v[146:149], v[212:215], v[70:73]
	v_mfma_f32_16x16x32_bf16 v[66:69], v[158:161], v[212:215], v[66:69]
	v_mfma_f32_16x16x32_bf16 v[54:57], v[146:149], v[220:223], v[54:57]
	v_mfma_f32_16x16x32_bf16 v[50:53], v[158:161], v[220:223], v[50:53]
	s_setprio 0
	s_setprio 1
	v_mfma_f32_16x16x32_bf16 v[34:37], v[146:149], v[228:231], v[34:37]
	v_mfma_f32_16x16x32_bf16 v[30:33], v[158:161], v[228:231], v[30:33]
	v_mfma_f32_16x16x32_bf16 v[14:17], v[146:149], v[236:239], v[14:17]
	v_mfma_f32_16x16x32_bf16 v[10:13], v[158:161], v[236:239], v[10:13]
	s_setprio 0
	s_setprio 1
	v_mfma_f32_16x16x32_bf16 v[62:65], v[162:165], v[208:211], v[62:65]
	v_mfma_f32_16x16x32_bf16 v[58:61], v[200:203], v[208:211], v[58:61]
	v_mfma_f32_16x16x32_bf16 v[46:49], v[162:165], v[216:219], v[46:49]
	v_mfma_f32_16x16x32_bf16 v[42:45], v[200:203], v[216:219], v[42:45]
	s_setprio 0
	s_setprio 1
	v_mfma_f32_16x16x32_bf16 v[22:25], v[162:165], v[224:227], v[22:25]
	v_mfma_f32_16x16x32_bf16 v[18:21], v[200:203], v[224:227], v[18:21]
	v_mfma_f32_16x16x32_bf16 v[6:9], v[162:165], v[232:235], v[6:9]
	v_mfma_f32_16x16x32_bf16 v[2:5], v[200:203], v[232:235], v[2:5]
	s_setprio 0
	s_setprio 1
	v_mfma_f32_16x16x32_bf16 v[62:65], v[196:199], v[212:215], v[62:65]
	v_mfma_f32_16x16x32_bf16 v[58:61], v[204:207], v[212:215], v[58:61]
	v_mfma_f32_16x16x32_bf16 v[46:49], v[196:199], v[220:223], v[46:49]
	v_mfma_f32_16x16x32_bf16 v[42:45], v[204:207], v[220:223], v[42:45]
	s_setprio 0
	s_setprio 1
	v_mfma_f32_16x16x32_bf16 v[22:25], v[196:199], v[228:231], v[22:25]
	v_mfma_f32_16x16x32_bf16 v[18:21], v[204:207], v[228:231], v[18:21]
	v_mfma_f32_16x16x32_bf16 v[6:9], v[196:199], v[236:239], v[6:9]
	v_mfma_f32_16x16x32_bf16 v[2:5], v[204:207], v[236:239], v[2:5]
	s_setprio 0
	s_barrier
	v_add_u32_e32 v145, s6, v40
	ds_read_b128 v[138:141], v145
	ds_read_b128 v[146:149], v145 offset:1024
	ds_read_b128 v[150:153], v145 offset:2048
	ds_read_b128 v[158:161], v145 offset:3072
	v_add_u32_e32 v145, s7, v40
	ds_read_b128 v[162:165], v145
	ds_read_b128 v[196:199], v145 offset:1024
	ds_read_b128 v[200:203], v145 offset:2048
	ds_read_b128 v[204:207], v145 offset:3072
	s_mov_b32 m0, s13
	v_lshl_add_u64 v[244:245], s[48:49], 0, v[26:27]
	ds_read_b128 v[208:211], v41 offset:32768
	ds_read_b128 v[212:215], v41 offset:33792
	ds_read_b128 v[216:219], v41 offset:34816
	ds_read_b128 v[220:223], v41 offset:35840
	ds_read_b128 v[224:227], v41 offset:36864
	ds_read_b128 v[228:231], v41 offset:37888
	ds_read_b128 v[232:235], v41 offset:38912
	ds_read_b128 v[236:239], v41 offset:39936
	global_load_lds_dwordx4 v[244:245], off
	v_lshl_add_u64 v[244:245], s[48:49], 0, v[28:29]
	s_mov_b32 m0, s16
	s_mov_b64 s[48:49], 0x280
	global_load_lds_dwordx4 v[244:245], off
	s_waitcnt vmcnt(8)
	s_waitcnt lgkmcnt(0)
	s_barrier
	s_setprio 1
	s_waitcnt lgkmcnt(0)
	v_mfma_f32_16x16x32_bf16 v[134:137], v[138:141], v[208:211], v[134:137]
	v_mfma_f32_16x16x32_bf16 v[130:133], v[150:153], v[208:211], v[130:133]
	v_mfma_f32_16x16x32_bf16 v[118:121], v[138:141], v[216:219], v[118:121]
	v_mfma_f32_16x16x32_bf16 v[114:117], v[150:153], v[216:219], v[114:117]
	s_setprio 0
	s_setprio 1
	v_mfma_f32_16x16x32_bf16 v[102:105], v[138:141], v[224:227], v[102:105]
	v_mfma_f32_16x16x32_bf16 v[98:101], v[150:153], v[224:227], v[98:101]
	v_mfma_f32_16x16x32_bf16 v[86:89], v[138:141], v[232:235], v[86:89]
	v_mfma_f32_16x16x32_bf16 v[82:85], v[150:153], v[232:235], v[82:85]
	s_setprio 0
	s_setprio 1
	v_mfma_f32_16x16x32_bf16 v[134:137], v[146:149], v[212:215], v[134:137]
	v_mfma_f32_16x16x32_bf16 v[130:133], v[158:161], v[212:215], v[130:133]
	v_mfma_f32_16x16x32_bf16 v[118:121], v[146:149], v[220:223], v[118:121]
	v_mfma_f32_16x16x32_bf16 v[114:117], v[158:161], v[220:223], v[114:117]
	s_setprio 0
	s_setprio 1
	v_mfma_f32_16x16x32_bf16 v[102:105], v[146:149], v[228:231], v[102:105]
	v_mfma_f32_16x16x32_bf16 v[98:101], v[158:161], v[228:231], v[98:101]
	v_mfma_f32_16x16x32_bf16 v[86:89], v[146:149], v[236:239], v[86:89]
	v_mfma_f32_16x16x32_bf16 v[82:85], v[158:161], v[236:239], v[82:85]
	s_setprio 0
	s_setprio 1
	v_mfma_f32_16x16x32_bf16 v[126:129], v[162:165], v[208:211], v[126:129]
	v_mfma_f32_16x16x32_bf16 v[122:125], v[200:203], v[208:211], v[122:125]
	v_mfma_f32_16x16x32_bf16 v[110:113], v[162:165], v[216:219], v[110:113]
	v_mfma_f32_16x16x32_bf16 v[106:109], v[200:203], v[216:219], v[106:109]
	s_setprio 0
	s_setprio 1
	v_mfma_f32_16x16x32_bf16 v[94:97], v[162:165], v[224:227], v[94:97]
	v_mfma_f32_16x16x32_bf16 v[90:93], v[200:203], v[224:227], v[90:93]
	v_mfma_f32_16x16x32_bf16 v[78:81], v[162:165], v[232:235], v[78:81]
	v_mfma_f32_16x16x32_bf16 v[74:77], v[200:203], v[232:235], v[74:77]
	s_setprio 0
	s_setprio 1
	v_mfma_f32_16x16x32_bf16 v[126:129], v[196:199], v[212:215], v[126:129]
	v_mfma_f32_16x16x32_bf16 v[122:125], v[204:207], v[212:215], v[122:125]
	v_mfma_f32_16x16x32_bf16 v[110:113], v[196:199], v[220:223], v[110:113]
	v_mfma_f32_16x16x32_bf16 v[106:109], v[204:207], v[220:223], v[106:109]
	s_setprio 0
	s_setprio 1
	v_mfma_f32_16x16x32_bf16 v[94:97], v[196:199], v[228:231], v[94:97]
	v_mfma_f32_16x16x32_bf16 v[90:93], v[204:207], v[228:231], v[90:93]
	v_mfma_f32_16x16x32_bf16 v[78:81], v[196:199], v[236:239], v[78:81]
	v_mfma_f32_16x16x32_bf16 v[74:77], v[204:207], v[236:239], v[74:77]
	s_setprio 0
	s_barrier
	s_mov_b32 m0, s62
	v_lshl_add_u64 v[142:143], v[142:143], 0, s[48:49]
	ds_read_b128 v[208:211], v41 offset:49152
	ds_read_b128 v[212:215], v41 offset:50176
	ds_read_b128 v[216:219], v41 offset:51200
	ds_read_b128 v[220:223], v41 offset:52224
	ds_read_b128 v[224:227], v41 offset:53248
	ds_read_b128 v[228:231], v41 offset:54272
	ds_read_b128 v[232:235], v41 offset:55296
	ds_read_b128 v[236:239], v41 offset:56320
	global_load_lds_dwordx4 v[142:143], off
	v_lshl_add_u64 v[142:143], v[154:155], 0, s[48:49]
	s_mov_b32 m0, s56
	s_nop 0
	global_load_lds_dwordx4 v[142:143], off
	v_lshl_add_u64 v[142:143], s[46:47], 0, v[0:1]
	s_mov_b32 m0, s57
	s_nop 0
	global_load_lds_dwordx4 v[142:143], off
	v_lshl_add_u64 v[142:143], s[46:47], 0, v[38:39]
	s_mov_b32 m0, s20
	s_nop 0
	global_load_lds_dwordx4 v[142:143], off
	v_lshl_add_u64 v[142:143], v[240:241], 0, s[24:25]
	s_mov_b32 m0, s17
	s_nop 0
	global_load_lds_dwordx4 v[142:143], off
	v_lshl_add_u64 v[142:143], v[242:243], 0, s[24:25]
	s_mov_b32 m0, s19
	s_nop 0
	global_load_lds_dwordx4 v[142:143], off
	s_waitcnt vmcnt(8)
	s_waitcnt lgkmcnt(0)
	s_barrier
	s_setprio 1
	s_waitcnt lgkmcnt(0)
	v_mfma_f32_16x16x32_bf16 v[70:73], v[138:141], v[208:211], v[70:73]
	v_mfma_f32_16x16x32_bf16 v[66:69], v[150:153], v[208:211], v[66:69]
	v_mfma_f32_16x16x32_bf16 v[54:57], v[138:141], v[216:219], v[54:57]
	v_mfma_f32_16x16x32_bf16 v[50:53], v[150:153], v[216:219], v[50:53]
	s_setprio 0
	s_setprio 1
	v_mfma_f32_16x16x32_bf16 v[34:37], v[138:141], v[224:227], v[34:37]
	v_mfma_f32_16x16x32_bf16 v[30:33], v[150:153], v[224:227], v[30:33]
	v_mfma_f32_16x16x32_bf16 v[14:17], v[138:141], v[232:235], v[14:17]
	v_mfma_f32_16x16x32_bf16 v[10:13], v[150:153], v[232:235], v[10:13]
	s_setprio 0
	s_setprio 1
	v_mfma_f32_16x16x32_bf16 v[70:73], v[146:149], v[212:215], v[70:73]
	v_mfma_f32_16x16x32_bf16 v[66:69], v[158:161], v[212:215], v[66:69]
	v_mfma_f32_16x16x32_bf16 v[54:57], v[146:149], v[220:223], v[54:57]
	v_mfma_f32_16x16x32_bf16 v[50:53], v[158:161], v[220:223], v[50:53]
	s_setprio 0
	s_setprio 1
	v_mfma_f32_16x16x32_bf16 v[34:37], v[146:149], v[228:231], v[34:37]
	v_mfma_f32_16x16x32_bf16 v[30:33], v[158:161], v[228:231], v[30:33]
	v_mfma_f32_16x16x32_bf16 v[14:17], v[146:149], v[236:239], v[14:17]
	v_mfma_f32_16x16x32_bf16 v[10:13], v[158:161], v[236:239], v[10:13]
	s_setprio 0
	s_setprio 1
	v_mfma_f32_16x16x32_bf16 v[62:65], v[162:165], v[208:211], v[62:65]
	v_mfma_f32_16x16x32_bf16 v[58:61], v[200:203], v[208:211], v[58:61]
	v_mfma_f32_16x16x32_bf16 v[46:49], v[162:165], v[216:219], v[46:49]
	v_mfma_f32_16x16x32_bf16 v[42:45], v[200:203], v[216:219], v[42:45]
	s_setprio 0
	s_setprio 1
	v_mfma_f32_16x16x32_bf16 v[22:25], v[162:165], v[224:227], v[22:25]
	v_mfma_f32_16x16x32_bf16 v[18:21], v[200:203], v[224:227], v[18:21]
	v_mfma_f32_16x16x32_bf16 v[6:9], v[162:165], v[232:235], v[6:9]
	v_mfma_f32_16x16x32_bf16 v[2:5], v[200:203], v[232:235], v[2:5]
	s_setprio 0
	s_setprio 1
	v_mfma_f32_16x16x32_bf16 v[62:65], v[196:199], v[212:215], v[62:65]
	v_mfma_f32_16x16x32_bf16 v[58:61], v[204:207], v[212:215], v[58:61]
	v_mfma_f32_16x16x32_bf16 v[46:49], v[196:199], v[220:223], v[46:49]
	v_mfma_f32_16x16x32_bf16 v[42:45], v[204:207], v[220:223], v[42:45]
	s_setprio 0
	s_setprio 1
	v_mfma_f32_16x16x32_bf16 v[22:25], v[196:199], v[228:231], v[22:25]
	v_mfma_f32_16x16x32_bf16 v[18:21], v[204:207], v[228:231], v[18:21]
	v_mfma_f32_16x16x32_bf16 v[6:9], v[196:199], v[236:239], v[6:9]
	v_mfma_f32_16x16x32_bf16 v[2:5], v[204:207], v[236:239], v[2:5]
	s_setprio 0
	s_barrier
	s_andn2_b64 vcc, exec, s[44:45]
	s_mov_b64 s[46:47], -1
	s_mov_b64 s[44:45], 0
	s_movk_i32 s20, 0x100
	s_cbranch_vccz .LBB0_482
	s_waitcnt vmcnt(0)
	s_cmpk_lt_u32 s9, 0x100
	s_movk_i32 s83, 0x2000
	s_movk_i32 s86, 0x1fff
	s_cbranch_scc0 .LBB0_485
	s_barrier

.LBB0_1254:
	s_add_i32 s44, s20, 0x100
	s_and_b64 s[42:43], s[42:43], exec
	s_cselect_b32 s43, 0, s44
	s_cselect_b32 s42, 0, 0
	s_add_u32 s46, s2, s43
	s_addc_u32 s47, s3, s42
	s_add_i32 s70, 0, 0x10000
	s_add_u32 s52, s8, s43
	s_addc_u32 s53, s9, s42
	s_add_i32 s43, 0, 0x14000
	s_add_u32 s56, s18, s20
	s_addc_u32 s57, s19, 0
	s_add_i32 s67, s70, s10
	s_add_i32 m0, s11, 0xc000
	s_add_i32 s82, s11, 0xe000
	s_add_i32 s63, s67, 0x2000
	v_add_u32_e32 v139, s70, v137
	s_add_u32 s54, s52, 0x10000
	ds_read_b128 v[140:143], v139
	ds_read_b128 v[144:147], v139 offset:1024
	ds_read_b128 v[148:151], v139 offset:2048
	ds_read_b128 v[152:155], v139 offset:3072
	v_add_u32_e32 v139, s43, v137
	s_addc_u32 s55, s53, 0
	s_add_i32 s66, s43, s10
	ds_read_b128 v[158:161], v139
	ds_read_b128 v[162:165], v139 offset:1024
	ds_read_b128 v[196:199], v139 offset:2048
	ds_read_b128 v[200:203], v139 offset:3072
	s_add_i32 s65, s66, 0x2000
	s_add_i32 s62, 0, 0x18000
	s_add_i32 s59, 0, 0x1c000
	s_add_u32 s44, s46, 0x10000
	s_addc_u32 s45, s47, 0
	s_add_i32 s58, s62, s10
	s_add_i32 s20, s58, 0x2000
	s_add_u32 s42, s52, 0x10080
	s_addc_u32 s43, s53, 0
	s_add_i32 s84, s59, s10
	s_add_i32 s70, s84, 0x2000
	v_lshl_add_u64 v[236:237], s[56:57], 0, v[130:131]
	v_lshl_add_u64 v[236:237], v[236:237], 0, s[24:25]
	ds_read_b128 v[204:207], v138
	ds_read_b128 v[208:211], v138 offset:1024
	ds_read_b128 v[212:215], v138 offset:2048
	ds_read_b128 v[216:219], v138 offset:3072
	ds_read_b128 v[220:223], v138 offset:4096
	ds_read_b128 v[224:227], v138 offset:5120
	ds_read_b128 v[228:231], v138 offset:6144
	ds_read_b128 v[232:235], v138 offset:7168
	global_load_lds_dwordx4 v[236:237], off
	v_lshl_add_u64 v[236:237], s[56:57], 0, v[132:133]
	v_lshl_add_u64 v[236:237], v[236:237], 0, s[24:25]
	s_mov_b32 m0, s82
	s_nop 0
	global_load_lds_dwordx4 v[236:237], off
	s_waitcnt vmcnt(8)
	s_waitcnt lgkmcnt(0)
	s_barrier
	s_setprio 1
	s_waitcnt lgkmcnt(0)
	v_mfma_f32_16x16x32_bf16 v[126:129], v[140:143], v[204:207], v[126:129]
	v_mfma_f32_16x16x32_bf16 v[122:125], v[148:151], v[204:207], v[122:125]
	v_mfma_f32_16x16x32_bf16 v[118:121], v[140:143], v[212:215], v[118:121]
	v_mfma_f32_16x16x32_bf16 v[114:117], v[148:151], v[212:215], v[114:117]
	s_setprio 0
	s_setprio 1
	v_mfma_f32_16x16x32_bf16 v[102:105], v[140:143], v[220:223], v[102:105]
	v_mfma_f32_16x16x32_bf16 v[98:101], v[148:151], v[220:223], v[98:101]
	v_mfma_f32_16x16x32_bf16 v[86:89], v[140:143], v[228:231], v[86:89]
	v_mfma_f32_16x16x32_bf16 v[82:85], v[148:151], v[228:231], v[82:85]
	s_setprio 0
	s_setprio 1
	v_mfma_f32_16x16x32_bf16 v[126:129], v[144:147], v[208:211], v[126:129]
	v_mfma_f32_16x16x32_bf16 v[122:125], v[152:155], v[208:211], v[122:125]
	v_mfma_f32_16x16x32_bf16 v[118:121], v[144:147], v[216:219], v[118:121]
	v_mfma_f32_16x16x32_bf16 v[114:117], v[152:155], v[216:219], v[114:117]
	s_setprio 0
	s_setprio 1
	v_mfma_f32_16x16x32_bf16 v[102:105], v[144:147], v[224:227], v[102:105]
	v_mfma_f32_16x16x32_bf16 v[98:101], v[152:155], v[224:227], v[98:101]
	v_mfma_f32_16x16x32_bf16 v[86:89], v[144:147], v[232:235], v[86:89]
	v_mfma_f32_16x16x32_bf16 v[82:85], v[152:155], v[232:235], v[82:85]
	s_setprio 0
	s_setprio 1
	v_mfma_f32_16x16x32_bf16 v[110:113], v[158:161], v[204:207], v[110:113]
	v_mfma_f32_16x16x32_bf16 v[106:109], v[196:199], v[204:207], v[106:109]
	v_mfma_f32_16x16x32_bf16 v[94:97], v[158:161], v[212:215], v[94:97]
	v_mfma_f32_16x16x32_bf16 v[90:93], v[196:199], v[212:215], v[90:93]
	s_setprio 0
	s_setprio 1
	v_mfma_f32_16x16x32_bf16 v[78:81], v[158:161], v[220:223], v[78:81]
	v_mfma_f32_16x16x32_bf16 v[74:77], v[196:199], v[220:223], v[74:77]
	v_mfma_f32_16x16x32_bf16 v[70:73], v[158:161], v[228:231], v[70:73]
	v_mfma_f32_16x16x32_bf16 v[66:69], v[196:199], v[228:231], v[66:69]
	s_setprio 0
	s_setprio 1
	v_mfma_f32_16x16x32_bf16 v[110:113], v[162:165], v[208:211], v[110:113]
	v_mfma_f32_16x16x32_bf16 v[106:109], v[200:203], v[208:211], v[106:109]
	v_mfma_f32_16x16x32_bf16 v[94:97], v[162:165], v[216:219], v[94:97]
	v_mfma_f32_16x16x32_bf16 v[90:93], v[200:203], v[216:219], v[90:93]
	s_setprio 0
	s_setprio 1
	v_mfma_f32_16x16x32_bf16 v[78:81], v[162:165], v[224:227], v[78:81]
	v_mfma_f32_16x16x32_bf16 v[74:77], v[200:203], v[224:227], v[74:77]
	v_mfma_f32_16x16x32_bf16 v[70:73], v[162:165], v[232:235], v[70:73]
	v_mfma_f32_16x16x32_bf16 v[66:69], v[200:203], v[232:235], v[66:69]
	s_setprio 0
	s_barrier
	s_mov_b32 m0, s67
	v_lshl_add_u64 v[236:237], s[52:53], 0, v[0:1]
	ds_read_b128 v[204:207], v138 offset:16384
	ds_read_b128 v[208:211], v138 offset:17408
	ds_read_b128 v[212:215], v138 offset:18432
	ds_read_b128 v[216:219], v138 offset:19456
	ds_read_b128 v[220:223], v138 offset:20480
	ds_read_b128 v[224:227], v138 offset:21504
	ds_read_b128 v[228:231], v138 offset:22528
	ds_read_b128 v[232:235], v138 offset:23552
	global_load_lds_dwordx4 v[236:237], off
	v_lshl_add_u64 v[238:239], s[52:53], 0, v[134:135]
	s_mov_b32 m0, s63
	v_lshl_add_u64 v[240:241], s[54:55], 0, v[0:1]
	global_load_lds_dwordx4 v[238:239], off
	s_mov_b32 m0, s66
	v_lshl_add_u64 v[242:243], s[46:47], 0, v[132:133]
	global_load_lds_dwordx4 v[240:241], off
	v_lshl_add_u64 v[240:241], s[54:55], 0, v[134:135]
	s_mov_b32 m0, s65
	s_nop 0
	global_load_lds_dwordx4 v[240:241], off
	v_lshl_add_u64 v[240:241], s[46:47], 0, v[130:131]
	s_mov_b32 m0, s11
	s_nop 0
	global_load_lds_dwordx4 v[240:241], off
	s_mov_b32 m0, s12
	s_nop 0
	global_load_lds_dwordx4 v[242:243], off
	s_waitcnt vmcnt(8)
	s_waitcnt lgkmcnt(0)
	s_barrier
	s_setprio 1
	s_waitcnt lgkmcnt(0)
	v_mfma_f32_16x16x32_bf16 v[62:65], v[140:143], v[204:207], v[62:65]
	v_mfma_f32_16x16x32_bf16 v[58:61], v[148:151], v[204:207], v[58:61]
	v_mfma_f32_16x16x32_bf16 v[54:57], v[140:143], v[212:215], v[54:57]
	v_mfma_f32_16x16x32_bf16 v[50:53], v[148:151], v[212:215], v[50:53]
	s_setprio 0
	s_setprio 1
	v_mfma_f32_16x16x32_bf16 v[38:41], v[140:143], v[220:223], v[38:41]
	v_mfma_f32_16x16x32_bf16 v[34:37], v[148:151], v[220:223], v[34:37]
	v_mfma_f32_16x16x32_bf16 v[22:25], v[140:143], v[228:231], v[22:25]
	v_mfma_f32_16x16x32_bf16 v[18:21], v[148:151], v[228:231], v[18:21]
	s_setprio 0
	s_setprio 1
	v_mfma_f32_16x16x32_bf16 v[62:65], v[144:147], v[208:211], v[62:65]
	v_mfma_f32_16x16x32_bf16 v[58:61], v[152:155], v[208:211], v[58:61]
	v_mfma_f32_16x16x32_bf16 v[54:57], v[144:147], v[216:219], v[54:57]
	v_mfma_f32_16x16x32_bf16 v[50:53], v[152:155], v[216:219], v[50:53]
	s_setprio 0
	s_setprio 1
	v_mfma_f32_16x16x32_bf16 v[38:41], v[144:147], v[224:227], v[38:41]
	v_mfma_f32_16x16x32_bf16 v[34:37], v[152:155], v[224:227], v[34:37]
	v_mfma_f32_16x16x32_bf16 v[22:25], v[144:147], v[232:235], v[22:25]
	v_mfma_f32_16x16x32_bf16 v[18:21], v[152:155], v[232:235], v[18:21]
	s_setprio 0
	s_setprio 1
	v_mfma_f32_16x16x32_bf16 v[46:49], v[158:161], v[204:207], v[46:49]
	v_mfma_f32_16x16x32_bf16 v[42:45], v[196:199], v[204:207], v[42:45]
	v_mfma_f32_16x16x32_bf16 v[30:33], v[158:161], v[212:215], v[30:33]
	v_mfma_f32_16x16x32_bf16 v[26:29], v[196:199], v[212:215], v[26:29]
	s_setprio 0
	s_setprio 1
	v_mfma_f32_16x16x32_bf16 v[14:17], v[158:161], v[220:223], v[14:17]
	v_mfma_f32_16x16x32_bf16 v[10:13], v[196:199], v[220:223], v[10:13]
	v_mfma_f32_16x16x32_bf16 v[6:9], v[158:161], v[228:231], v[6:9]
	v_mfma_f32_16x16x32_bf16 v[2:5], v[196:199], v[228:231], v[2:5]
	s_setprio 0
	s_setprio 1
	v_mfma_f32_16x16x32_bf16 v[46:49], v[162:165], v[208:211], v[46:49]
	v_mfma_f32_16x16x32_bf16 v[42:45], v[200:203], v[208:211], v[42:45]
	v_mfma_f32_16x16x32_bf16 v[30:33], v[162:165], v[216:219], v[30:33]
	v_mfma_f32_16x16x32_bf16 v[26:29], v[200:203], v[216:219], v[26:29]
	s_setprio 0
	s_setprio 1
	v_mfma_f32_16x16x32_bf16 v[14:17], v[162:165], v[224:227], v[14:17]
	v_mfma_f32_16x16x32_bf16 v[10:13], v[200:203], v[224:227], v[10:13]
	v_mfma_f32_16x16x32_bf16 v[6:9], v[162:165], v[232:235], v[6:9]
	v_mfma_f32_16x16x32_bf16 v[2:5], v[200:203], v[232:235], v[2:5]
	s_setprio 0
	s_barrier
	v_add_u32_e32 v139, s62, v137
	ds_read_b128 v[140:143], v139
	ds_read_b128 v[144:147], v139 offset:1024
	ds_read_b128 v[148:151], v139 offset:2048
	ds_read_b128 v[152:155], v139 offset:3072
	v_add_u32_e32 v139, s59, v137
	ds_read_b128 v[158:161], v139
	ds_read_b128 v[162:165], v139 offset:1024
	ds_read_b128 v[196:199], v139 offset:2048
	ds_read_b128 v[200:203], v139 offset:3072
	s_mov_b32 m0, s13
	v_lshl_add_u64 v[244:245], s[44:45], 0, v[130:131]
	ds_read_b128 v[204:207], v138 offset:32768
	ds_read_b128 v[208:211], v138 offset:33792
	ds_read_b128 v[212:215], v138 offset:34816
	ds_read_b128 v[216:219], v138 offset:35840
	ds_read_b128 v[220:223], v138 offset:36864
	ds_read_b128 v[224:227], v138 offset:37888
	ds_read_b128 v[228:231], v138 offset:38912
	ds_read_b128 v[232:235], v138 offset:39936
	global_load_lds_dwordx4 v[244:245], off
	v_lshl_add_u64 v[244:245], s[44:45], 0, v[132:133]
	s_mov_b32 m0, s16
	s_nop 0
	global_load_lds_dwordx4 v[244:245], off
	s_waitcnt vmcnt(8)
	s_waitcnt lgkmcnt(0)
	s_barrier
	s_setprio 1
	s_waitcnt lgkmcnt(0)
	v_mfma_f32_16x16x32_bf16 v[126:129], v[140:143], v[204:207], v[126:129]
	v_mfma_f32_16x16x32_bf16 v[122:125], v[148:151], v[204:207], v[122:125]
	v_mfma_f32_16x16x32_bf16 v[118:121], v[140:143], v[212:215], v[118:121]
	v_mfma_f32_16x16x32_bf16 v[114:117], v[148:151], v[212:215], v[114:117]
	s_setprio 0
	s_setprio 1
	v_mfma_f32_16x16x32_bf16 v[102:105], v[140:143], v[220:223], v[102:105]
	v_mfma_f32_16x16x32_bf16 v[98:101], v[148:151], v[220:223], v[98:101]
	v_mfma_f32_16x16x32_bf16 v[86:89], v[140:143], v[228:231], v[86:89]
	v_mfma_f32_16x16x32_bf16 v[82:85], v[148:151], v[228:231], v[82:85]
	s_setprio 0
	s_setprio 1
	v_mfma_f32_16x16x32_bf16 v[126:129], v[144:147], v[208:211], v[126:129]
	v_mfma_f32_16x16x32_bf16 v[122:125], v[152:155], v[208:211], v[122:125]
	v_mfma_f32_16x16x32_bf16 v[118:121], v[144:147], v[216:219], v[118:121]
	v_mfma_f32_16x16x32_bf16 v[114:117], v[152:155], v[216:219], v[114:117]
	s_setprio 0
	s_setprio 1
	v_mfma_f32_16x16x32_bf16 v[102:105], v[144:147], v[224:227], v[102:105]
	v_mfma_f32_16x16x32_bf16 v[98:101], v[152:155], v[224:227], v[98:101]
	v_mfma_f32_16x16x32_bf16 v[86:89], v[144:147], v[232:235], v[86:89]
	v_mfma_f32_16x16x32_bf16 v[82:85], v[152:155], v[232:235], v[82:85]
	s_setprio 0
	s_setprio 1
	v_mfma_f32_16x16x32_bf16 v[110:113], v[158:161], v[204:207], v[110:113]
	v_mfma_f32_16x16x32_bf16 v[106:109], v[196:199], v[204:207], v[106:109]
	v_mfma_f32_16x16x32_bf16 v[94:97], v[158:161], v[212:215], v[94:97]
	v_mfma_f32_16x16x32_bf16 v[90:93], v[196:199], v[212:215], v[90:93]
	s_setprio 0
	s_setprio 1
	v_mfma_f32_16x16x32_bf16 v[78:81], v[158:161], v[220:223], v[78:81]
	v_mfma_f32_16x16x32_bf16 v[74:77], v[196:199], v[220:223], v[74:77]
	v_mfma_f32_16x16x32_bf16 v[70:73], v[158:161], v[228:231], v[70:73]
	v_mfma_f32_16x16x32_bf16 v[66:69], v[196:199], v[228:231], v[66:69]
	s_setprio 0
	s_setprio 1
	v_mfma_f32_16x16x32_bf16 v[110:113], v[162:165], v[208:211], v[110:113]
	v_mfma_f32_16x16x32_bf16 v[106:109], v[200:203], v[208:211], v[106:109]
	v_mfma_f32_16x16x32_bf16 v[94:97], v[162:165], v[216:219], v[94:97]
	v_mfma_f32_16x16x32_bf16 v[90:93], v[200:203], v[216:219], v[90:93]
	s_setprio 0
	s_setprio 1
	v_mfma_f32_16x16x32_bf16 v[78:81], v[162:165], v[224:227], v[78:81]
	v_mfma_f32_16x16x32_bf16 v[74:77], v[200:203], v[224:227], v[74:77]
	v_mfma_f32_16x16x32_bf16 v[70:73], v[162:165], v[232:235], v[70:73]
	v_mfma_f32_16x16x32_bf16 v[66:69], v[200:203], v[232:235], v[66:69]
	s_setprio 0
	s_barrier
	s_mov_b32 m0, s58
	v_lshl_add_u64 v[236:237], v[236:237], 0, s[24:25]
	ds_read_b128 v[204:207], v138 offset:49152
	ds_read_b128 v[208:211], v138 offset:50176
	ds_read_b128 v[212:215], v138 offset:51200
	ds_read_b128 v[216:219], v138 offset:52224
	ds_read_b128 v[220:223], v138 offset:53248
	ds_read_b128 v[224:227], v138 offset:54272
	ds_read_b128 v[228:231], v138 offset:55296
	ds_read_b128 v[232:235], v138 offset:56320
	global_load_lds_dwordx4 v[236:237], off
	v_lshl_add_u64 v[236:237], v[238:239], 0, s[24:25]
	s_mov_b32 m0, s20
	s_nop 0
	global_load_lds_dwordx4 v[236:237], off
	v_lshl_add_u64 v[236:237], s[42:43], 0, v[0:1]
	s_mov_b32 m0, s84
	s_nop 0
	global_load_lds_dwordx4 v[236:237], off
	v_lshl_add_u64 v[236:237], s[42:43], 0, v[134:135]
	s_mov_b32 m0, s70
	s_nop 0
	global_load_lds_dwordx4 v[236:237], off
	v_lshl_add_u64 v[236:237], v[240:241], 0, s[24:25]
	s_mov_b32 m0, s17
	s_nop 0
	global_load_lds_dwordx4 v[236:237], off
	v_lshl_add_u64 v[236:237], v[242:243], 0, s[24:25]
	s_mov_b32 m0, s28
	s_nop 0
	global_load_lds_dwordx4 v[236:237], off
	s_waitcnt vmcnt(8)
	s_waitcnt lgkmcnt(0)
	s_barrier
	s_setprio 1
	s_waitcnt lgkmcnt(0)
	v_mfma_f32_16x16x32_bf16 v[62:65], v[140:143], v[204:207], v[62:65]
	v_mfma_f32_16x16x32_bf16 v[58:61], v[148:151], v[204:207], v[58:61]
	v_mfma_f32_16x16x32_bf16 v[54:57], v[140:143], v[212:215], v[54:57]
	v_mfma_f32_16x16x32_bf16 v[50:53], v[148:151], v[212:215], v[50:53]
	s_setprio 0
	s_setprio 1
	v_mfma_f32_16x16x32_bf16 v[38:41], v[140:143], v[220:223], v[38:41]
	v_mfma_f32_16x16x32_bf16 v[34:37], v[148:151], v[220:223], v[34:37]
	v_mfma_f32_16x16x32_bf16 v[22:25], v[140:143], v[228:231], v[22:25]
	v_mfma_f32_16x16x32_bf16 v[18:21], v[148:151], v[228:231], v[18:21]
	s_setprio 0
	s_setprio 1
	v_mfma_f32_16x16x32_bf16 v[62:65], v[144:147], v[208:211], v[62:65]
	v_mfma_f32_16x16x32_bf16 v[58:61], v[152:155], v[208:211], v[58:61]
	v_mfma_f32_16x16x32_bf16 v[54:57], v[144:147], v[216:219], v[54:57]
	v_mfma_f32_16x16x32_bf16 v[50:53], v[152:155], v[216:219], v[50:53]
	s_setprio 0
	s_setprio 1
	v_mfma_f32_16x16x32_bf16 v[38:41], v[144:147], v[224:227], v[38:41]
	v_mfma_f32_16x16x32_bf16 v[34:37], v[152:155], v[224:227], v[34:37]
	v_mfma_f32_16x16x32_bf16 v[22:25], v[144:147], v[232:235], v[22:25]
	v_mfma_f32_16x16x32_bf16 v[18:21], v[152:155], v[232:235], v[18:21]
	s_setprio 0
	s_setprio 1
	v_mfma_f32_16x16x32_bf16 v[46:49], v[158:161], v[204:207], v[46:49]
	v_mfma_f32_16x16x32_bf16 v[42:45], v[196:199], v[204:207], v[42:45]
	v_mfma_f32_16x16x32_bf16 v[30:33], v[158:161], v[212:215], v[30:33]
	v_mfma_f32_16x16x32_bf16 v[26:29], v[196:199], v[212:215], v[26:29]
	s_setprio 0
	s_setprio 1
	v_mfma_f32_16x16x32_bf16 v[14:17], v[158:161], v[220:223], v[14:17]
	v_mfma_f32_16x16x32_bf16 v[10:13], v[196:199], v[220:223], v[10:13]
	v_mfma_f32_16x16x32_bf16 v[6:9], v[158:161], v[228:231], v[6:9]
	v_mfma_f32_16x16x32_bf16 v[2:5], v[196:199], v[228:231], v[2:5]
	s_setprio 0
	s_setprio 1
	v_mfma_f32_16x16x32_bf16 v[46:49], v[162:165], v[208:211], v[46:49]
	v_mfma_f32_16x16x32_bf16 v[42:45], v[200:203], v[208:211], v[42:45]
	v_mfma_f32_16x16x32_bf16 v[30:33], v[162:165], v[216:219], v[30:33]
	v_mfma_f32_16x16x32_bf16 v[26:29], v[200:203], v[216:219], v[26:29]
	s_setprio 0
	s_setprio 1
	v_mfma_f32_16x16x32_bf16 v[14:17], v[162:165], v[224:227], v[14:17]
	v_mfma_f32_16x16x32_bf16 v[10:13], v[200:203], v[224:227], v[10:13]
	v_mfma_f32_16x16x32_bf16 v[6:9], v[162:165], v[232:235], v[6:9]
	v_mfma_f32_16x16x32_bf16 v[2:5], v[200:203], v[232:235], v[2:5]
	s_setprio 0
	s_barrier
	s_andn2_b64 vcc, exec, s[40:41]
	s_mov_b64 s[42:43], -1
	s_mov_b64 s[40:41], 0
	s_movk_i32 s20, 0x100
	s_cbranch_vccz .LBB0_1254
	s_waitcnt vmcnt(0)
	s_cmpk_lt_u32 s7, 0x100
	s_cbranch_scc0 .LBB0_1257
	s_barrier

.LBB0_1302:
	s_add_u32 s17, s40, 0xfce78080
	s_addc_u32 s20, s41, -1
	s_cmp_lg_u32 s16, 12
	s_cselect_b32 s17, s17, 0
	s_cselect_b32 s20, s20, 0
	s_add_u32 s44, s6, s17
	s_addc_u32 s45, s7, s20
	s_add_i32 s46, 0, 0x10000
	s_add_u32 s42, s8, s17
	v_add_u32_e32 v143, s46, v141
	s_addc_u32 s43, s9, s20
	s_add_i32 s17, 0, 0x14000
	ds_read_b128 v[144:147], v143
	ds_read_b128 v[148:151], v143 offset:1024
	ds_read_b128 v[152:155], v143 offset:2048
	ds_read_b128 v[158:161], v143 offset:3072
	v_add_u32_e32 v143, s17, v141
	ds_read_b128 v[162:165], v143
	ds_read_b128 v[196:199], v143 offset:1024
	ds_read_b128 v[200:203], v143 offset:2048
	ds_read_b128 v[204:207], v143 offset:3072
	v_lshl_add_u64 v[240:241], v[138:139], 0, s[40:41]
	s_add_i32 m0, s4, 0xc000
	ds_read_b128 v[208:211], v142
	ds_read_b128 v[212:215], v142 offset:1024
	ds_read_b128 v[216:219], v142 offset:2048
	ds_read_b128 v[220:223], v142 offset:3072
	ds_read_b128 v[224:227], v142 offset:4096
	ds_read_b128 v[228:231], v142 offset:5120
	ds_read_b128 v[232:235], v142 offset:6144
	ds_read_b128 v[236:239], v142 offset:7168
	global_load_lds_dwordx4 v[240:241], off
	v_lshl_add_u64 v[240:241], v[136:137], 0, s[40:41]
	s_add_i32 m0, s4, 0xe000
	s_nop 0
	global_load_lds_dwordx4 v[240:241], off
	s_waitcnt vmcnt(8)
	s_waitcnt lgkmcnt(0)
	s_barrier
	s_setprio 1
	s_waitcnt lgkmcnt(0)
	v_mfma_f32_16x16x32_bf16 v[126:129], v[144:147], v[208:211], v[126:129]
	v_mfma_f32_16x16x32_bf16 v[122:125], v[152:155], v[208:211], v[122:125]
	v_mfma_f32_16x16x32_bf16 v[110:113], v[144:147], v[216:219], v[110:113]
	v_mfma_f32_16x16x32_bf16 v[106:109], v[152:155], v[216:219], v[106:109]
	s_setprio 0
	s_setprio 1
	v_mfma_f32_16x16x32_bf16 v[94:97], v[144:147], v[224:227], v[94:97]
	v_mfma_f32_16x16x32_bf16 v[90:93], v[152:155], v[224:227], v[90:93]
	v_mfma_f32_16x16x32_bf16 v[78:81], v[144:147], v[232:235], v[78:81]
	v_mfma_f32_16x16x32_bf16 v[74:77], v[152:155], v[232:235], v[74:77]
	s_setprio 0
	s_setprio 1
	v_mfma_f32_16x16x32_bf16 v[126:129], v[148:151], v[212:215], v[126:129]
	v_mfma_f32_16x16x32_bf16 v[122:125], v[158:161], v[212:215], v[122:125]
	v_mfma_f32_16x16x32_bf16 v[110:113], v[148:151], v[220:223], v[110:113]
	v_mfma_f32_16x16x32_bf16 v[106:109], v[158:161], v[220:223], v[106:109]
	s_setprio 0
	s_setprio 1
	v_mfma_f32_16x16x32_bf16 v[94:97], v[148:151], v[228:231], v[94:97]
	v_mfma_f32_16x16x32_bf16 v[90:93], v[158:161], v[228:231], v[90:93]
	v_mfma_f32_16x16x32_bf16 v[78:81], v[148:151], v[236:239], v[78:81]
	v_mfma_f32_16x16x32_bf16 v[74:77], v[158:161], v[236:239], v[74:77]
	s_setprio 0
	s_setprio 1
	v_mfma_f32_16x16x32_bf16 v[118:121], v[162:165], v[208:211], v[118:121]
	v_mfma_f32_16x16x32_bf16 v[114:117], v[200:203], v[208:211], v[114:117]
	v_mfma_f32_16x16x32_bf16 v[102:105], v[162:165], v[216:219], v[102:105]
	v_mfma_f32_16x16x32_bf16 v[98:101], v[200:203], v[216:219], v[98:101]
	s_setprio 0
	s_setprio 1
	v_mfma_f32_16x16x32_bf16 v[86:89], v[162:165], v[224:227], v[86:89]
	v_mfma_f32_16x16x32_bf16 v[82:85], v[200:203], v[224:227], v[82:85]
	v_mfma_f32_16x16x32_bf16 v[70:73], v[162:165], v[232:235], v[70:73]
	v_mfma_f32_16x16x32_bf16 v[66:69], v[200:203], v[232:235], v[66:69]
	s_setprio 0
	s_setprio 1
	v_mfma_f32_16x16x32_bf16 v[118:121], v[196:199], v[212:215], v[118:121]
	v_mfma_f32_16x16x32_bf16 v[114:117], v[204:207], v[212:215], v[114:117]
	v_mfma_f32_16x16x32_bf16 v[102:105], v[196:199], v[220:223], v[102:105]
	v_mfma_f32_16x16x32_bf16 v[98:101], v[204:207], v[220:223], v[98:101]
	s_setprio 0
	s_setprio 1
	v_mfma_f32_16x16x32_bf16 v[86:89], v[196:199], v[228:231], v[86:89]
	v_mfma_f32_16x16x32_bf16 v[82:85], v[204:207], v[228:231], v[82:85]
	v_mfma_f32_16x16x32_bf16 v[70:73], v[196:199], v[236:239], v[70:73]
	v_mfma_f32_16x16x32_bf16 v[66:69], v[204:207], v[236:239], v[66:69]
	s_setprio 0
	s_barrier
	s_add_i32 s20, s46, s3
	v_lshl_add_u64 v[240:241], s[42:43], 0, v[0:1]
	s_mov_b32 m0, s20
	ds_read_b128 v[208:211], v142 offset:16384
	ds_read_b128 v[212:215], v142 offset:17408
	ds_read_b128 v[216:219], v142 offset:18432
	ds_read_b128 v[220:223], v142 offset:19456
	ds_read_b128 v[224:227], v142 offset:20480
	ds_read_b128 v[228:231], v142 offset:21504
	ds_read_b128 v[232:235], v142 offset:22528
	ds_read_b128 v[236:239], v142 offset:23552
	global_load_lds_dwordx4 v[240:241], off
	s_add_i32 m0, s20, 0x2000
	s_add_u32 s46, s42, 0x10000
	v_lshl_add_u64 v[242:243], s[42:43], 0, v[134:135]
	s_addc_u32 s47, s43, 0
	s_add_i32 s17, s17, s3
	global_load_lds_dwordx4 v[242:243], off
	v_lshl_add_u64 v[244:245], s[46:47], 0, v[0:1]
	s_mov_b32 m0, s17
	v_lshl_add_u64 v[246:247], s[44:45], 0, v[132:133]
	global_load_lds_dwordx4 v[244:245], off
	v_lshl_add_u64 v[244:245], s[46:47], 0, v[134:135]
	s_add_i32 m0, s17, 0x2000
	s_nop 0
	global_load_lds_dwordx4 v[244:245], off
	v_lshl_add_u64 v[244:245], s[44:45], 0, v[130:131]
	s_mov_b32 m0, s4
	s_nop 0
	global_load_lds_dwordx4 v[244:245], off
	s_mov_b32 m0, s5
	s_nop 0
	global_load_lds_dwordx4 v[246:247], off
	s_waitcnt vmcnt(8)
	s_waitcnt lgkmcnt(0)
	s_barrier
	s_setprio 1
	s_waitcnt lgkmcnt(0)
	v_mfma_f32_16x16x32_bf16 v[62:65], v[144:147], v[208:211], v[62:65]
	v_mfma_f32_16x16x32_bf16 v[58:61], v[152:155], v[208:211], v[58:61]
	v_mfma_f32_16x16x32_bf16 v[46:49], v[144:147], v[216:219], v[46:49]
	v_mfma_f32_16x16x32_bf16 v[42:45], v[152:155], v[216:219], v[42:45]
	s_setprio 0
	s_setprio 1
	v_mfma_f32_16x16x32_bf16 v[30:33], v[144:147], v[224:227], v[30:33]
	v_mfma_f32_16x16x32_bf16 v[26:29], v[152:155], v[224:227], v[26:29]
	v_mfma_f32_16x16x32_bf16 v[14:17], v[144:147], v[232:235], v[14:17]
	v_mfma_f32_16x16x32_bf16 v[10:13], v[152:155], v[232:235], v[10:13]
	s_setprio 0
	s_setprio 1
	v_mfma_f32_16x16x32_bf16 v[62:65], v[148:151], v[212:215], v[62:65]
	v_mfma_f32_16x16x32_bf16 v[58:61], v[158:161], v[212:215], v[58:61]
	v_mfma_f32_16x16x32_bf16 v[46:49], v[148:151], v[220:223], v[46:49]
	v_mfma_f32_16x16x32_bf16 v[42:45], v[158:161], v[220:223], v[42:45]
	s_setprio 0
	s_setprio 1
	v_mfma_f32_16x16x32_bf16 v[30:33], v[148:151], v[228:231], v[30:33]
	v_mfma_f32_16x16x32_bf16 v[26:29], v[158:161], v[228:231], v[26:29]
	v_mfma_f32_16x16x32_bf16 v[14:17], v[148:151], v[236:239], v[14:17]
	v_mfma_f32_16x16x32_bf16 v[10:13], v[158:161], v[236:239], v[10:13]
	s_setprio 0
	s_setprio 1
	v_mfma_f32_16x16x32_bf16 v[54:57], v[162:165], v[208:211], v[54:57]
	v_mfma_f32_16x16x32_bf16 v[50:53], v[200:203], v[208:211], v[50:53]
	v_mfma_f32_16x16x32_bf16 v[38:41], v[162:165], v[216:219], v[38:41]
	v_mfma_f32_16x16x32_bf16 v[34:37], v[200:203], v[216:219], v[34:37]
	s_setprio 0
	s_setprio 1
	v_mfma_f32_16x16x32_bf16 v[22:25], v[162:165], v[224:227], v[22:25]
	v_mfma_f32_16x16x32_bf16 v[18:21], v[200:203], v[224:227], v[18:21]
	v_mfma_f32_16x16x32_bf16 v[6:9], v[162:165], v[232:235], v[6:9]
	v_mfma_f32_16x16x32_bf16 v[2:5], v[200:203], v[232:235], v[2:5]
	s_setprio 0
	s_setprio 1
	v_mfma_f32_16x16x32_bf16 v[54:57], v[196:199], v[212:215], v[54:57]
	v_mfma_f32_16x16x32_bf16 v[50:53], v[204:207], v[212:215], v[50:53]
	v_mfma_f32_16x16x32_bf16 v[38:41], v[196:199], v[220:223], v[38:41]
	v_mfma_f32_16x16x32_bf16 v[34:37], v[204:207], v[220:223], v[34:37]
	s_setprio 0
	s_setprio 1
	v_mfma_f32_16x16x32_bf16 v[22:25], v[196:199], v[228:231], v[22:25]
	v_mfma_f32_16x16x32_bf16 v[18:21], v[204:207], v[228:231], v[18:21]
	v_mfma_f32_16x16x32_bf16 v[6:9], v[196:199], v[236:239], v[6:9]
	v_mfma_f32_16x16x32_bf16 v[2:5], v[204:207], v[236:239], v[2:5]
	s_setprio 0
	s_barrier
	s_add_i32 s17, 0, 0x18000
	v_add_u32_e32 v143, s17, v141
	s_add_i32 s20, 0, 0x1c000
	ds_read_b128 v[144:147], v143
	ds_read_b128 v[148:151], v143 offset:1024
	ds_read_b128 v[152:155], v143 offset:2048
	ds_read_b128 v[158:161], v143 offset:3072
	v_add_u32_e32 v143, s20, v141
	ds_read_b128 v[162:165], v143
	ds_read_b128 v[196:199], v143 offset:1024
	ds_read_b128 v[200:203], v143 offset:2048
	ds_read_b128 v[204:207], v143 offset:3072
	s_add_u32 s44, s44, 0x40000
	s_addc_u32 s45, s45, 0
	s_mov_b32 m0, s10
	v_lshl_add_u64 v[248:249], s[44:45], 0, v[130:131]
	ds_read_b128 v[208:211], v142 offset:32768
	ds_read_b128 v[212:215], v142 offset:33792
	ds_read_b128 v[216:219], v142 offset:34816
	ds_read_b128 v[220:223], v142 offset:35840
	ds_read_b128 v[224:227], v142 offset:36864
	ds_read_b128 v[228:231], v142 offset:37888
	ds_read_b128 v[232:235], v142 offset:38912
	ds_read_b128 v[236:239], v142 offset:39936
	global_load_lds_dwordx4 v[248:249], off
	v_lshl_add_u64 v[248:249], s[44:45], 0, v[132:133]
	s_mov_b32 m0, s11
	s_nop 0
	global_load_lds_dwordx4 v[248:249], off
	s_waitcnt vmcnt(8)
	s_waitcnt lgkmcnt(0)
	s_barrier
	s_setprio 1
	s_waitcnt lgkmcnt(0)
	v_mfma_f32_16x16x32_bf16 v[126:129], v[144:147], v[208:211], v[126:129]
	v_mfma_f32_16x16x32_bf16 v[122:125], v[152:155], v[208:211], v[122:125]
	v_mfma_f32_16x16x32_bf16 v[110:113], v[144:147], v[216:219], v[110:113]
	v_mfma_f32_16x16x32_bf16 v[106:109], v[152:155], v[216:219], v[106:109]
	s_setprio 0
	s_setprio 1
	v_mfma_f32_16x16x32_bf16 v[94:97], v[144:147], v[224:227], v[94:97]
	v_mfma_f32_16x16x32_bf16 v[90:93], v[152:155], v[224:227], v[90:93]
	v_mfma_f32_16x16x32_bf16 v[78:81], v[144:147], v[232:235], v[78:81]
	v_mfma_f32_16x16x32_bf16 v[74:77], v[152:155], v[232:235], v[74:77]
	s_setprio 0
	s_setprio 1
	v_mfma_f32_16x16x32_bf16 v[126:129], v[148:151], v[212:215], v[126:129]
	v_mfma_f32_16x16x32_bf16 v[122:125], v[158:161], v[212:215], v[122:125]
	v_mfma_f32_16x16x32_bf16 v[110:113], v[148:151], v[220:223], v[110:113]
	v_mfma_f32_16x16x32_bf16 v[106:109], v[158:161], v[220:223], v[106:109]
	s_setprio 0
	s_setprio 1
	v_mfma_f32_16x16x32_bf16 v[94:97], v[148:151], v[228:231], v[94:97]
	v_mfma_f32_16x16x32_bf16 v[90:93], v[158:161], v[228:231], v[90:93]
	v_mfma_f32_16x16x32_bf16 v[78:81], v[148:151], v[236:239], v[78:81]
	v_mfma_f32_16x16x32_bf16 v[74:77], v[158:161], v[236:239], v[74:77]
	s_setprio 0
	s_setprio 1
	v_mfma_f32_16x16x32_bf16 v[118:121], v[162:165], v[208:211], v[118:121]
	v_mfma_f32_16x16x32_bf16 v[114:117], v[200:203], v[208:211], v[114:117]
	v_mfma_f32_16x16x32_bf16 v[102:105], v[162:165], v[216:219], v[102:105]
	v_mfma_f32_16x16x32_bf16 v[98:101], v[200:203], v[216:219], v[98:101]
	s_setprio 0
	s_setprio 1
	v_mfma_f32_16x16x32_bf16 v[86:89], v[162:165], v[224:227], v[86:89]
	v_mfma_f32_16x16x32_bf16 v[82:85], v[200:203], v[224:227], v[82:85]
	v_mfma_f32_16x16x32_bf16 v[70:73], v[162:165], v[232:235], v[70:73]
	v_mfma_f32_16x16x32_bf16 v[66:69], v[200:203], v[232:235], v[66:69]
	s_setprio 0
	s_setprio 1
	v_mfma_f32_16x16x32_bf16 v[118:121], v[196:199], v[212:215], v[118:121]
	v_mfma_f32_16x16x32_bf16 v[114:117], v[204:207], v[212:215], v[114:117]
	v_mfma_f32_16x16x32_bf16 v[102:105], v[196:199], v[220:223], v[102:105]
	v_mfma_f32_16x16x32_bf16 v[98:101], v[204:207], v[220:223], v[98:101]
	s_setprio 0
	s_setprio 1
	v_mfma_f32_16x16x32_bf16 v[86:89], v[196:199], v[228:231], v[86:89]
	v_mfma_f32_16x16x32_bf16 v[82:85], v[204:207], v[228:231], v[82:85]
	v_mfma_f32_16x16x32_bf16 v[70:73], v[196:199], v[236:239], v[70:73]
	v_mfma_f32_16x16x32_bf16 v[66:69], v[204:207], v[236:239], v[66:69]
	s_setprio 0
	s_barrier
	s_add_i32 s17, s17, s3
	v_lshl_add_u64 v[240:241], v[240:241], 0, s[24:25]
	s_mov_b32 m0, s17
	ds_read_b128 v[208:211], v142 offset:49152
	ds_read_b128 v[212:215], v142 offset:50176
	ds_read_b128 v[216:219], v142 offset:51200
	ds_read_b128 v[220:223], v142 offset:52224
	ds_read_b128 v[224:227], v142 offset:53248
	ds_read_b128 v[228:231], v142 offset:54272
	ds_read_b128 v[232:235], v142 offset:55296
	ds_read_b128 v[236:239], v142 offset:56320
	global_load_lds_dwordx4 v[240:241], off
	s_add_i32 m0, s17, 0x2000
	s_add_u32 s42, s42, 0x10080
	v_lshl_add_u64 v[240:241], v[242:243], 0, s[24:25]
	s_addc_u32 s43, s43, 0
	s_add_i32 s17, s20, s3
	global_load_lds_dwordx4 v[240:241], off
	v_lshl_add_u64 v[240:241], s[42:43], 0, v[0:1]
	s_mov_b32 m0, s17
	s_nop 0
	global_load_lds_dwordx4 v[240:241], off
	v_lshl_add_u64 v[240:241], s[42:43], 0, v[134:135]
	s_add_i32 m0, s17, 0x2000
	s_nop 0
	global_load_lds_dwordx4 v[240:241], off
	v_lshl_add_u64 v[240:241], v[244:245], 0, s[24:25]
	s_mov_b32 m0, s12
	s_nop 0
	global_load_lds_dwordx4 v[240:241], off
	v_lshl_add_u64 v[240:241], v[246:247], 0, s[24:25]
	s_mov_b32 m0, s13
	s_nop 0
	global_load_lds_dwordx4 v[240:241], off
	s_waitcnt vmcnt(8)
	s_waitcnt lgkmcnt(0)
	s_barrier
	s_setprio 1
	s_waitcnt lgkmcnt(0)
	v_mfma_f32_16x16x32_bf16 v[62:65], v[144:147], v[208:211], v[62:65]
	v_mfma_f32_16x16x32_bf16 v[58:61], v[152:155], v[208:211], v[58:61]
	v_mfma_f32_16x16x32_bf16 v[46:49], v[144:147], v[216:219], v[46:49]
	v_mfma_f32_16x16x32_bf16 v[42:45], v[152:155], v[216:219], v[42:45]
	s_setprio 0
	s_setprio 1
	v_mfma_f32_16x16x32_bf16 v[30:33], v[144:147], v[224:227], v[30:33]
	v_mfma_f32_16x16x32_bf16 v[26:29], v[152:155], v[224:227], v[26:29]
	v_mfma_f32_16x16x32_bf16 v[14:17], v[144:147], v[232:235], v[14:17]
	v_mfma_f32_16x16x32_bf16 v[10:13], v[152:155], v[232:235], v[10:13]
	s_setprio 0
	s_setprio 1
	v_mfma_f32_16x16x32_bf16 v[62:65], v[148:151], v[212:215], v[62:65]
	v_mfma_f32_16x16x32_bf16 v[58:61], v[158:161], v[212:215], v[58:61]
	v_mfma_f32_16x16x32_bf16 v[46:49], v[148:151], v[220:223], v[46:49]
	v_mfma_f32_16x16x32_bf16 v[42:45], v[158:161], v[220:223], v[42:45]
	s_setprio 0
	s_setprio 1
	v_mfma_f32_16x16x32_bf16 v[30:33], v[148:151], v[228:231], v[30:33]
	v_mfma_f32_16x16x32_bf16 v[26:29], v[158:161], v[228:231], v[26:29]
	v_mfma_f32_16x16x32_bf16 v[14:17], v[148:151], v[236:239], v[14:17]
	v_mfma_f32_16x16x32_bf16 v[10:13], v[158:161], v[236:239], v[10:13]
	s_setprio 0
	s_setprio 1
	v_mfma_f32_16x16x32_bf16 v[54:57], v[162:165], v[208:211], v[54:57]
	v_mfma_f32_16x16x32_bf16 v[50:53], v[200:203], v[208:211], v[50:53]
	v_mfma_f32_16x16x32_bf16 v[38:41], v[162:165], v[216:219], v[38:41]
	v_mfma_f32_16x16x32_bf16 v[34:37], v[200:203], v[216:219], v[34:37]
	s_setprio 0
	s_setprio 1
	v_mfma_f32_16x16x32_bf16 v[22:25], v[162:165], v[224:227], v[22:25]
	v_mfma_f32_16x16x32_bf16 v[18:21], v[200:203], v[224:227], v[18:21]
	v_mfma_f32_16x16x32_bf16 v[6:9], v[162:165], v[232:235], v[6:9]
	v_mfma_f32_16x16x32_bf16 v[2:5], v[200:203], v[232:235], v[2:5]
	s_setprio 0
	s_setprio 1
	v_mfma_f32_16x16x32_bf16 v[54:57], v[196:199], v[212:215], v[54:57]
	v_mfma_f32_16x16x32_bf16 v[50:53], v[204:207], v[212:215], v[50:53]
	v_mfma_f32_16x16x32_bf16 v[38:41], v[196:199], v[220:223], v[38:41]
	v_mfma_f32_16x16x32_bf16 v[34:37], v[204:207], v[220:223], v[34:37]
	s_setprio 0
	s_setprio 1
	v_mfma_f32_16x16x32_bf16 v[22:25], v[196:199], v[228:231], v[22:25]
	v_mfma_f32_16x16x32_bf16 v[18:21], v[204:207], v[228:231], v[18:21]
	v_mfma_f32_16x16x32_bf16 v[6:9], v[196:199], v[236:239], v[6:9]
	v_mfma_f32_16x16x32_bf16 v[2:5], v[204:207], v[236:239], v[2:5]
	s_setprio 0
	s_barrier
	s_add_i32 s16, s16, 2
	s_add_u32 s40, s40, 0x100
	s_addc_u32 s41, s41, 0
	s_cmp_gt_u32 s16, 13
	s_cbranch_scc0 .LBB0_1302
	s_waitcnt vmcnt(0)
	s_mov_b32 s12, s58
	s_cmpk_lt_u32 s1, 0x100
	s_cbranch_scc0 .LBB0_1305
	s_barrier
